# speedup vs baseline: 1.0308x; 1.0013x over previous
; #define WAIT_V(n) asm volatile("s_waitcnt vmcnt(" #n ")" ::: "memory")
; #define EPIW_ALL(F, BODY) _Pragma("unroll") for (int ai = 0; ai < 2; ++ai) _Pragma("unroll") for (int bj = 0; bj < 2; ++bj) { \
;   _Pragma("unroll") for (int m = 0; m < 4; ++m) { \
;     const int row = brow + ai * 128 + m * 16 + e_rr; const int tcw = bj * 128 + e_cw; \
;     const uint4 w = widen16(pack4(F(acc[ai][bj][m][0])), pack4(F(acc[ai][bj][m][1]))); BODY } SCHED; }
; __device__ __forceinline__ void phase_kvgemm(const Params& p, char* smem) {
;     ...
;   for (int it = it0; it < 24 * 16; it += gridDim.x) {
;     const int mt = it % 24, nt = it / 24, brow = mt * 256;
;     const int itn = it + gridDim.x;
;     f32x4 acc[2][2][4][2];
;     if (nt < 8) {
;       gemm_main<true>(A, Bt, brow, nt * 256, (u16*)smem, acc);
;       if (itn < 24 * 16) gemm_issue(A, Bt, (itn % 24) * 256, (itn / 24) * 256, (u16*)smem);
;       EPIW_BEGIN
;       EPIW_ALL(f_id, { *(uint4*)(km + ((unsigned)row * 2048u + nt * 256 + tcw)) = w; })
;     } else {
;       gemm_main<false>(A, Bt, brow, nt * 256, (u16*)smem, acc);
;       if (itn < 24 * 16) gemm_issue(A, Bt, (itn % 24) * 256, (itn / 24) * 256, (u16*)smem);
;       EPIX_BEGIN
;       EPIX_ALL(f_id, { *(uint4*)(vmt + ((size_t)mt * 2048 + (nt - 8) * 256 + tc) * 256 + (row8 - brow)) = w; })
;     }
;     WAIT_V(0);
.LBB0_79:
	s_nop 1
	s_cmpk_lt_i32 s42, 0x180
	s_cbranch_scc0 .LBB0_99

; #define WAIT_V(n) asm volatile("s_waitcnt vmcnt(" #n ")" ::: "memory")
; #define BAR __builtin_amdgcn_s_barrier()
; template <bool SWAP>
; __device__ __forceinline__ void gemm_main(const u16* __restrict__ A, const u16* __restrict__ Bt, int brow, int bcol,
;                                           u16* shm, f32x4 (&acc)[2][2][4][2]) {
;     ...
;   int tx = threadIdx.x; asm volatile("" : "+v"(tx));
;   const int wid = tx >> 6, lane = tx & 63, wr = wid >> 2, wc = wid & 3, fr = lane & 15, fq = lane >> 4;
; #pragma unroll
;   for (int a = 0; a < 2; ++a)
; #pragma unroll
;     for (int b = 0; b < 2; ++b)
; #pragma unroll
;       for (int m = 0; m < 4; ++m)
; #pragma unroll
;         for (int n = 0; n < 2; ++n) acc[a][b][m][n] = f32x4{0.f, 0.f, 0.f, 0.f};
;   bf16x8 At[4][2], B0[2][2], B1[2][2];
;   constexpr int nt = GK / BK;
;   GEMM_VOFF
;   const int lpart = (fr * 64 + fq * 16) ^ ((fr >> 3) << 5);
;   const int abase = wr * 8192 + lpart; int bbase = 65536 + wc * 4096 + lpart;
;   asm volatile("" : "+v"(bbase));
;   if (wr == 1) BAR;
;   WAIT_V(0); BAR;
;   BAR;
.LBB0_83:
	s_or_b64 exec, exec, s[26:27]
	v_bfe_i32 v4, v144, 27, 1
	v_lshlrev_b32_e32 v146, 4, v144
	v_lshrrev_b32_e32 v4, 22, v4
	v_add_u32_e32 v4, v146, v4
	v_and_b32_e32 v4, 0xfffffc00, v4
	v_sub_u32_e32 v4, v146, v4
	v_lshrrev_b32_e32 v5, 4, v4
	v_bitop3_b32 v4, v5, v4, 32 bitop3:0x6c
	v_ashrrev_i32_e32 v5, 31, v4
	v_lshrrev_b32_e32 v5, 26, v5
	v_add_u32_e32 v5, v4, v5
	v_ashrrev_i32_e32 v148, 6, v5
	v_and_b32_e32 v5, 0xc0, v5
	v_sub_u32_e32 v4, v4, v5
	v_ashrrev_i16_sdwa v4, v139, sext(v4) dst_sel:DWORD dst_unused:UNUSED_PAD src0_sel:DWORD src1_sel:BYTE_0
	v_bfe_i32 v149, v4, 0, 16
	v_add_u32_e32 v4, 0x2000, v146
	v_ashrrev_i32_e32 v5, 31, v4
	v_lshrrev_b32_e32 v5, 22, v5
	v_add_u32_e32 v5, v4, v5
	v_ashrrev_i32_e32 v150, 10, v5
	v_mul_i32_i24_e32 v5, 0x400, v150
	v_sub_u32_e32 v4, v4, v5
	v_lshrrev_b32_e32 v5, 4, v4
	v_bitop3_b32 v4, v5, v4, 32 bitop3:0x6c
	v_ashrrev_i32_e32 v5, 31, v4
	v_lshrrev_b32_e32 v5, 26, v5
	v_ashrrev_i32_e32 v3, 31, v144
	v_add_u32_e32 v5, v4, v5
	v_lshrrev_b32_e32 v3, 26, v3
	v_ashrrev_i32_e32 v151, 6, v5
	v_and_b32_e32 v5, 0xc0, v5
	v_add_u32_e32 v3, v144, v3
	v_sub_u32_e32 v4, v4, v5
	v_ashrrev_i32_e32 v147, 6, v3
	v_ashrrev_i16_sdwa v4, v139, sext(v4) dst_sel:DWORD dst_unused:UNUSED_PAD src0_sel:DWORD src1_sel:BYTE_0
	v_bfe_i32 v152, v4, 0, 16
	v_lshlrev_b32_e32 v4, 13, v0
	v_lshlrev_b32_e32 v0, 15, v147
	v_and_b32_e32 v0, 0xffff0000, v0
	v_lshl_add_u32 v0, v148, 12, v0
	v_and_or_b32 v0, v3, 64, v0
	v_lshl_add_u32 v128, v149, 1, v0
	v_lshlrev_b32_e32 v0, 15, v150
	v_and_b32_e32 v0, 0xffff0000, v0
	v_add_u32_e32 v5, 0, v2
	v_lshl_add_u32 v0, v151, 12, v0
	v_lshlrev_b32_e32 v2, 6, v150
	s_lshl_b32 s26, s28, 19
	s_mov_b32 s27, s5
	v_and_or_b32 v0, v2, 64, v0
	s_lshl_b32 s4, s25, 20
	s_lshl_b64 s[26:27], s[26:27], 1
	v_lshl_add_u32 v2, v152, 1, v0
	v_mov_b32_e32 v3, v129
	v_mov_b32_e32 v0, 0
	v_lshl_add_u64 v[130:131], s[26:27], 0, v[128:129]
	v_lshl_add_u64 v[132:133], s[26:27], 0, v[2:3]
	v_lshl_add_u64 v[134:135], v[128:129], 0, s[4:5]
	v_lshl_add_u64 v[136:137], v[2:3], 0, s[4:5]
	s_mov_b32 s28, -2
	v_add_u32_e32 v145, 0, v1
	v_add_u32_e32 v128, v5, v4
	s_mov_b64 s[26:27], s[50:51]
	v_mov_b32_e32 v1, v0
	v_mov_b32_e32 v2, v0
	v_mov_b32_e32 v3, v0
	v_mov_b32_e32 v4, v0
	v_mov_b32_e32 v5, v0
	v_mov_b32_e32 v6, v0
	v_mov_b32_e32 v7, v0
	v_mov_b32_e32 v8, v0
	v_mov_b32_e32 v9, v0
	v_mov_b32_e32 v10, v0
	v_mov_b32_e32 v11, v0
	v_mov_b32_e32 v12, v0
	v_mov_b32_e32 v13, v0
	v_mov_b32_e32 v14, v0
	v_mov_b32_e32 v15, v0
	v_mov_b32_e32 v16, v0
	v_mov_b32_e32 v17, v0
	v_mov_b32_e32 v18, v0
	v_mov_b32_e32 v19, v0
	v_mov_b32_e32 v20, v0
	v_mov_b32_e32 v21, v0
	v_mov_b32_e32 v22, v0
	v_mov_b32_e32 v23, v0
	v_mov_b32_e32 v24, v0
	v_mov_b32_e32 v25, v0
	v_mov_b32_e32 v26, v0
	v_mov_b32_e32 v27, v0
	v_mov_b32_e32 v28, v0
	v_mov_b32_e32 v29, v0
	v_mov_b32_e32 v30, v0
	v_mov_b32_e32 v31, v0
	v_mov_b32_e32 v32, v0
	v_mov_b32_e32 v33, v0
	v_mov_b32_e32 v34, v0
	v_mov_b32_e32 v35, v0
	v_mov_b32_e32 v36, v0
	v_mov_b32_e32 v37, v0
	v_mov_b32_e32 v38, v0
	v_mov_b32_e32 v39, v0
	v_mov_b32_e32 v40, v0
	v_mov_b32_e32 v41, v0
	v_mov_b32_e32 v42, v0
	v_mov_b32_e32 v43, v0
	v_mov_b32_e32 v44, v0
	v_mov_b32_e32 v45, v0
	v_mov_b32_e32 v46, v0
	v_mov_b32_e32 v47, v0
	v_mov_b32_e32 v48, v0
	v_mov_b32_e32 v49, v0
	v_mov_b32_e32 v50, v0
	v_mov_b32_e32 v51, v0
	v_mov_b32_e32 v52, v0
	v_mov_b32_e32 v53, v0
	v_mov_b32_e32 v54, v0
	v_mov_b32_e32 v55, v0
	v_mov_b32_e32 v56, v0
	v_mov_b32_e32 v57, v0
	v_mov_b32_e32 v58, v0
	v_mov_b32_e32 v59, v0
	v_mov_b32_e32 v60, v0
	v_mov_b32_e32 v61, v0
	v_mov_b32_e32 v62, v0
	v_mov_b32_e32 v63, v0
	v_mov_b32_e32 v64, v0
	v_mov_b32_e32 v65, v0
	v_mov_b32_e32 v66, v0
	v_mov_b32_e32 v67, v0
	v_mov_b32_e32 v68, v0
	v_mov_b32_e32 v69, v0
	v_mov_b32_e32 v70, v0
	v_mov_b32_e32 v71, v0
	v_mov_b32_e32 v72, v0
	v_mov_b32_e32 v73, v0
	v_mov_b32_e32 v74, v0
	v_mov_b32_e32 v75, v0
	v_mov_b32_e32 v76, v0
	v_mov_b32_e32 v77, v0
	v_mov_b32_e32 v78, v0
	v_mov_b32_e32 v79, v0
	v_mov_b32_e32 v80, v0
	v_mov_b32_e32 v81, v0
	v_mov_b32_e32 v82, v0
	v_mov_b32_e32 v83, v0
	v_mov_b32_e32 v84, v0
	v_mov_b32_e32 v85, v0
	v_mov_b32_e32 v86, v0
	v_mov_b32_e32 v87, v0
	v_mov_b32_e32 v88, v0
	v_mov_b32_e32 v89, v0
	v_mov_b32_e32 v90, v0
	v_mov_b32_e32 v91, v0
	v_mov_b32_e32 v92, v0
	v_mov_b32_e32 v93, v0
	v_mov_b32_e32 v94, v0
	v_mov_b32_e32 v95, v0
	v_mov_b32_e32 v96, v0
	v_mov_b32_e32 v97, v0
	v_mov_b32_e32 v98, v0
	v_mov_b32_e32 v99, v0
	v_mov_b32_e32 v100, v0
	v_mov_b32_e32 v101, v0
	v_mov_b32_e32 v102, v0
	v_mov_b32_e32 v103, v0
	v_mov_b32_e32 v104, v0
	v_mov_b32_e32 v105, v0
	v_mov_b32_e32 v106, v0
	v_mov_b32_e32 v107, v0
	v_mov_b32_e32 v108, v0
	v_mov_b32_e32 v109, v0
	v_mov_b32_e32 v110, v0
	v_mov_b32_e32 v111, v0
	v_mov_b32_e32 v112, v0
	v_mov_b32_e32 v113, v0
	v_mov_b32_e32 v114, v0
	v_mov_b32_e32 v115, v0
	v_mov_b32_e32 v116, v0
	v_mov_b32_e32 v117, v0
	v_mov_b32_e32 v118, v0
	v_mov_b32_e32 v119, v0
	v_mov_b32_e32 v120, v0
	v_mov_b32_e32 v121, v0
	v_mov_b32_e32 v122, v0
	v_mov_b32_e32 v123, v0
	v_mov_b32_e32 v124, v0
	v_mov_b32_e32 v125, v0
	v_mov_b32_e32 v126, v0
	v_mov_b32_e32 v127, v0
	v_readfirstlane_b32 s29, v146
	s_waitcnt vmcnt(0)
	s_barrier
	s_barrier

; #define WAIT_V(n) asm volatile("s_waitcnt vmcnt(" #n ")" ::: "memory")
; #define BAR __builtin_amdgcn_s_barrier()
; template <bool SWAP>
; __device__ __forceinline__ void gemm_main(const u16* __restrict__ A, const u16* __restrict__ Bt, int brow, int bcol,
;                                           u16* shm, f32x4 (&acc)[2][2][4][2]) {
;     ...
;   int tx = threadIdx.x; asm volatile("" : "+v"(tx));
;   const int wid = tx >> 6, lane = tx & 63, wr = wid >> 2, wc = wid & 3, fr = lane & 15, fq = lane >> 4;
; #pragma unroll
;   for (int a = 0; a < 2; ++a)
; #pragma unroll
;     for (int b = 0; b < 2; ++b)
; #pragma unroll
;       for (int m = 0; m < 4; ++m)
; #pragma unroll
;         for (int n = 0; n < 2; ++n) acc[a][b][m][n] = f32x4{0.f, 0.f, 0.f, 0.f};
;   bf16x8 At[4][2], B0[2][2], B1[2][2];
;   constexpr int nt = GK / BK;
;   GEMM_VOFF
;   const int lpart = (fr * 64 + fq * 16) ^ ((fr >> 3) << 5);
;   const int abase = wr * 8192 + lpart; int bbase = 65536 + wc * 4096 + lpart;
;   asm volatile("" : "+v"(bbase));
;   if (wr == 1) BAR;
;   WAIT_V(0); BAR;
;   BAR;
.LBB0_93:
	s_or_b64 exec, exec, s[26:27]
	v_bfe_i32 v4, v144, 27, 1
	v_lshlrev_b32_e32 v147, 4, v144
	v_lshrrev_b32_e32 v4, 22, v4
	v_add_u32_e32 v4, v147, v4
	v_and_b32_e32 v4, 0xfffffc00, v4
	v_sub_u32_e32 v4, v147, v4
	v_lshrrev_b32_e32 v5, 4, v4
	v_bitop3_b32 v4, v5, v4, 32 bitop3:0x6c
	v_ashrrev_i32_e32 v5, 31, v4
	v_lshrrev_b32_e32 v5, 26, v5
	v_add_u32_e32 v5, v4, v5
	v_ashrrev_i32_e32 v149, 6, v5
	v_and_b32_e32 v5, 0xc0, v5
	v_sub_u32_e32 v4, v4, v5
	v_ashrrev_i16_sdwa v4, v139, sext(v4) dst_sel:DWORD dst_unused:UNUSED_PAD src0_sel:DWORD src1_sel:BYTE_0
	v_bfe_i32 v150, v4, 0, 16
	v_add_u32_e32 v4, 0x2000, v147
	v_ashrrev_i32_e32 v5, 31, v4
	v_lshrrev_b32_e32 v5, 22, v5
	v_add_u32_e32 v5, v4, v5
	v_ashrrev_i32_e32 v151, 10, v5
	v_mul_i32_i24_e32 v5, 0x400, v151
	v_sub_u32_e32 v4, v4, v5
	v_lshrrev_b32_e32 v5, 4, v4
	v_bitop3_b32 v4, v5, v4, 32 bitop3:0x6c
	v_ashrrev_i32_e32 v3, 31, v144
	v_ashrrev_i32_e32 v5, 31, v4
	v_lshrrev_b32_e32 v3, 26, v3
	v_lshrrev_b32_e32 v5, 26, v5
	v_add_u32_e32 v3, v144, v3
	v_add_u32_e32 v5, v4, v5
	v_ashrrev_i32_e32 v148, 6, v3
	v_ashrrev_i32_e32 v152, 6, v5
	v_and_b32_e32 v5, 0xc0, v5
	v_sub_u32_e32 v4, v4, v5
	v_add_u32_e32 v5, 0, v0
	v_lshlrev_b32_e32 v0, 15, v148
	v_and_b32_e32 v0, 0xffff0000, v0
	v_lshl_add_u32 v0, v149, 12, v0
	v_and_or_b32 v0, v3, 64, v0
	v_lshl_add_u32 v128, v150, 1, v0
	v_lshlrev_b32_e32 v0, 15, v151
	v_ashrrev_i16_sdwa v4, v139, sext(v4) dst_sel:DWORD dst_unused:UNUSED_PAD src0_sel:DWORD src1_sel:BYTE_0
	v_and_b32_e32 v0, 0xffff0000, v0
	v_bfe_i32 v153, v4, 0, 16
	v_lshlrev_b32_e32 v4, 13, v2
	s_lshl_b32 s26, s25, 8
	v_lshl_add_u32 v0, v152, 12, v0
	v_lshlrev_b32_e32 v2, 6, v151
	s_ashr_i32 s25, s24, 31
	s_ashr_i32 s27, s26, 31
	v_and_or_b32 v0, v2, 64, v0
	s_lshl_b64 s[30:31], s[24:25], 12
	s_lshl_b64 s[34:35], s[26:27], 12
	v_lshl_add_u32 v2, v153, 1, v0
	v_mov_b32_e32 v3, v129
	v_mov_b32_e32 v0, 0
	v_lshl_add_u64 v[130:131], s[30:31], 0, v[2:3]
	v_lshl_add_u64 v[132:133], s[34:35], 0, v[2:3]
	s_mov_b32 s4, -2
	v_add_u32_e32 v146, 0, v1
	v_add_u32_e32 v145, v5, v4
	s_mov_b64 s[28:29], s[50:51]
	v_mov_b32_e32 v1, v0
	v_mov_b32_e32 v2, v0
	v_mov_b32_e32 v3, v0
	v_mov_b32_e32 v4, v0
	v_mov_b32_e32 v5, v0
	v_mov_b32_e32 v6, v0
	v_mov_b32_e32 v7, v0
	v_mov_b32_e32 v8, v0
	v_mov_b32_e32 v9, v0
	v_mov_b32_e32 v10, v0
	v_mov_b32_e32 v11, v0
	v_mov_b32_e32 v12, v0
	v_mov_b32_e32 v13, v0
	v_mov_b32_e32 v14, v0
	v_mov_b32_e32 v15, v0
	v_mov_b32_e32 v16, v0
	v_mov_b32_e32 v17, v0
	v_mov_b32_e32 v18, v0
	v_mov_b32_e32 v19, v0
	v_mov_b32_e32 v20, v0
	v_mov_b32_e32 v21, v0
	v_mov_b32_e32 v22, v0
	v_mov_b32_e32 v23, v0
	v_mov_b32_e32 v24, v0
	v_mov_b32_e32 v25, v0
	v_mov_b32_e32 v26, v0
	v_mov_b32_e32 v27, v0
	v_mov_b32_e32 v28, v0
	v_mov_b32_e32 v29, v0
	v_mov_b32_e32 v30, v0
	v_mov_b32_e32 v31, v0
	v_mov_b32_e32 v32, v0
	v_mov_b32_e32 v33, v0
	v_mov_b32_e32 v34, v0
	v_mov_b32_e32 v35, v0
	v_mov_b32_e32 v36, v0
	v_mov_b32_e32 v37, v0
	v_mov_b32_e32 v38, v0
	v_mov_b32_e32 v39, v0
	v_mov_b32_e32 v40, v0
	v_mov_b32_e32 v41, v0
	v_mov_b32_e32 v42, v0
	v_mov_b32_e32 v43, v0
	v_mov_b32_e32 v44, v0
	v_mov_b32_e32 v45, v0
	v_mov_b32_e32 v46, v0
	v_mov_b32_e32 v47, v0
	v_mov_b32_e32 v48, v0
	v_mov_b32_e32 v49, v0
	v_mov_b32_e32 v50, v0
	v_mov_b32_e32 v51, v0
	v_mov_b32_e32 v52, v0
	v_mov_b32_e32 v53, v0
	v_mov_b32_e32 v54, v0
	v_mov_b32_e32 v55, v0
	v_mov_b32_e32 v56, v0
	v_mov_b32_e32 v57, v0
	v_mov_b32_e32 v58, v0
	v_mov_b32_e32 v59, v0
	v_mov_b32_e32 v60, v0
	v_mov_b32_e32 v61, v0
	v_mov_b32_e32 v62, v0
	v_mov_b32_e32 v63, v0
	v_mov_b32_e32 v64, v0
	v_mov_b32_e32 v65, v0
	v_mov_b32_e32 v66, v0
	v_mov_b32_e32 v67, v0
	v_mov_b32_e32 v68, v0
	v_mov_b32_e32 v69, v0
	v_mov_b32_e32 v70, v0
	v_mov_b32_e32 v71, v0
	v_mov_b32_e32 v72, v0
	v_mov_b32_e32 v73, v0
	v_mov_b32_e32 v74, v0
	v_mov_b32_e32 v75, v0
	v_mov_b32_e32 v76, v0
	v_mov_b32_e32 v77, v0
	v_mov_b32_e32 v78, v0
	v_mov_b32_e32 v79, v0
	v_mov_b32_e32 v80, v0
	v_mov_b32_e32 v81, v0
	v_mov_b32_e32 v82, v0
	v_mov_b32_e32 v83, v0
	v_mov_b32_e32 v84, v0
	v_mov_b32_e32 v85, v0
	v_mov_b32_e32 v86, v0
	v_mov_b32_e32 v87, v0
	v_mov_b32_e32 v88, v0
	v_mov_b32_e32 v89, v0
	v_mov_b32_e32 v90, v0
	v_mov_b32_e32 v91, v0
	v_mov_b32_e32 v92, v0
	v_mov_b32_e32 v93, v0
	v_mov_b32_e32 v94, v0
	v_mov_b32_e32 v95, v0
	v_mov_b32_e32 v96, v0
	v_mov_b32_e32 v97, v0
	v_mov_b32_e32 v98, v0
	v_mov_b32_e32 v99, v0
	v_mov_b32_e32 v100, v0
	v_mov_b32_e32 v101, v0
	v_mov_b32_e32 v102, v0
	v_mov_b32_e32 v103, v0
	v_mov_b32_e32 v104, v0
	v_mov_b32_e32 v105, v0
	v_mov_b32_e32 v106, v0
	v_mov_b32_e32 v107, v0
	v_mov_b32_e32 v108, v0
	v_mov_b32_e32 v109, v0
	v_mov_b32_e32 v110, v0
	v_mov_b32_e32 v111, v0
	v_mov_b32_e32 v112, v0
	v_mov_b32_e32 v113, v0
	v_mov_b32_e32 v114, v0
	v_mov_b32_e32 v115, v0
	v_mov_b32_e32 v116, v0
	v_mov_b32_e32 v117, v0
	v_mov_b32_e32 v118, v0
	v_mov_b32_e32 v119, v0
	v_mov_b32_e32 v120, v0
	v_mov_b32_e32 v121, v0
	v_mov_b32_e32 v122, v0
	v_mov_b32_e32 v123, v0
	v_mov_b32_e32 v124, v0
	v_mov_b32_e32 v125, v0
	v_mov_b32_e32 v126, v0
	v_mov_b32_e32 v127, v0
	v_lshl_add_u64 v[134:135], s[30:31], 0, v[128:129]
	v_lshl_add_u64 v[136:137], s[34:35], 0, v[128:129]
	v_readfirstlane_b32 s25, v147
	s_waitcnt vmcnt(0)
	s_barrier
	s_barrier

; #define WAIT_V(n) asm volatile("s_waitcnt vmcnt(" #n ")" ::: "memory")
; __device__ __forceinline__ void phase_kvgemm(const Params& p, char* smem) {
;     ...
;     WAIT_V(0);
;   }
; }
.LBB0_99:
	s_waitcnt vmcnt(0)
	v_readlane_b32 s54, v253, 27
	v_readlane_b32 s92, v253, 26
	v_readlane_b32 s55, v253, 28

; __device__ __forceinline__ void phase_inproj1(const Params& p, char* smem) {
;     ...
;   for (int it = blockIdx.x; it < 128 * 25; it += gridDim.x) {
;     IN1_TILE(it, nt, brow)
;     const int itn = it + gridDim.x;
;     IN1_TILE(itn, ntn, brown)
;     f32x4 acc[2][2][4][2];
;     if (nt < 8) {
;       gemm_main<true>(A, Bt, brow, nt * 256, (u16*)smem, acc);
;       if (itn < 128 * 25) gemm_issue(A, Bt, brown, ntn * 256, (u16*)smem);
;       EPIW_BEGIN
;       EPIW_ALL(f_id, { *(uint4*)(qb + ((unsigned)row * 2048u + nt * 256 + tcw)) = w; })
;     } else {
;       gemm_main<false>(A, Bt, brow, nt * 256, (u16*)smem, acc);
;       if (nt < 16) {
;         {
;           int e_ro = e_wr * 64 + e_fq * 4, e_co2 = e_wc * 32 + e_fr; asm volatile("" : "+v"(e_ro), "+v"(e_co2));
; #pragma unroll
;           for (int ai = 0; ai < 2; ++ai)
; #pragma unroll
;             for (int bj = 0; bj < 2; ++bj) {
;               __syncthreads();
; #pragma unroll
;               for (int m = 0; m < 4; ++m)
; #pragma unroll
;                 for (int n = 0; n < 2; ++n) {
;                   f32x4 v = acc[ai][bj][m][n] * 0.0625f;
;                   uint2 pk = pack4(v);
;                   char* d = smem + (m * 16 + e_ro) * 272 + (n * 16 + e_co2) * 2;
;                   *(u16*)(d) = (u16)(pk.x & 0xffffu); *(u16*)(d + 272) = (u16)(pk.x >> 16);
;                   *(u16*)(d + 544) = (u16)(pk.y & 0xffffu); *(u16*)(d + 816) = (u16)(pk.y >> 16);
;                 }
;               __syncthreads();
; #pragma unroll
;               for (int k = 0; k < 4; ++k) {
;                 int idx = tx + k * 512, r = idx >> 4, sgm = idx & 15;
;                 uint4 val = *(const uint4*)(smem + r * 272 + sgm * 16);
;                 *(uint4*)(kb + ((unsigned)(brow + ai * 128 + r) * 2048u + (nt - 8) * 256 + bj * 128 + sgm * 8)) = val;
;               }
;             }
;           __syncthreads();
;         }
;         if (itn < 128 * 25) gemm_issue(A, Bt, brown, ntn * 256, (u16*)smem);
;         EPIX_BEGIN
;         EPIX_ALL(f_k16, { *(uint4*)(ktb + ((unsigned)((nt - 8) * 256 + tc) * (unsigned)THALF + row8)) = w; })
;       } else if (nt < 24) {
;         if (itn < 128 * 25) gemm_issue(A, Bt, brown, ntn * 256, (u16*)smem);
;         EPIX_BEGIN
;         EPIX_ALL(f_id, { *(uint4*)(vtb + ((unsigned)((nt - 16) * 256 + tc) * (unsigned)THALF + row8)) = w; })
;       } else {
.LBB0_109:
	s_nop 1
	s_cmpk_lt_i32 s25, 0xc80
	s_cbranch_scc0 .LBB0_205

; #define WAIT_V(n) asm volatile("s_waitcnt vmcnt(" #n ")" ::: "memory")
; #define BAR __builtin_amdgcn_s_barrier()
; template <bool SWAP>
; __device__ __forceinline__ void gemm_main(const u16* __restrict__ A, const u16* __restrict__ Bt, int brow, int bcol,
;                                           u16* shm, f32x4 (&acc)[2][2][4][2]) {
;     ...
;   int tx = threadIdx.x; asm volatile("" : "+v"(tx));
;   const int wid = tx >> 6, lane = tx & 63, wr = wid >> 2, wc = wid & 3, fr = lane & 15, fq = lane >> 4;
; #pragma unroll
;   for (int a = 0; a < 2; ++a)
; #pragma unroll
;     for (int b = 0; b < 2; ++b)
; #pragma unroll
;       for (int m = 0; m < 4; ++m)
; #pragma unroll
;         for (int n = 0; n < 2; ++n) acc[a][b][m][n] = f32x4{0.f, 0.f, 0.f, 0.f};
;   bf16x8 At[4][2], B0[2][2], B1[2][2];
;   constexpr int nt = GK / BK;
;   GEMM_VOFF
;   const int lpart = (fr * 64 + fq * 16) ^ ((fr >> 3) << 5);
;   const int abase = wr * 8192 + lpart; int bbase = 65536 + wc * 4096 + lpart;
;   asm volatile("" : "+v"(bbase));
;   if (wr == 1) BAR;
;   WAIT_V(0); BAR;
;   BAR;
.LBB0_113:
	s_or_b64 exec, exec, s[0:1]
	v_bfe_i32 v4, v136, 27, 1
	v_lshlrev_b32_e32 v153, 4, v136
	v_lshrrev_b32_e32 v4, 22, v4
	v_add_u32_e32 v4, v153, v4
	v_and_b32_e32 v4, 0xfffffc00, v4
	v_sub_u32_e32 v4, v153, v4
	v_lshrrev_b32_e32 v5, 4, v4
	v_bitop3_b32 v4, v5, v4, 32 bitop3:0x6c
	v_ashrrev_i32_e32 v5, 31, v4
	v_lshrrev_b32_e32 v5, 26, v5
	v_add_u32_e32 v5, v4, v5
	v_ashrrev_i32_e32 v155, 6, v5
	v_and_b32_e32 v5, 0xc0, v5
	v_sub_u32_e32 v4, v4, v5
	v_ashrrev_i16_sdwa v4, v215, sext(v4) dst_sel:DWORD dst_unused:UNUSED_PAD src0_sel:DWORD src1_sel:BYTE_0
	v_bfe_i32 v156, v4, 0, 16
	v_add_u32_e32 v4, 0x2000, v153
	v_ashrrev_i32_e32 v5, 31, v4
	v_lshrrev_b32_e32 v5, 22, v5
	v_add_u32_e32 v5, v4, v5
	v_ashrrev_i32_e32 v157, 10, v5
	v_mul_i32_i24_e32 v5, 0x400, v157
	v_sub_u32_e32 v4, v4, v5
	v_lshrrev_b32_e32 v5, 4, v4
	v_bitop3_b32 v4, v5, v4, 32 bitop3:0x6c
	v_ashrrev_i32_e32 v5, 31, v4
	v_lshrrev_b32_e32 v5, 26, v5
	v_ashrrev_i32_e32 v3, 31, v136
	v_add_u32_e32 v5, v4, v5
	v_lshrrev_b32_e32 v3, 26, v3
	v_ashrrev_i32_e32 v158, 6, v5
	v_and_b32_e32 v5, 0xc0, v5
	v_add_u32_e32 v3, v136, v3
	v_sub_u32_e32 v4, v4, v5
	v_ashrrev_i32_e32 v154, 6, v3
	v_ashrrev_i16_sdwa v4, v215, sext(v4) dst_sel:DWORD dst_unused:UNUSED_PAD src0_sel:DWORD src1_sel:BYTE_0
	v_bfe_i32 v159, v4, 0, 16
	v_lshlrev_b32_e32 v4, 13, v0
	v_lshlrev_b32_e32 v0, 15, v154
	v_and_b32_e32 v0, 0xffff0000, v0
	v_lshl_add_u32 v0, v155, 12, v0
	v_and_or_b32 v0, v3, 64, v0
	v_lshl_add_u32 v192, v156, 1, v0
	v_lshlrev_b32_e32 v0, 15, v157
	v_readlane_b32 s0, v253, 59
	v_and_b32_e32 v0, 0xffff0000, v0
	v_add_u32_e32 v5, 0, v2
	v_readlane_b32 s1, v253, 60
	v_lshl_add_u32 v0, v158, 12, v0
	v_lshlrev_b32_e32 v2, 6, v157
	s_mov_b32 s5, s1
	s_lshl_b32 s4, s2, 19
	v_writelane_b32 v253, s0, 59
	v_and_or_b32 v0, v2, 64, v0
	v_lshl_add_u32 v2, v159, 1, v0
	v_writelane_b32 v253, s1, 60
	s_lshl_b64 s[0:1], s[4:5], 1
	v_mov_b32_e32 v3, v193
	v_lshl_add_u64 v[128:129], s[0:1], 0, v[192:193]
	v_lshl_add_u64 v[130:131], s[0:1], 0, v[2:3]
	s_add_i32 s0, s93, s73
	s_ashr_i32 s1, s0, 31
	s_lshl_b64 s[0:1], s[0:1], 12
	v_mov_b32_e32 v0, 0
	v_lshl_add_u64 v[132:133], s[0:1], 0, v[192:193]
	v_lshl_add_u64 v[134:135], s[0:1], 0, v[2:3]
	s_mov_b32 s3, -2
	v_add_u32_e32 v152, 0, v1
	v_add_u32_e32 v137, v5, v4
	s_mov_b64 s[0:1], s[50:51]
	v_mov_b32_e32 v1, v0
	v_mov_b32_e32 v2, v0
	v_mov_b32_e32 v3, v0
	v_mov_b32_e32 v4, v0
	v_mov_b32_e32 v5, v0
	v_mov_b32_e32 v6, v0
	v_mov_b32_e32 v7, v0
	v_mov_b32_e32 v8, v0
	v_mov_b32_e32 v9, v0
	v_mov_b32_e32 v10, v0
	v_mov_b32_e32 v11, v0
	v_mov_b32_e32 v12, v0
	v_mov_b32_e32 v13, v0
	v_mov_b32_e32 v14, v0
	v_mov_b32_e32 v15, v0
	v_mov_b32_e32 v16, v0
	v_mov_b32_e32 v17, v0
	v_mov_b32_e32 v18, v0
	v_mov_b32_e32 v19, v0
	v_mov_b32_e32 v20, v0
	v_mov_b32_e32 v21, v0
	v_mov_b32_e32 v22, v0
	v_mov_b32_e32 v23, v0
	v_mov_b32_e32 v24, v0
	v_mov_b32_e32 v25, v0
	v_mov_b32_e32 v26, v0
	v_mov_b32_e32 v27, v0
	v_mov_b32_e32 v28, v0
	v_mov_b32_e32 v29, v0
	v_mov_b32_e32 v30, v0
	v_mov_b32_e32 v31, v0
	v_mov_b32_e32 v32, v0
	v_mov_b32_e32 v33, v0
	v_mov_b32_e32 v34, v0
	v_mov_b32_e32 v35, v0
	v_mov_b32_e32 v36, v0
	v_mov_b32_e32 v37, v0
	v_mov_b32_e32 v38, v0
	v_mov_b32_e32 v39, v0
	v_mov_b32_e32 v40, v0
	v_mov_b32_e32 v41, v0
	v_mov_b32_e32 v42, v0
	v_mov_b32_e32 v43, v0
	v_mov_b32_e32 v44, v0
	v_mov_b32_e32 v45, v0
	v_mov_b32_e32 v46, v0
	v_mov_b32_e32 v47, v0
	v_mov_b32_e32 v48, v0
	v_mov_b32_e32 v49, v0
	v_mov_b32_e32 v50, v0
	v_mov_b32_e32 v51, v0
	v_mov_b32_e32 v52, v0
	v_mov_b32_e32 v53, v0
	v_mov_b32_e32 v54, v0
	v_mov_b32_e32 v55, v0
	v_mov_b32_e32 v56, v0
	v_mov_b32_e32 v57, v0
	v_mov_b32_e32 v58, v0
	v_mov_b32_e32 v59, v0
	v_mov_b32_e32 v60, v0
	v_mov_b32_e32 v61, v0
	v_mov_b32_e32 v62, v0
	v_mov_b32_e32 v63, v0
	v_mov_b32_e32 v64, v0
	v_mov_b32_e32 v65, v0
	v_mov_b32_e32 v66, v0
	v_mov_b32_e32 v67, v0
	v_mov_b32_e32 v68, v0
	v_mov_b32_e32 v69, v0
	v_mov_b32_e32 v70, v0
	v_mov_b32_e32 v71, v0
	v_mov_b32_e32 v72, v0
	v_mov_b32_e32 v73, v0
	v_mov_b32_e32 v74, v0
	v_mov_b32_e32 v75, v0
	v_mov_b32_e32 v76, v0
	v_mov_b32_e32 v77, v0
	v_mov_b32_e32 v78, v0
	v_mov_b32_e32 v79, v0
	v_mov_b32_e32 v80, v0
	v_mov_b32_e32 v81, v0
	v_mov_b32_e32 v82, v0
	v_mov_b32_e32 v83, v0
	v_mov_b32_e32 v84, v0
	v_mov_b32_e32 v85, v0
	v_mov_b32_e32 v86, v0
	v_mov_b32_e32 v87, v0
	v_mov_b32_e32 v88, v0
	v_mov_b32_e32 v89, v0
	v_mov_b32_e32 v90, v0
	v_mov_b32_e32 v91, v0
	v_mov_b32_e32 v92, v0
	v_mov_b32_e32 v93, v0
	v_mov_b32_e32 v94, v0
	v_mov_b32_e32 v95, v0
	v_mov_b32_e32 v96, v0
	v_mov_b32_e32 v97, v0
	v_mov_b32_e32 v98, v0
	v_mov_b32_e32 v99, v0
	v_mov_b32_e32 v100, v0
	v_mov_b32_e32 v101, v0
	v_mov_b32_e32 v102, v0
	v_mov_b32_e32 v103, v0
	v_mov_b32_e32 v104, v0
	v_mov_b32_e32 v105, v0
	v_mov_b32_e32 v106, v0
	v_mov_b32_e32 v107, v0
	v_mov_b32_e32 v108, v0
	v_mov_b32_e32 v109, v0
	v_mov_b32_e32 v110, v0
	v_mov_b32_e32 v111, v0
	v_mov_b32_e32 v112, v0
	v_mov_b32_e32 v113, v0
	v_mov_b32_e32 v114, v0
	v_mov_b32_e32 v115, v0
	v_mov_b32_e32 v116, v0
	v_mov_b32_e32 v117, v0
	v_mov_b32_e32 v118, v0
	v_mov_b32_e32 v119, v0
	v_mov_b32_e32 v120, v0
	v_mov_b32_e32 v121, v0
	v_mov_b32_e32 v122, v0
	v_mov_b32_e32 v123, v0
	v_mov_b32_e32 v124, v0
	v_mov_b32_e32 v125, v0
	v_mov_b32_e32 v126, v0
	v_mov_b32_e32 v127, v0
	v_readfirstlane_b32 s4, v153
	s_waitcnt vmcnt(0)
	s_barrier
	s_barrier

; #define WAIT_V(n) asm volatile("s_waitcnt vmcnt(" #n ")" ::: "memory")
; #define BAR __builtin_amdgcn_s_barrier()
; template <bool SWAP>
; __device__ __forceinline__ void gemm_main(const u16* __restrict__ A, const u16* __restrict__ Bt, int brow, int bcol,
;                                           u16* shm, f32x4 (&acc)[2][2][4][2]) {
;     ...
;   int tx = threadIdx.x; asm volatile("" : "+v"(tx));
;   const int wid = tx >> 6, lane = tx & 63, wr = wid >> 2, wc = wid & 3, fr = lane & 15, fq = lane >> 4;
; #pragma unroll
;   for (int a = 0; a < 2; ++a)
; #pragma unroll
;     for (int b = 0; b < 2; ++b)
; #pragma unroll
;       for (int m = 0; m < 4; ++m)
; #pragma unroll
;         for (int n = 0; n < 2; ++n) acc[a][b][m][n] = f32x4{0.f, 0.f, 0.f, 0.f};
;   bf16x8 At[4][2], B0[2][2], B1[2][2];
;   constexpr int nt = GK / BK;
;   GEMM_VOFF
;   const int lpart = (fr * 64 + fq * 16) ^ ((fr >> 3) << 5);
;   const int abase = wr * 8192 + lpart; int bbase = 65536 + wc * 4096 + lpart;
;   asm volatile("" : "+v"(bbase));
;   if (wr == 1) BAR;
;   WAIT_V(0); BAR;
;   BAR;
.LBB0_199:
	s_or_b64 exec, exec, s[0:1]
	v_bfe_i32 v4, v136, 27, 1
	v_lshlrev_b32_e32 v153, 4, v136
	v_lshrrev_b32_e32 v4, 22, v4
	v_add_u32_e32 v4, v153, v4
	v_and_b32_e32 v4, 0xfffffc00, v4
	v_sub_u32_e32 v4, v153, v4
	v_lshrrev_b32_e32 v5, 4, v4
	v_bitop3_b32 v4, v5, v4, 32 bitop3:0x6c
	v_ashrrev_i32_e32 v5, 31, v4
	v_lshrrev_b32_e32 v5, 26, v5
	v_add_u32_e32 v5, v4, v5
	v_ashrrev_i32_e32 v155, 6, v5
	v_and_b32_e32 v5, 0xc0, v5
	v_sub_u32_e32 v4, v4, v5
	v_ashrrev_i16_sdwa v4, v215, sext(v4) dst_sel:DWORD dst_unused:UNUSED_PAD src0_sel:DWORD src1_sel:BYTE_0
	v_bfe_i32 v156, v4, 0, 16
	v_add_u32_e32 v4, 0x2000, v153
	v_ashrrev_i32_e32 v5, 31, v4
	v_lshrrev_b32_e32 v5, 22, v5
	v_add_u32_e32 v5, v4, v5
	v_ashrrev_i32_e32 v157, 10, v5
	v_mul_i32_i24_e32 v5, 0x400, v157
	v_sub_u32_e32 v4, v4, v5
	v_lshrrev_b32_e32 v5, 4, v4
	v_bitop3_b32 v4, v5, v4, 32 bitop3:0x6c
	v_ashrrev_i32_e32 v5, 31, v4
	v_lshrrev_b32_e32 v5, 26, v5
	v_ashrrev_i32_e32 v3, 31, v136
	v_add_u32_e32 v5, v4, v5
	v_lshrrev_b32_e32 v3, 26, v3
	v_ashrrev_i32_e32 v158, 6, v5
	v_and_b32_e32 v5, 0xc0, v5
	v_add_u32_e32 v3, v136, v3
	v_sub_u32_e32 v4, v4, v5
	v_ashrrev_i32_e32 v154, 6, v3
	v_ashrrev_i16_sdwa v4, v215, sext(v4) dst_sel:DWORD dst_unused:UNUSED_PAD src0_sel:DWORD src1_sel:BYTE_0
	v_bfe_i32 v159, v4, 0, 16
	v_lshlrev_b32_e32 v4, 13, v0
	v_lshlrev_b32_e32 v0, 15, v154
	v_and_b32_e32 v0, 0xffff0000, v0
	v_lshl_add_u32 v0, v155, 12, v0
	v_and_or_b32 v0, v3, 64, v0
	v_lshl_add_u32 v192, v156, 1, v0
	v_lshlrev_b32_e32 v0, 15, v157
	v_and_b32_e32 v0, 0xffff0000, v0
	v_add_u32_e32 v5, 0, v2
	v_lshl_add_u32 v0, v158, 12, v0
	v_lshlrev_b32_e32 v2, 6, v157
	s_ashr_i32 s43, s42, 31
	v_and_or_b32 v0, v2, 64, v0
	s_lshl_b64 s[0:1], s[42:43], 12
	v_lshl_add_u32 v2, v159, 1, v0
	v_mov_b32_e32 v3, v193
	v_lshl_add_u64 v[128:129], s[0:1], 0, v[192:193]
	v_lshl_add_u64 v[130:131], s[0:1], 0, v[2:3]
	s_add_i32 s0, s93, s73
	s_ashr_i32 s1, s0, 31
	s_lshl_b64 s[0:1], s[0:1], 12
	v_mov_b32_e32 v0, 0
	v_lshl_add_u64 v[132:133], s[0:1], 0, v[192:193]
	v_lshl_add_u64 v[134:135], s[0:1], 0, v[2:3]
	s_mov_b32 s2, -2
	v_add_u32_e32 v152, 0, v1
	v_add_u32_e32 v137, v5, v4
	s_mov_b64 s[0:1], s[50:51]
	v_mov_b32_e32 v1, v0
	v_mov_b32_e32 v2, v0
	v_mov_b32_e32 v3, v0
	v_mov_b32_e32 v4, v0
	v_mov_b32_e32 v5, v0
	v_mov_b32_e32 v6, v0
	v_mov_b32_e32 v7, v0
	v_mov_b32_e32 v8, v0
	v_mov_b32_e32 v9, v0
	v_mov_b32_e32 v10, v0
	v_mov_b32_e32 v11, v0
	v_mov_b32_e32 v12, v0
	v_mov_b32_e32 v13, v0
	v_mov_b32_e32 v14, v0
	v_mov_b32_e32 v15, v0
	v_mov_b32_e32 v16, v0
	v_mov_b32_e32 v17, v0
	v_mov_b32_e32 v18, v0
	v_mov_b32_e32 v19, v0
	v_mov_b32_e32 v20, v0
	v_mov_b32_e32 v21, v0
	v_mov_b32_e32 v22, v0
	v_mov_b32_e32 v23, v0
	v_mov_b32_e32 v24, v0
	v_mov_b32_e32 v25, v0
	v_mov_b32_e32 v26, v0
	v_mov_b32_e32 v27, v0
	v_mov_b32_e32 v28, v0
	v_mov_b32_e32 v29, v0
	v_mov_b32_e32 v30, v0
	v_mov_b32_e32 v31, v0
	v_mov_b32_e32 v32, v0
	v_mov_b32_e32 v33, v0
	v_mov_b32_e32 v34, v0
	v_mov_b32_e32 v35, v0
	v_mov_b32_e32 v36, v0
	v_mov_b32_e32 v37, v0
	v_mov_b32_e32 v38, v0
	v_mov_b32_e32 v39, v0
	v_mov_b32_e32 v40, v0
	v_mov_b32_e32 v41, v0
	v_mov_b32_e32 v42, v0
	v_mov_b32_e32 v43, v0
	v_mov_b32_e32 v44, v0
	v_mov_b32_e32 v45, v0
	v_mov_b32_e32 v46, v0
	v_mov_b32_e32 v47, v0
	v_mov_b32_e32 v48, v0
	v_mov_b32_e32 v49, v0
	v_mov_b32_e32 v50, v0
	v_mov_b32_e32 v51, v0
	v_mov_b32_e32 v52, v0
	v_mov_b32_e32 v53, v0
	v_mov_b32_e32 v54, v0
	v_mov_b32_e32 v55, v0
	v_mov_b32_e32 v56, v0
	v_mov_b32_e32 v57, v0
	v_mov_b32_e32 v58, v0
	v_mov_b32_e32 v59, v0
	v_mov_b32_e32 v60, v0
	v_mov_b32_e32 v61, v0
	v_mov_b32_e32 v62, v0
	v_mov_b32_e32 v63, v0
	v_mov_b32_e32 v64, v0
	v_mov_b32_e32 v65, v0
	v_mov_b32_e32 v66, v0
	v_mov_b32_e32 v67, v0
	v_mov_b32_e32 v68, v0
	v_mov_b32_e32 v69, v0
	v_mov_b32_e32 v70, v0
	v_mov_b32_e32 v71, v0
	v_mov_b32_e32 v72, v0
	v_mov_b32_e32 v73, v0
	v_mov_b32_e32 v74, v0
	v_mov_b32_e32 v75, v0
	v_mov_b32_e32 v76, v0
	v_mov_b32_e32 v77, v0
	v_mov_b32_e32 v78, v0
	v_mov_b32_e32 v79, v0
	v_mov_b32_e32 v80, v0
	v_mov_b32_e32 v81, v0
	v_mov_b32_e32 v82, v0
	v_mov_b32_e32 v83, v0
	v_mov_b32_e32 v84, v0
	v_mov_b32_e32 v85, v0
	v_mov_b32_e32 v86, v0
	v_mov_b32_e32 v87, v0
	v_mov_b32_e32 v88, v0
	v_mov_b32_e32 v89, v0
	v_mov_b32_e32 v90, v0
	v_mov_b32_e32 v91, v0
	v_mov_b32_e32 v92, v0
	v_mov_b32_e32 v93, v0
	v_mov_b32_e32 v94, v0
	v_mov_b32_e32 v95, v0
	v_mov_b32_e32 v96, v0
	v_mov_b32_e32 v97, v0
	v_mov_b32_e32 v98, v0
	v_mov_b32_e32 v99, v0
	v_mov_b32_e32 v100, v0
	v_mov_b32_e32 v101, v0
	v_mov_b32_e32 v102, v0
	v_mov_b32_e32 v103, v0
	v_mov_b32_e32 v104, v0
	v_mov_b32_e32 v105, v0
	v_mov_b32_e32 v106, v0
	v_mov_b32_e32 v107, v0
	v_mov_b32_e32 v108, v0
	v_mov_b32_e32 v109, v0
	v_mov_b32_e32 v110, v0
	v_mov_b32_e32 v111, v0
	v_mov_b32_e32 v112, v0
	v_mov_b32_e32 v113, v0
	v_mov_b32_e32 v114, v0
	v_mov_b32_e32 v115, v0
	v_mov_b32_e32 v116, v0
	v_mov_b32_e32 v117, v0
	v_mov_b32_e32 v118, v0
	v_mov_b32_e32 v119, v0
	v_mov_b32_e32 v120, v0
	v_mov_b32_e32 v121, v0
	v_mov_b32_e32 v122, v0
	v_mov_b32_e32 v123, v0
	v_mov_b32_e32 v124, v0
	v_mov_b32_e32 v125, v0
	v_mov_b32_e32 v126, v0
	v_mov_b32_e32 v127, v0
	v_readfirstlane_b32 s3, v153
	s_waitcnt vmcnt(0)
	s_barrier
	s_barrier

; #define WAIT_V(n) asm volatile("s_waitcnt vmcnt(" #n ")" ::: "memory")
; __device__ __forceinline__ void phase_inproj1(const Params& p, char* smem) {
;     ...
;     WAIT_V(0);
;   }
; }
.LBB0_205:
	s_waitcnt vmcnt(0)
	v_readlane_b32 s18, v252, 24
	v_readlane_b32 s19, v252, 25

; __global__ void __launch_bounds__(NT) fwd_megakernel(Params p) {
;     ...
;     for (int sg = 0; sg < THALF / SGT; ++sg) {
;       phase_inproj2(p, half, sg, smem);
;       xcd_barrier(xb);
;       phase_attn_conv(p, half, sg, smem);
;       xcd_barrier(xb);
;       phase_branch(p, smem);
;       xcd_barrier(xb);
;       phase_outproj(p, half, sg, smem);
;     }
.LBB0_427:
	s_waitcnt vmcnt(0)
	v_readlane_b32 s0, v252, 40
	v_readlane_b32 s1, v252, 41
	s_mov_b32 s2, 1
	s_mov_b64 s[14:15], 0
	s_and_b64 vcc, exec, s[0:1]
	s_cbranch_vccnz .LBB0_632

; __device__ __forceinline__ void phase_inproj2(const Params& p, int half, int sg, char* smem) {
;     ...
;   for (int it = blockIdx.x; it < NT2; it += gridDim.x) {
;     IN2_TILE(it, nt, brow)
;     const int itn = it + gridDim.x;
;     f32x4 acc[2][2][4][2];
;     gemm_main<true>(A, Bt, brow, nt * 256, (u16*)smem, acc);
;     IN2_TILE(itn, ntn, brown)
;     if (itn < NT2) gemm_issue(A, Bt, brown, ntn * 256, (u16*)smem);
.LBB0_432:
	s_nop 1
	s_andn2_b64 vcc, exec, s[8:9]
	s_cbranch_vccz .LBB0_457

; #define WAIT_V(n) asm volatile("s_waitcnt vmcnt(" #n ")" ::: "memory")
; #define BAR __builtin_amdgcn_s_barrier()
; template <bool SWAP>
; __device__ __forceinline__ void gemm_main(const u16* __restrict__ A, const u16* __restrict__ Bt, int brow, int bcol,
;                                           u16* shm, f32x4 (&acc)[2][2][4][2]) {
;     ...
;   int tx = threadIdx.x; asm volatile("" : "+v"(tx));
;   const int wid = tx >> 6, lane = tx & 63, wr = wid >> 2, wc = wid & 3, fr = lane & 15, fq = lane >> 4;
; #pragma unroll
;   for (int a = 0; a < 2; ++a)
; #pragma unroll
;     for (int b = 0; b < 2; ++b)
; #pragma unroll
;       for (int m = 0; m < 4; ++m)
; #pragma unroll
;         for (int n = 0; n < 2; ++n) acc[a][b][m][n] = f32x4{0.f, 0.f, 0.f, 0.f};
;   bf16x8 At[4][2], B0[2][2], B1[2][2];
;   constexpr int nt = GK / BK;
;   GEMM_VOFF
;   const int lpart = (fr * 64 + fq * 16) ^ ((fr >> 3) << 5);
;   const int abase = wr * 8192 + lpart; int bbase = 65536 + wc * 4096 + lpart;
;   asm volatile("" : "+v"(bbase));
;   if (wr == 1) BAR;
;   WAIT_V(0); BAR;
;   BAR;
.LBB0_435:
	s_or_b64 exec, exec, s[0:1]
	v_bfe_i32 v4, v136, 27, 1
	v_lshlrev_b32_e32 v139, 4, v136
	v_lshrrev_b32_e32 v4, 22, v4
	v_add_u32_e32 v4, v139, v4
	v_and_b32_e32 v4, 0xfffffc00, v4
	v_sub_u32_e32 v4, v139, v4
	v_lshrrev_b32_e32 v5, 4, v4
	v_bitop3_b32 v4, v5, v4, 32 bitop3:0x6c
	v_ashrrev_i32_e32 v5, 31, v4
	v_lshrrev_b32_e32 v5, 26, v5
	v_add_u32_e32 v5, v4, v5
	v_ashrrev_i32_e32 v143, 6, v5
	v_and_b32_e32 v5, 0xc0, v5
	v_sub_u32_e32 v4, v4, v5
	v_ashrrev_i16_sdwa v4, v215, sext(v4) dst_sel:DWORD dst_unused:UNUSED_PAD src0_sel:DWORD src1_sel:BYTE_0
	v_bfe_i32 v144, v4, 0, 16
	v_add_u32_e32 v4, 0x2000, v139
	v_ashrrev_i32_e32 v5, 31, v4
	v_lshrrev_b32_e32 v5, 22, v5
	v_add_u32_e32 v5, v4, v5
	v_ashrrev_i32_e32 v145, 10, v5
	v_mul_i32_i24_e32 v5, 0x400, v145
	v_sub_u32_e32 v4, v4, v5
	v_lshrrev_b32_e32 v5, 4, v4
	v_bitop3_b32 v4, v5, v4, 32 bitop3:0x6c
	v_ashrrev_i32_e32 v5, 31, v4
	v_lshrrev_b32_e32 v5, 26, v5
	v_ashrrev_i32_e32 v3, 31, v136
	v_add_u32_e32 v5, v4, v5
	v_lshrrev_b32_e32 v3, 26, v3
	v_ashrrev_i32_e32 v146, 6, v5
	v_and_b32_e32 v5, 0xc0, v5
	v_add_u32_e32 v3, v136, v3
	v_sub_u32_e32 v4, v4, v5
	s_mul_hi_i32 s0, s24, 0x2e8ba2e9
	v_ashrrev_i32_e32 v142, 6, v3
	v_ashrrev_i16_sdwa v4, v215, sext(v4) dst_sel:DWORD dst_unused:UNUSED_PAD src0_sel:DWORD src1_sel:BYTE_0
	s_lshr_b32 s1, s0, 31
	s_ashr_i32 s0, s0, 9
	v_bfe_i32 v147, v4, 0, 16
	v_lshlrev_b32_e32 v4, 13, v0
	v_lshlrev_b32_e32 v0, 15, v142
	s_add_i32 s0, s0, s1
	v_and_b32_e32 v0, 0xffff0000, v0
	s_mul_i32 s1, s0, 0xb00
	v_lshl_add_u32 v0, v143, 12, v0
	s_sub_i32 s1, s24, s1
	v_and_or_b32 v0, v3, 64, v0
	s_ashr_i32 s25, s1, 5
	v_lshl_add_u32 v192, v144, 1, v0
	v_lshlrev_b32_e32 v0, 15, v145
	s_lshl_b32 s2, s0, 13
	s_lshl_b32 s0, s1, 8
	s_lshl_b32 s6, s25, 8
	v_and_b32_e32 v0, 0xffff0000, v0
	s_and_b32 s3, s0, 0x1f00
	s_add_i32 s0, s6, 0x1900
	v_add_u32_e32 v5, 0, v2
	v_lshl_add_u32 v0, v146, 12, v0
	v_lshlrev_b32_e32 v2, 6, v145
	s_ashr_i32 s1, s0, 31
	v_and_or_b32 v0, v2, 64, v0
	s_lshl_b64 s[0:1], s[0:1], 12
	v_lshl_add_u32 v2, v147, 1, v0
	v_mov_b32_e32 v3, v193
	v_lshl_add_u64 v[128:129], s[0:1], 0, v[192:193]
	v_lshl_add_u64 v[130:131], s[0:1], 0, v[2:3]
	s_or_b32 s0, s2, s3
	s_ashr_i32 s1, s0, 31
	s_lshl_b64 s[2:3], s[0:1], 12
	s_add_u32 s2, s4, s2
	s_addc_u32 s3, s5, s3
	v_mov_b32_e32 v0, 0
	v_lshl_add_u64 v[132:133], s[2:3], 0, v[192:193]
	v_lshl_add_u64 v[134:135], s[2:3], 0, v[2:3]
	s_mov_b32 s1, -2
	v_add_u32_e32 v138, 0, v1
	v_add_u32_e32 v137, v5, v4
	v_mov_b32_e32 v1, v0
	v_mov_b32_e32 v2, v0
	v_mov_b32_e32 v3, v0
	v_mov_b32_e32 v4, v0
	v_mov_b32_e32 v5, v0
	v_mov_b32_e32 v6, v0
	v_mov_b32_e32 v7, v0
	v_mov_b32_e32 v8, v0
	v_mov_b32_e32 v9, v0
	v_mov_b32_e32 v10, v0
	v_mov_b32_e32 v11, v0
	v_mov_b32_e32 v12, v0
	v_mov_b32_e32 v13, v0
	v_mov_b32_e32 v14, v0
	v_mov_b32_e32 v15, v0
	v_mov_b32_e32 v16, v0
	v_mov_b32_e32 v17, v0
	v_mov_b32_e32 v18, v0
	v_mov_b32_e32 v19, v0
	v_mov_b32_e32 v20, v0
	v_mov_b32_e32 v21, v0
	v_mov_b32_e32 v22, v0
	v_mov_b32_e32 v23, v0
	v_mov_b32_e32 v24, v0
	v_mov_b32_e32 v25, v0
	v_mov_b32_e32 v26, v0
	v_mov_b32_e32 v27, v0
	v_mov_b32_e32 v28, v0
	v_mov_b32_e32 v29, v0
	v_mov_b32_e32 v30, v0
	v_mov_b32_e32 v31, v0
	v_mov_b32_e32 v32, v0
	v_mov_b32_e32 v33, v0
	v_mov_b32_e32 v34, v0
	v_mov_b32_e32 v35, v0
	v_mov_b32_e32 v36, v0
	v_mov_b32_e32 v37, v0
	v_mov_b32_e32 v38, v0
	v_mov_b32_e32 v39, v0
	v_mov_b32_e32 v40, v0
	v_mov_b32_e32 v41, v0
	v_mov_b32_e32 v42, v0
	v_mov_b32_e32 v43, v0
	v_mov_b32_e32 v44, v0
	v_mov_b32_e32 v45, v0
	v_mov_b32_e32 v46, v0
	v_mov_b32_e32 v47, v0
	v_mov_b32_e32 v48, v0
	v_mov_b32_e32 v49, v0
	v_mov_b32_e32 v50, v0
	v_mov_b32_e32 v51, v0
	v_mov_b32_e32 v52, v0
	v_mov_b32_e32 v53, v0
	v_mov_b32_e32 v54, v0
	v_mov_b32_e32 v55, v0
	v_mov_b32_e32 v56, v0
	v_mov_b32_e32 v57, v0
	v_mov_b32_e32 v58, v0
	v_mov_b32_e32 v59, v0
	v_mov_b32_e32 v60, v0
	v_mov_b32_e32 v61, v0
	v_mov_b32_e32 v62, v0
	v_mov_b32_e32 v63, v0
	v_mov_b32_e32 v64, v0
	v_mov_b32_e32 v65, v0
	v_mov_b32_e32 v66, v0
	v_mov_b32_e32 v67, v0
	v_mov_b32_e32 v68, v0
	v_mov_b32_e32 v69, v0
	v_mov_b32_e32 v70, v0
	v_mov_b32_e32 v71, v0
	v_mov_b32_e32 v72, v0
	v_mov_b32_e32 v73, v0
	v_mov_b32_e32 v74, v0
	v_mov_b32_e32 v75, v0
	v_mov_b32_e32 v76, v0
	v_mov_b32_e32 v77, v0
	v_mov_b32_e32 v78, v0
	v_mov_b32_e32 v79, v0
	v_mov_b32_e32 v80, v0
	v_mov_b32_e32 v81, v0
	v_mov_b32_e32 v82, v0
	v_mov_b32_e32 v83, v0
	v_mov_b32_e32 v84, v0
	v_mov_b32_e32 v85, v0
	v_mov_b32_e32 v86, v0
	v_mov_b32_e32 v87, v0
	v_mov_b32_e32 v88, v0
	v_mov_b32_e32 v89, v0
	v_mov_b32_e32 v90, v0
	v_mov_b32_e32 v91, v0
	v_mov_b32_e32 v92, v0
	v_mov_b32_e32 v93, v0
	v_mov_b32_e32 v94, v0
	v_mov_b32_e32 v95, v0
	v_mov_b32_e32 v96, v0
	v_mov_b32_e32 v97, v0
	v_mov_b32_e32 v98, v0
	v_mov_b32_e32 v99, v0
	v_mov_b32_e32 v100, v0
	v_mov_b32_e32 v101, v0
	v_mov_b32_e32 v102, v0
	v_mov_b32_e32 v103, v0
	v_mov_b32_e32 v104, v0
	v_mov_b32_e32 v105, v0
	v_mov_b32_e32 v106, v0
	v_mov_b32_e32 v107, v0
	v_mov_b32_e32 v108, v0
	v_mov_b32_e32 v109, v0
	v_mov_b32_e32 v110, v0
	v_mov_b32_e32 v111, v0
	v_mov_b32_e32 v112, v0
	v_mov_b32_e32 v113, v0
	v_mov_b32_e32 v114, v0
	v_mov_b32_e32 v115, v0
	v_mov_b32_e32 v116, v0
	v_mov_b32_e32 v117, v0
	v_mov_b32_e32 v118, v0
	v_mov_b32_e32 v119, v0
	v_mov_b32_e32 v120, v0
	v_mov_b32_e32 v121, v0
	v_mov_b32_e32 v122, v0
	v_mov_b32_e32 v123, v0
	v_mov_b32_e32 v124, v0
	v_mov_b32_e32 v125, v0
	v_mov_b32_e32 v126, v0
	v_mov_b32_e32 v127, v0
	v_readfirstlane_b32 s2, v139
	s_waitcnt vmcnt(0)
	s_barrier
	s_barrier

.LBB0_560:
	v_mov_b32_e32 v128, v224
	v_mov_b32_e32 v129, v223
	v_readlane_b32 s2, v251, 52
	v_add_u32_e32 v226, s55, v128
	v_add_lshl_u32 v227, v129, s8, 11
	v_add_u32_e32 v192, v227, v226
	v_lshlrev_b64 v[128:129], 1, v[192:193]
	v_readlane_b32 s3, v251, 53
	v_lshl_add_u64 v[208:209], s[84:85], 0, v[128:129]
	global_load_dwordx4 v[184:187], v[208:209], off
	v_lshl_add_u64 v[130:131], s[2:3], 0, v[128:129]
	global_load_dwordx4 v[188:191], v[130:131], off
	v_add_u32_e32 v132, 0x8000, v227
	v_add_u32_e32 v192, v132, v226
	v_lshlrev_b64 v[128:129], 1, v[192:193]
	v_lshl_add_u64 v[206:207], s[84:85], 0, v[128:129]
	global_load_dwordx4 v[176:179], v[206:207], off
	v_lshl_add_u64 v[130:131], s[2:3], 0, v[128:129]
	global_load_dwordx4 v[180:183], v[130:131], off
	v_add_u32_e32 v133, 0x10000, v227
	v_add_u32_e32 v192, v133, v226
	v_lshlrev_b64 v[128:129], 1, v[192:193]
	v_lshl_add_u64 v[204:205], s[84:85], 0, v[128:129]
	global_load_dwordx4 v[168:171], v[204:205], off
	v_lshl_add_u64 v[130:131], s[2:3], 0, v[128:129]
	global_load_dwordx4 v[172:175], v[130:131], off
	v_add_u32_e32 v134, 0x18000, v227
	v_add_u32_e32 v192, v134, v226
	v_lshlrev_b64 v[128:129], 1, v[192:193]
	v_lshl_add_u64 v[202:203], s[84:85], 0, v[128:129]
	global_load_dwordx4 v[160:163], v[202:203], off
	v_lshl_add_u64 v[130:131], s[2:3], 0, v[128:129]
	global_load_dwordx4 v[164:167], v[130:131], off
	v_add_u32_e32 v225, 0x80, v226
	v_add_u32_e32 v192, v225, v227
	v_lshlrev_b64 v[128:129], 1, v[192:193]
	v_lshl_add_u64 v[200:201], s[84:85], 0, v[128:129]
	v_add_u32_e32 v192, v132, v225
	global_load_dwordx4 v[152:155], v[200:201], off
	v_lshl_add_u64 v[130:131], s[2:3], 0, v[128:129]
	v_lshlrev_b64 v[128:129], 1, v[192:193]
	v_lshl_add_u64 v[198:199], s[84:85], 0, v[128:129]
	v_add_u32_e32 v192, v133, v225
	global_load_dwordx4 v[156:159], v[130:131], off
	global_load_dwordx4 v[144:147], v[198:199], off
	v_lshl_add_u64 v[130:131], s[2:3], 0, v[128:129]
	v_lshlrev_b64 v[128:129], 1, v[192:193]
	v_add_u32_e32 v192, v134, v225
	v_lshl_add_u64 v[196:197], s[84:85], 0, v[128:129]
	v_lshlrev_b64 v[132:133], 1, v[192:193]
	global_load_dwordx4 v[148:151], v[130:131], off
	global_load_dwordx4 v[136:139], v[196:197], off
	v_lshl_add_u64 v[130:131], s[2:3], 0, v[128:129]
	v_lshl_add_u64 v[128:129], s[2:3], 0, v[132:133]
	v_lshl_add_u64 v[194:195], s[84:85], 0, v[132:133]
	global_load_dwordx4 v[140:143], v[130:131], off
	global_load_dwordx4 v[132:135], v[194:195], off
	s_waitcnt vmcnt(0)
	v_mov_b32_e32 v229, v186
	global_load_dwordx4 v[128:131], v[128:129], off
	v_mov_b32_e32 v192, v190
	v_mov_b32_e32 v228, v191
	v_mov_b32_e32 v230, v187
	v_permlane16_swap_b32_e32 v188, v192
	v_permlane16_swap_b32_e32 v189, v228
	v_permlane16_swap_b32_e32 v184, v229
	v_permlane16_swap_b32_e32 v185, v230
	v_lshlrev_b32_e32 v186, 16, v188
	v_and_b32_e32 v187, 0xffff0000, v188
	v_lshlrev_b32_e32 v188, 16, v189
	v_and_b32_e32 v189, 0xffff0000, v189
	v_lshlrev_b32_e32 v190, 16, v184
	v_and_b32_e32 v191, 0xffff0000, v184
	v_lshlrev_b32_e32 v184, 16, v185
	v_and_b32_e32 v185, 0xffff0000, v185
	v_pk_fma_f32 v[124:125], v[124:125], v[186:187], v[190:191]
	v_pk_fma_f32 v[126:127], v[126:127], v[188:189], v[184:185]
	v_cvt_pk_bf16_f32 v124, v124, v125
	v_cvt_pk_bf16_f32 v125, v126, v127
	v_lshlrev_b32_e32 v126, 16, v192
	v_and_b32_e32 v127, 0xffff0000, v192
	v_lshlrev_b32_e32 v186, 16, v229
	v_and_b32_e32 v187, 0xffff0000, v229
	v_lshlrev_b32_e32 v184, 16, v228
	v_and_b32_e32 v185, 0xffff0000, v228
	v_pk_fma_f32 v[120:121], v[120:121], v[126:127], v[186:187]
	v_lshlrev_b32_e32 v126, 16, v230
	v_and_b32_e32 v127, 0xffff0000, v230
	v_pk_fma_f32 v[122:123], v[122:123], v[184:185], v[126:127]
	v_cvt_pk_bf16_f32 v126, v120, v121
	v_cvt_pk_bf16_f32 v127, v122, v123
	s_nop 0
	v_permlane16_swap_b32_e32 v124, v126
	v_permlane16_swap_b32_e32 v125, v127
	global_store_dwordx4 v[208:209], v[124:127], off
	v_permlane16_swap_b32_e32 v176, v178
	s_nop 0
	v_mov_b32_e32 v126, v182
	s_nop 1
	v_permlane16_swap_b32_e32 v180, v126
	v_mov_b32_e32 v127, v183
	s_nop 1
	v_permlane16_swap_b32_e32 v181, v127
	v_permlane16_swap_b32_e32 v177, v179
	v_lshlrev_b32_e32 v120, 16, v180
	v_and_b32_e32 v121, 0xffff0000, v180
	v_lshlrev_b32_e32 v124, 16, v176
	v_and_b32_e32 v125, 0xffff0000, v176
	v_lshlrev_b32_e32 v122, 16, v181
	v_and_b32_e32 v123, 0xffff0000, v181
	v_pk_fma_f32 v[116:117], v[116:117], v[120:121], v[124:125]
	v_lshlrev_b32_e32 v120, 16, v177
	v_and_b32_e32 v121, 0xffff0000, v177
	v_pk_fma_f32 v[118:119], v[118:119], v[122:123], v[120:121]
	v_cvt_pk_bf16_f32 v116, v116, v117
	v_cvt_pk_bf16_f32 v117, v118, v119
	v_lshlrev_b32_e32 v118, 16, v126
	v_and_b32_e32 v119, 0xffff0000, v126
	v_lshlrev_b32_e32 v122, 16, v178
	v_and_b32_e32 v123, 0xffff0000, v178
	v_lshlrev_b32_e32 v120, 16, v127
	v_and_b32_e32 v121, 0xffff0000, v127
	v_pk_fma_f32 v[112:113], v[112:113], v[118:119], v[122:123]
	v_lshlrev_b32_e32 v118, 16, v179
	v_and_b32_e32 v119, 0xffff0000, v179
	v_pk_fma_f32 v[114:115], v[114:115], v[120:121], v[118:119]
	v_cvt_pk_bf16_f32 v118, v112, v113
	v_cvt_pk_bf16_f32 v119, v114, v115
	s_nop 0
	v_permlane16_swap_b32_e32 v116, v118
	v_permlane16_swap_b32_e32 v117, v119
	global_store_dwordx4 v[206:207], v[116:119], off
	v_mov_b32_e32 v120, v170
	s_nop 1
	v_permlane16_swap_b32_e32 v168, v120
	v_mov_b32_e32 v118, v174
	s_nop 1
	v_permlane16_swap_b32_e32 v172, v118
	v_mov_b32_e32 v119, v175
	v_mov_b32_e32 v121, v171
	s_nop 0
	v_permlane16_swap_b32_e32 v173, v119
	v_permlane16_swap_b32_e32 v169, v121
	v_lshlrev_b32_e32 v112, 16, v172
	v_and_b32_e32 v113, 0xffff0000, v172
	v_lshlrev_b32_e32 v116, 16, v168
	v_and_b32_e32 v117, 0xffff0000, v168
	v_lshlrev_b32_e32 v114, 16, v173
	v_and_b32_e32 v115, 0xffff0000, v173
	v_pk_fma_f32 v[108:109], v[108:109], v[112:113], v[116:117]
	v_lshlrev_b32_e32 v112, 16, v169
	v_and_b32_e32 v113, 0xffff0000, v169
	v_pk_fma_f32 v[110:111], v[110:111], v[114:115], v[112:113]
	v_cvt_pk_bf16_f32 v108, v108, v109
	v_cvt_pk_bf16_f32 v109, v110, v111
	v_lshlrev_b32_e32 v110, 16, v118
	v_and_b32_e32 v111, 0xffff0000, v118
	v_lshlrev_b32_e32 v114, 16, v120
	v_and_b32_e32 v115, 0xffff0000, v120
	v_lshlrev_b32_e32 v112, 16, v119
	v_and_b32_e32 v113, 0xffff0000, v119
	v_pk_fma_f32 v[104:105], v[104:105], v[110:111], v[114:115]
	v_lshlrev_b32_e32 v110, 16, v121
	v_and_b32_e32 v111, 0xffff0000, v121
	v_pk_fma_f32 v[106:107], v[106:107], v[112:113], v[110:111]
	v_cvt_pk_bf16_f32 v110, v104, v105
	v_cvt_pk_bf16_f32 v111, v106, v107
	s_nop 0
	v_permlane16_swap_b32_e32 v108, v110
	v_permlane16_swap_b32_e32 v109, v111
	global_store_dwordx4 v[204:205], v[108:111], off
	v_mov_b32_e32 v112, v162
	s_nop 1
	v_permlane16_swap_b32_e32 v160, v112
	v_mov_b32_e32 v110, v166
	s_nop 1
	v_permlane16_swap_b32_e32 v164, v110
	v_mov_b32_e32 v111, v167
	v_mov_b32_e32 v113, v163
	s_nop 0
	v_permlane16_swap_b32_e32 v165, v111
	v_permlane16_swap_b32_e32 v161, v113
	v_lshlrev_b32_e32 v104, 16, v164
	v_and_b32_e32 v105, 0xffff0000, v164
	v_lshlrev_b32_e32 v108, 16, v160
	v_and_b32_e32 v109, 0xffff0000, v160
	v_lshlrev_b32_e32 v106, 16, v165
	v_and_b32_e32 v107, 0xffff0000, v165
	v_pk_fma_f32 v[100:101], v[100:101], v[104:105], v[108:109]
	v_lshlrev_b32_e32 v104, 16, v161
	v_and_b32_e32 v105, 0xffff0000, v161
	v_pk_fma_f32 v[102:103], v[102:103], v[106:107], v[104:105]
	v_cvt_pk_bf16_f32 v100, v100, v101
	v_cvt_pk_bf16_f32 v101, v102, v103
	v_lshlrev_b32_e32 v102, 16, v110
	v_and_b32_e32 v103, 0xffff0000, v110
	v_lshlrev_b32_e32 v106, 16, v112
	v_and_b32_e32 v107, 0xffff0000, v112
	v_lshlrev_b32_e32 v104, 16, v111
	v_and_b32_e32 v105, 0xffff0000, v111
	v_pk_fma_f32 v[96:97], v[96:97], v[102:103], v[106:107]
	v_lshlrev_b32_e32 v102, 16, v113
	v_and_b32_e32 v103, 0xffff0000, v113
	v_pk_fma_f32 v[98:99], v[98:99], v[104:105], v[102:103]
	v_cvt_pk_bf16_f32 v102, v96, v97
	v_cvt_pk_bf16_f32 v103, v98, v99
	s_nop 0
	v_permlane16_swap_b32_e32 v100, v102
	v_permlane16_swap_b32_e32 v101, v103
	global_store_dwordx4 v[202:203], v[100:103], off
	v_add_u32_e32 v168, 0x40000, v227
	v_add_u32_e32 v192, v168, v226
	v_add_u32_e32 v169, 0x48000, v227
	v_lshlrev_b64 v[96:97], 1, v[192:193]
	v_add_u32_e32 v192, v169, v226
	v_add_u32_e32 v170, 0x50000, v227
	v_lshl_add_u64 v[98:99], s[2:3], 0, v[96:97]
	v_lshl_add_u64 v[166:167], s[84:85], 0, v[96:97]
	v_lshlrev_b64 v[96:97], 1, v[192:193]
	v_add_u32_e32 v192, v170, v226
	v_add_u32_e32 v171, 0x58000, v227
	global_load_dwordx4 v[124:127], v[98:99], off
	global_load_dwordx4 v[120:123], v[166:167], off
	v_lshl_add_u64 v[98:99], s[2:3], 0, v[96:97]
	v_lshl_add_u64 v[164:165], s[84:85], 0, v[96:97]
	v_lshlrev_b64 v[96:97], 1, v[192:193]
	v_add_u32_e32 v192, v171, v226
	global_load_dwordx4 v[116:119], v[98:99], off
	global_load_dwordx4 v[112:115], v[164:165], off
	v_lshl_add_u64 v[98:99], s[2:3], 0, v[96:97]
	v_lshl_add_u64 v[162:163], s[84:85], 0, v[96:97]
	v_lshlrev_b64 v[96:97], 1, v[192:193]
	global_load_dwordx4 v[108:111], v[98:99], off
	global_load_dwordx4 v[104:107], v[162:163], off
	v_lshl_add_u64 v[98:99], s[2:3], 0, v[96:97]
	v_lshl_add_u64 v[160:161], s[84:85], 0, v[96:97]
	global_load_dwordx4 v[100:103], v[98:99], off
	s_nop 0
	global_load_dwordx4 v[96:99], v[160:161], off
	v_mov_b32_e32 v172, v158
	v_mov_b32_e32 v173, v159
	v_mov_b32_e32 v174, v154
	v_mov_b32_e32 v175, v155
	v_permlane16_swap_b32_e32 v156, v172
	v_permlane16_swap_b32_e32 v157, v173
	v_permlane16_swap_b32_e32 v152, v174
	v_permlane16_swap_b32_e32 v153, v175
	v_lshlrev_b32_e32 v154, 16, v156
	v_and_b32_e32 v155, 0xffff0000, v156
	v_lshlrev_b32_e32 v156, 16, v157
	v_and_b32_e32 v157, 0xffff0000, v157
	v_lshlrev_b32_e32 v158, 16, v152
	v_and_b32_e32 v159, 0xffff0000, v152
	v_lshlrev_b32_e32 v152, 16, v153
	v_and_b32_e32 v153, 0xffff0000, v153
	v_pk_fma_f32 v[92:93], v[92:93], v[154:155], v[158:159]
	v_pk_fma_f32 v[94:95], v[94:95], v[156:157], v[152:153]
	v_cvt_pk_bf16_f32 v92, v92, v93
	v_cvt_pk_bf16_f32 v93, v94, v95
	v_lshlrev_b32_e32 v94, 16, v172
	v_and_b32_e32 v95, 0xffff0000, v172
	v_lshlrev_b32_e32 v154, 16, v174
	v_and_b32_e32 v155, 0xffff0000, v174
	v_lshlrev_b32_e32 v152, 16, v173
	v_and_b32_e32 v153, 0xffff0000, v173
	v_pk_fma_f32 v[88:89], v[88:89], v[94:95], v[154:155]
	v_lshlrev_b32_e32 v94, 16, v175
	v_and_b32_e32 v95, 0xffff0000, v175
	v_pk_fma_f32 v[90:91], v[90:91], v[152:153], v[94:95]
	v_cvt_pk_bf16_f32 v94, v88, v89
	v_cvt_pk_bf16_f32 v95, v90, v91
	s_nop 0
	v_permlane16_swap_b32_e32 v92, v94
	v_permlane16_swap_b32_e32 v93, v95
	global_store_dwordx4 v[200:201], v[92:95], off
	v_permlane16_swap_b32_e32 v144, v146
	s_nop 0
	v_mov_b32_e32 v94, v150
	s_nop 1
	v_permlane16_swap_b32_e32 v148, v94
	v_mov_b32_e32 v95, v151
	s_nop 1
	v_permlane16_swap_b32_e32 v149, v95
	v_permlane16_swap_b32_e32 v145, v147
	v_lshlrev_b32_e32 v88, 16, v148
	v_and_b32_e32 v89, 0xffff0000, v148
	v_lshlrev_b32_e32 v92, 16, v144
	v_and_b32_e32 v93, 0xffff0000, v144
	v_lshlrev_b32_e32 v90, 16, v149
	v_and_b32_e32 v91, 0xffff0000, v149
	v_pk_fma_f32 v[84:85], v[84:85], v[88:89], v[92:93]
	v_lshlrev_b32_e32 v88, 16, v145
	v_and_b32_e32 v89, 0xffff0000, v145
	v_pk_fma_f32 v[86:87], v[86:87], v[90:91], v[88:89]
	v_cvt_pk_bf16_f32 v84, v84, v85
	v_cvt_pk_bf16_f32 v85, v86, v87
	v_lshlrev_b32_e32 v86, 16, v94
	v_and_b32_e32 v87, 0xffff0000, v94
	v_lshlrev_b32_e32 v90, 16, v146
	v_and_b32_e32 v91, 0xffff0000, v146
	v_lshlrev_b32_e32 v88, 16, v95
	v_and_b32_e32 v89, 0xffff0000, v95
	v_pk_fma_f32 v[80:81], v[80:81], v[86:87], v[90:91]
	v_lshlrev_b32_e32 v86, 16, v147
	v_and_b32_e32 v87, 0xffff0000, v147
	v_pk_fma_f32 v[82:83], v[82:83], v[88:89], v[86:87]
	v_cvt_pk_bf16_f32 v86, v80, v81
	v_cvt_pk_bf16_f32 v87, v82, v83
	s_nop 0
	v_permlane16_swap_b32_e32 v84, v86
	v_permlane16_swap_b32_e32 v85, v87
	global_store_dwordx4 v[198:199], v[84:87], off
	v_mov_b32_e32 v88, v138
	s_nop 1
	v_permlane16_swap_b32_e32 v136, v88
	v_mov_b32_e32 v86, v142
	s_nop 1
	v_permlane16_swap_b32_e32 v140, v86
	v_mov_b32_e32 v87, v143
	v_mov_b32_e32 v89, v139
	s_nop 0
	v_permlane16_swap_b32_e32 v141, v87
	v_permlane16_swap_b32_e32 v137, v89
	v_lshlrev_b32_e32 v80, 16, v140
	v_and_b32_e32 v81, 0xffff0000, v140
	v_lshlrev_b32_e32 v84, 16, v136
	v_and_b32_e32 v85, 0xffff0000, v136
	v_lshlrev_b32_e32 v82, 16, v141
	v_and_b32_e32 v83, 0xffff0000, v141
	v_pk_fma_f32 v[76:77], v[76:77], v[80:81], v[84:85]
	v_lshlrev_b32_e32 v80, 16, v137
	v_and_b32_e32 v81, 0xffff0000, v137
	v_pk_fma_f32 v[78:79], v[78:79], v[82:83], v[80:81]
	v_cvt_pk_bf16_f32 v76, v76, v77
	v_cvt_pk_bf16_f32 v77, v78, v79
	v_lshlrev_b32_e32 v78, 16, v86
	v_and_b32_e32 v79, 0xffff0000, v86
	v_lshlrev_b32_e32 v82, 16, v88
	v_and_b32_e32 v83, 0xffff0000, v88
	v_lshlrev_b32_e32 v80, 16, v87
	v_and_b32_e32 v81, 0xffff0000, v87
	v_pk_fma_f32 v[72:73], v[72:73], v[78:79], v[82:83]
	v_lshlrev_b32_e32 v78, 16, v89
	v_and_b32_e32 v79, 0xffff0000, v89
	v_pk_fma_f32 v[74:75], v[74:75], v[80:81], v[78:79]
	v_cvt_pk_bf16_f32 v78, v72, v73
	v_cvt_pk_bf16_f32 v79, v74, v75
	s_nop 0
	v_permlane16_swap_b32_e32 v76, v78
	v_permlane16_swap_b32_e32 v77, v79
	global_store_dwordx4 v[196:197], v[76:79], off
	v_mov_b32_e32 v80, v134
	s_nop 1
	v_permlane16_swap_b32_e32 v132, v80
	s_waitcnt vmcnt(0)
	v_mov_b32_e32 v78, v130
	s_nop 1
	v_permlane16_swap_b32_e32 v128, v78
	v_mov_b32_e32 v79, v131
	v_mov_b32_e32 v81, v135
	s_nop 0
	v_permlane16_swap_b32_e32 v129, v79
	v_permlane16_swap_b32_e32 v133, v81
	v_lshlrev_b32_e32 v72, 16, v128
	v_and_b32_e32 v73, 0xffff0000, v128
	v_lshlrev_b32_e32 v76, 16, v132
	v_and_b32_e32 v77, 0xffff0000, v132
	v_lshlrev_b32_e32 v74, 16, v129
	v_and_b32_e32 v75, 0xffff0000, v129
	v_pk_fma_f32 v[68:69], v[68:69], v[72:73], v[76:77]
	v_lshlrev_b32_e32 v72, 16, v133
	v_and_b32_e32 v73, 0xffff0000, v133
	v_pk_fma_f32 v[70:71], v[70:71], v[74:75], v[72:73]
	v_cvt_pk_bf16_f32 v68, v68, v69
	v_cvt_pk_bf16_f32 v69, v70, v71
	v_lshlrev_b32_e32 v70, 16, v78
	v_and_b32_e32 v71, 0xffff0000, v78
	v_lshlrev_b32_e32 v74, 16, v80
	v_and_b32_e32 v75, 0xffff0000, v80
	v_lshlrev_b32_e32 v72, 16, v79
	v_and_b32_e32 v73, 0xffff0000, v79
	v_pk_fma_f32 v[64:65], v[64:65], v[70:71], v[74:75]
	v_lshlrev_b32_e32 v70, 16, v81
	v_and_b32_e32 v71, 0xffff0000, v81
	v_pk_fma_f32 v[66:67], v[66:67], v[72:73], v[70:71]
	v_cvt_pk_bf16_f32 v70, v64, v65
	v_cvt_pk_bf16_f32 v71, v66, v67
	s_nop 0
	v_permlane16_swap_b32_e32 v68, v70
	v_permlane16_swap_b32_e32 v69, v71
	global_store_dwordx4 v[194:195], v[68:71], off
	v_add_u32_e32 v192, v168, v225
	v_lshlrev_b64 v[64:65], 1, v[192:193]
	v_add_u32_e32 v192, v169, v225
	v_lshl_add_u64 v[66:67], s[2:3], 0, v[64:65]
	v_lshl_add_u64 v[134:135], s[84:85], 0, v[64:65]
	v_lshlrev_b64 v[64:65], 1, v[192:193]
	v_add_u32_e32 v192, v170, v225
	global_load_dwordx4 v[92:95], v[66:67], off
	global_load_dwordx4 v[88:91], v[134:135], off
	v_lshl_add_u64 v[66:67], s[2:3], 0, v[64:65]
	v_lshl_add_u64 v[132:133], s[84:85], 0, v[64:65]
	v_lshlrev_b64 v[64:65], 1, v[192:193]
	v_add_u32_e32 v192, v171, v225
	global_load_dwordx4 v[84:87], v[66:67], off
	global_load_dwordx4 v[80:83], v[132:133], off
	v_lshl_add_u64 v[66:67], s[2:3], 0, v[64:65]
	v_lshl_add_u64 v[130:131], s[84:85], 0, v[64:65]
	v_lshlrev_b64 v[64:65], 1, v[192:193]
	global_load_dwordx4 v[76:79], v[66:67], off
	global_load_dwordx4 v[72:75], v[130:131], off
	v_lshl_add_u64 v[66:67], s[2:3], 0, v[64:65]
	v_lshl_add_u64 v[128:129], s[84:85], 0, v[64:65]
	global_load_dwordx4 v[68:71], v[66:67], off
	s_nop 0
	global_load_dwordx4 v[64:67], v[128:129], off
	v_mov_b32_e32 v136, v126
	v_mov_b32_e32 v137, v127
	v_mov_b32_e32 v138, v122
	v_mov_b32_e32 v139, v123
	v_permlane16_swap_b32_e32 v124, v136
	v_permlane16_swap_b32_e32 v125, v137
	v_permlane16_swap_b32_e32 v120, v138
	v_permlane16_swap_b32_e32 v121, v139
	v_lshlrev_b32_e32 v122, 16, v124
	v_and_b32_e32 v123, 0xffff0000, v124
	v_lshlrev_b32_e32 v124, 16, v125
	v_and_b32_e32 v125, 0xffff0000, v125
	v_lshlrev_b32_e32 v126, 16, v120
	v_and_b32_e32 v127, 0xffff0000, v120
	v_lshlrev_b32_e32 v120, 16, v121
	v_and_b32_e32 v121, 0xffff0000, v121
	v_pk_fma_f32 v[60:61], v[60:61], v[122:123], v[126:127]
	v_pk_fma_f32 v[62:63], v[62:63], v[124:125], v[120:121]
	v_cvt_pk_bf16_f32 v60, v60, v61
	v_cvt_pk_bf16_f32 v61, v62, v63
	v_lshlrev_b32_e32 v62, 16, v136
	v_and_b32_e32 v63, 0xffff0000, v136
	v_lshlrev_b32_e32 v122, 16, v138
	v_and_b32_e32 v123, 0xffff0000, v138
	v_lshlrev_b32_e32 v120, 16, v137
	v_and_b32_e32 v121, 0xffff0000, v137
	v_pk_fma_f32 v[56:57], v[56:57], v[62:63], v[122:123]
	v_lshlrev_b32_e32 v62, 16, v139
	v_and_b32_e32 v63, 0xffff0000, v139
	v_pk_fma_f32 v[58:59], v[58:59], v[120:121], v[62:63]
	v_cvt_pk_bf16_f32 v62, v56, v57
	v_cvt_pk_bf16_f32 v63, v58, v59
	s_nop 0
	v_permlane16_swap_b32_e32 v60, v62
	v_permlane16_swap_b32_e32 v61, v63
	global_store_dwordx4 v[166:167], v[60:63], off
	v_permlane16_swap_b32_e32 v112, v114
	s_nop 0
	v_mov_b32_e32 v62, v118
	s_nop 1
	v_permlane16_swap_b32_e32 v116, v62
	v_mov_b32_e32 v63, v119
	s_nop 1
	v_permlane16_swap_b32_e32 v117, v63
	v_permlane16_swap_b32_e32 v113, v115
	v_lshlrev_b32_e32 v56, 16, v116
	v_and_b32_e32 v57, 0xffff0000, v116
	v_lshlrev_b32_e32 v60, 16, v112
	v_and_b32_e32 v61, 0xffff0000, v112
	v_lshlrev_b32_e32 v58, 16, v117
	v_and_b32_e32 v59, 0xffff0000, v117
	v_pk_fma_f32 v[52:53], v[52:53], v[56:57], v[60:61]
	v_lshlrev_b32_e32 v56, 16, v113
	v_and_b32_e32 v57, 0xffff0000, v113
	v_pk_fma_f32 v[54:55], v[54:55], v[58:59], v[56:57]
	v_cvt_pk_bf16_f32 v52, v52, v53
	v_cvt_pk_bf16_f32 v53, v54, v55
	v_lshlrev_b32_e32 v54, 16, v62
	v_and_b32_e32 v55, 0xffff0000, v62
	v_lshlrev_b32_e32 v58, 16, v114
	v_and_b32_e32 v59, 0xffff0000, v114
	v_lshlrev_b32_e32 v56, 16, v63
	v_and_b32_e32 v57, 0xffff0000, v63
	v_pk_fma_f32 v[48:49], v[48:49], v[54:55], v[58:59]
	v_lshlrev_b32_e32 v54, 16, v115
	v_and_b32_e32 v55, 0xffff0000, v115
	v_pk_fma_f32 v[50:51], v[50:51], v[56:57], v[54:55]
	v_cvt_pk_bf16_f32 v54, v48, v49
	v_cvt_pk_bf16_f32 v55, v50, v51
	s_nop 0
	v_permlane16_swap_b32_e32 v52, v54
	v_permlane16_swap_b32_e32 v53, v55
	global_store_dwordx4 v[164:165], v[52:55], off
	v_mov_b32_e32 v56, v106
	s_nop 1
	v_permlane16_swap_b32_e32 v104, v56
	v_mov_b32_e32 v54, v110
	s_nop 1
	v_permlane16_swap_b32_e32 v108, v54
	v_mov_b32_e32 v55, v111
	v_mov_b32_e32 v57, v107
	s_nop 0
	v_permlane16_swap_b32_e32 v109, v55
	v_permlane16_swap_b32_e32 v105, v57
	v_lshlrev_b32_e32 v48, 16, v108
	v_and_b32_e32 v49, 0xffff0000, v108
	v_lshlrev_b32_e32 v52, 16, v104
	v_and_b32_e32 v53, 0xffff0000, v104
	v_lshlrev_b32_e32 v50, 16, v109
	v_and_b32_e32 v51, 0xffff0000, v109
	v_pk_fma_f32 v[44:45], v[44:45], v[48:49], v[52:53]
	v_lshlrev_b32_e32 v48, 16, v105
	v_and_b32_e32 v49, 0xffff0000, v105
	v_pk_fma_f32 v[46:47], v[46:47], v[50:51], v[48:49]
	v_cvt_pk_bf16_f32 v44, v44, v45
	v_cvt_pk_bf16_f32 v45, v46, v47
	v_lshlrev_b32_e32 v46, 16, v54
	v_and_b32_e32 v47, 0xffff0000, v54
	v_lshlrev_b32_e32 v50, 16, v56
	v_and_b32_e32 v51, 0xffff0000, v56
	v_lshlrev_b32_e32 v48, 16, v55
	v_and_b32_e32 v49, 0xffff0000, v55
	v_pk_fma_f32 v[40:41], v[40:41], v[46:47], v[50:51]
	v_lshlrev_b32_e32 v46, 16, v57
	v_and_b32_e32 v47, 0xffff0000, v57
	v_pk_fma_f32 v[42:43], v[42:43], v[48:49], v[46:47]
	v_cvt_pk_bf16_f32 v46, v40, v41
	v_cvt_pk_bf16_f32 v47, v42, v43
	s_nop 0
	v_permlane16_swap_b32_e32 v44, v46
	v_permlane16_swap_b32_e32 v45, v47
	global_store_dwordx4 v[162:163], v[44:47], off
	v_mov_b32_e32 v48, v98
	s_nop 1
	v_permlane16_swap_b32_e32 v96, v48
	v_mov_b32_e32 v46, v102
	s_nop 1
	v_permlane16_swap_b32_e32 v100, v46
	v_mov_b32_e32 v47, v103
	v_mov_b32_e32 v49, v99
	s_nop 0
	v_permlane16_swap_b32_e32 v101, v47
	v_permlane16_swap_b32_e32 v97, v49
	v_lshlrev_b32_e32 v40, 16, v100
	v_and_b32_e32 v41, 0xffff0000, v100
	v_lshlrev_b32_e32 v44, 16, v96
	v_and_b32_e32 v45, 0xffff0000, v96
	v_lshlrev_b32_e32 v42, 16, v101
	v_and_b32_e32 v43, 0xffff0000, v101
	v_pk_fma_f32 v[36:37], v[36:37], v[40:41], v[44:45]
	v_lshlrev_b32_e32 v40, 16, v97
	v_and_b32_e32 v41, 0xffff0000, v97
	v_pk_fma_f32 v[38:39], v[38:39], v[42:43], v[40:41]
	v_cvt_pk_bf16_f32 v36, v36, v37
	v_cvt_pk_bf16_f32 v37, v38, v39
	v_lshlrev_b32_e32 v38, 16, v46
	v_and_b32_e32 v39, 0xffff0000, v46
	v_lshlrev_b32_e32 v42, 16, v48
	v_and_b32_e32 v43, 0xffff0000, v48
	v_lshlrev_b32_e32 v40, 16, v47
	v_and_b32_e32 v41, 0xffff0000, v47
	v_pk_fma_f32 v[32:33], v[32:33], v[38:39], v[42:43]
	v_lshlrev_b32_e32 v38, 16, v49
	v_and_b32_e32 v39, 0xffff0000, v49
	v_pk_fma_f32 v[34:35], v[34:35], v[40:41], v[38:39]
	v_cvt_pk_bf16_f32 v38, v32, v33
	v_cvt_pk_bf16_f32 v39, v34, v35
	s_nop 0
	v_permlane16_swap_b32_e32 v36, v38
	v_permlane16_swap_b32_e32 v37, v39
	global_store_dwordx4 v[160:161], v[36:39], off
	s_waitcnt vmcnt(0)
	s_nop 0
	v_mov_b32_e32 v38, v94
	v_mov_b32_e32 v40, v90
	s_nop 0
	v_permlane16_swap_b32_e32 v92, v38
	v_mov_b32_e32 v39, v95
	v_permlane16_swap_b32_e32 v88, v40
	v_mov_b32_e32 v41, v91
	v_permlane16_swap_b32_e32 v93, v39
	s_nop 0
	v_permlane16_swap_b32_e32 v89, v41
	v_lshlrev_b32_e32 v32, 16, v92
	v_and_b32_e32 v33, 0xffff0000, v92
	v_lshlrev_b32_e32 v36, 16, v88
	v_and_b32_e32 v37, 0xffff0000, v88
	v_lshlrev_b32_e32 v34, 16, v93
	v_and_b32_e32 v35, 0xffff0000, v93
	v_pk_fma_f32 v[28:29], v[28:29], v[32:33], v[36:37]
	v_lshlrev_b32_e32 v32, 16, v89
	v_and_b32_e32 v33, 0xffff0000, v89
	v_pk_fma_f32 v[30:31], v[30:31], v[34:35], v[32:33]
	v_cvt_pk_bf16_f32 v28, v28, v29
	v_cvt_pk_bf16_f32 v29, v30, v31
	v_lshlrev_b32_e32 v30, 16, v38
	v_and_b32_e32 v31, 0xffff0000, v38
	v_lshlrev_b32_e32 v34, 16, v40
	v_and_b32_e32 v35, 0xffff0000, v40
	v_lshlrev_b32_e32 v32, 16, v39
	v_and_b32_e32 v33, 0xffff0000, v39
	v_pk_fma_f32 v[24:25], v[24:25], v[30:31], v[34:35]
	v_lshlrev_b32_e32 v30, 16, v41
	v_and_b32_e32 v31, 0xffff0000, v41
	v_pk_fma_f32 v[26:27], v[26:27], v[32:33], v[30:31]
	v_cvt_pk_bf16_f32 v30, v24, v25
	v_cvt_pk_bf16_f32 v31, v26, v27
	s_nop 0
	v_permlane16_swap_b32_e32 v28, v30
	v_permlane16_swap_b32_e32 v29, v31
	global_store_dwordx4 v[134:135], v[28:31], off
	v_mov_b32_e32 v32, v82
	s_nop 1
	v_permlane16_swap_b32_e32 v80, v32
	v_mov_b32_e32 v30, v86
	s_nop 1
	v_permlane16_swap_b32_e32 v84, v30
	v_mov_b32_e32 v31, v87
	v_mov_b32_e32 v33, v83
	s_nop 0
	v_permlane16_swap_b32_e32 v85, v31
	v_permlane16_swap_b32_e32 v81, v33
	v_lshlrev_b32_e32 v24, 16, v84
	v_and_b32_e32 v25, 0xffff0000, v84
	v_lshlrev_b32_e32 v28, 16, v80
	v_and_b32_e32 v29, 0xffff0000, v80
	v_lshlrev_b32_e32 v26, 16, v85
	v_and_b32_e32 v27, 0xffff0000, v85
	v_pk_fma_f32 v[20:21], v[20:21], v[24:25], v[28:29]
	v_lshlrev_b32_e32 v24, 16, v81
	v_and_b32_e32 v25, 0xffff0000, v81
	v_pk_fma_f32 v[22:23], v[22:23], v[26:27], v[24:25]
	v_cvt_pk_bf16_f32 v20, v20, v21
	v_cvt_pk_bf16_f32 v21, v22, v23
	v_lshlrev_b32_e32 v22, 16, v30
	v_and_b32_e32 v23, 0xffff0000, v30
	v_lshlrev_b32_e32 v26, 16, v32
	v_and_b32_e32 v27, 0xffff0000, v32
	v_lshlrev_b32_e32 v24, 16, v31
	v_and_b32_e32 v25, 0xffff0000, v31
	v_pk_fma_f32 v[16:17], v[16:17], v[22:23], v[26:27]
	v_lshlrev_b32_e32 v22, 16, v33
	v_and_b32_e32 v23, 0xffff0000, v33
	v_pk_fma_f32 v[18:19], v[18:19], v[24:25], v[22:23]
	v_cvt_pk_bf16_f32 v22, v16, v17
	v_cvt_pk_bf16_f32 v23, v18, v19
	s_nop 0
	v_permlane16_swap_b32_e32 v20, v22
	v_permlane16_swap_b32_e32 v21, v23
	global_store_dwordx4 v[132:133], v[20:23], off
	v_mov_b32_e32 v24, v74
	s_nop 1
	v_permlane16_swap_b32_e32 v72, v24
	v_mov_b32_e32 v22, v78
	s_nop 1
	v_permlane16_swap_b32_e32 v76, v22
	v_mov_b32_e32 v23, v79
	v_mov_b32_e32 v25, v75
	s_nop 0
	v_permlane16_swap_b32_e32 v77, v23
	v_permlane16_swap_b32_e32 v73, v25
	v_lshlrev_b32_e32 v16, 16, v76
	v_and_b32_e32 v17, 0xffff0000, v76
	v_lshlrev_b32_e32 v20, 16, v72
	v_and_b32_e32 v21, 0xffff0000, v72
	v_lshlrev_b32_e32 v18, 16, v77
	v_and_b32_e32 v19, 0xffff0000, v77
	v_pk_fma_f32 v[12:13], v[12:13], v[16:17], v[20:21]
	v_lshlrev_b32_e32 v16, 16, v73
	v_and_b32_e32 v17, 0xffff0000, v73
	v_pk_fma_f32 v[14:15], v[14:15], v[18:19], v[16:17]
	v_cvt_pk_bf16_f32 v12, v12, v13
	v_cvt_pk_bf16_f32 v13, v14, v15
	v_lshlrev_b32_e32 v14, 16, v22
	v_and_b32_e32 v15, 0xffff0000, v22
	v_lshlrev_b32_e32 v18, 16, v24
	v_and_b32_e32 v19, 0xffff0000, v24
	v_lshlrev_b32_e32 v16, 16, v23
	v_and_b32_e32 v17, 0xffff0000, v23
	v_pk_fma_f32 v[8:9], v[8:9], v[14:15], v[18:19]
	v_lshlrev_b32_e32 v14, 16, v25
	v_and_b32_e32 v15, 0xffff0000, v25
	v_pk_fma_f32 v[10:11], v[10:11], v[16:17], v[14:15]
	v_cvt_pk_bf16_f32 v14, v8, v9
	v_cvt_pk_bf16_f32 v15, v10, v11
	s_nop 0
	v_permlane16_swap_b32_e32 v12, v14
	v_permlane16_swap_b32_e32 v13, v15
	global_store_dwordx4 v[130:131], v[12:15], off
	v_mov_b32_e32 v16, v66
	s_nop 1
	v_permlane16_swap_b32_e32 v64, v16
	v_mov_b32_e32 v14, v70
	s_nop 1
	v_permlane16_swap_b32_e32 v68, v14
	v_mov_b32_e32 v15, v71
	v_mov_b32_e32 v17, v67
	s_nop 0
	v_permlane16_swap_b32_e32 v69, v15
	v_permlane16_swap_b32_e32 v65, v17
	v_lshlrev_b32_e32 v8, 16, v68
	v_and_b32_e32 v9, 0xffff0000, v68
	v_lshlrev_b32_e32 v12, 16, v64
	v_and_b32_e32 v13, 0xffff0000, v64
	v_lshlrev_b32_e32 v10, 16, v69
	v_and_b32_e32 v11, 0xffff0000, v69
	v_pk_fma_f32 v[4:5], v[4:5], v[8:9], v[12:13]
	v_lshlrev_b32_e32 v8, 16, v65
	v_and_b32_e32 v9, 0xffff0000, v65
	v_pk_fma_f32 v[6:7], v[6:7], v[10:11], v[8:9]
	v_cvt_pk_bf16_f32 v4, v4, v5
	v_cvt_pk_bf16_f32 v5, v6, v7
	v_lshlrev_b32_e32 v6, 16, v14
	v_and_b32_e32 v7, 0xffff0000, v14
	v_lshlrev_b32_e32 v10, 16, v16
	v_and_b32_e32 v11, 0xffff0000, v16
	v_lshlrev_b32_e32 v8, 16, v15
	v_and_b32_e32 v9, 0xffff0000, v15
	v_pk_fma_f32 v[0:1], v[0:1], v[6:7], v[10:11]
	v_lshlrev_b32_e32 v6, 16, v17
	v_and_b32_e32 v7, 0xffff0000, v17
	v_pk_fma_f32 v[2:3], v[2:3], v[8:9], v[6:7]
	v_cvt_pk_bf16_f32 v6, v0, v1
	v_cvt_pk_bf16_f32 v7, v2, v3
	s_nop 0
	v_permlane16_swap_b32_e32 v4, v6
	v_permlane16_swap_b32_e32 v5, v7
	global_store_dwordx4 v[128:129], v[4:7], off
	s_nop 1
	v_readlane_b32 s2, v252, 4
	s_andn2_b64 vcc, exec, s[0:1]
	v_readlane_b32 s0, v252, 16
	s_add_i32 s7, s7, s2
	s_add_i32 s6, s6, s0
	s_cbranch_vccz .LBB0_581

; #define WAIT_V(n) asm volatile("s_waitcnt vmcnt(" #n ")" ::: "memory")
; #define BAR __builtin_amdgcn_s_barrier()
; template <bool SWAP>
; __device__ __forceinline__ void gemm_main(const u16* __restrict__ A, const u16* __restrict__ Bt, int brow, int bcol,
;                                           u16* shm, f32x4 (&acc)[2][2][4][2]) {
;     ...
;   int tx = threadIdx.x; asm volatile("" : "+v"(tx));
;   const int wid = tx >> 6, lane = tx & 63, wr = wid >> 2, wc = wid & 3, fr = lane & 15, fq = lane >> 4;
; #pragma unroll
;   for (int a = 0; a < 2; ++a)
; #pragma unroll
;     for (int b = 0; b < 2; ++b)
; #pragma unroll
;       for (int m = 0; m < 4; ++m)
; #pragma unroll
;         for (int n = 0; n < 2; ++n) acc[a][b][m][n] = f32x4{0.f, 0.f, 0.f, 0.f};
;   bf16x8 At[4][2], B0[2][2], B1[2][2];
;   constexpr int nt = GK / BK;
;   GEMM_VOFF
;   const int lpart = (fr * 64 + fq * 16) ^ ((fr >> 3) << 5);
;   const int abase = wr * 8192 + lpart; int bbase = 65536 + wc * 4096 + lpart;
;   asm volatile("" : "+v"(bbase));
;   if (wr == 1) BAR;
;   WAIT_V(0); BAR;
;   BAR;
.LBB0_563:
	s_or_b64 exec, exec, s[0:1]
	v_bfe_i32 v4, v136, 27, 1
	v_lshlrev_b32_e32 v141, 4, v136
	v_lshrrev_b32_e32 v4, 22, v4
	v_add_u32_e32 v4, v141, v4
	v_and_b32_e32 v4, 0xfffffc00, v4
	v_sub_u32_e32 v4, v141, v4
	v_lshrrev_b32_e32 v5, 4, v4
	v_bitop3_b32 v4, v5, v4, 32 bitop3:0x6c
	v_ashrrev_i32_e32 v5, 31, v4
	v_lshrrev_b32_e32 v5, 26, v5
	v_add_u32_e32 v5, v4, v5
	v_ashrrev_i32_e32 v140, 6, v5
	v_and_b32_e32 v5, 0xc0, v5
	v_sub_u32_e32 v4, v4, v5
	v_ashrrev_i16_sdwa v4, v215, sext(v4) dst_sel:DWORD dst_unused:UNUSED_PAD src0_sel:DWORD src1_sel:BYTE_0
	v_bfe_i32 v142, v4, 0, 16
	v_add_u32_e32 v4, 0x2000, v141
	v_ashrrev_i32_e32 v5, 31, v4
	v_lshrrev_b32_e32 v5, 22, v5
	v_add_u32_e32 v5, v4, v5
	v_ashrrev_i32_e32 v143, 10, v5
	v_mul_i32_i24_e32 v5, 0x400, v143
	v_sub_u32_e32 v4, v4, v5
	v_lshrrev_b32_e32 v5, 4, v4
	v_bitop3_b32 v4, v5, v4, 32 bitop3:0x6c
	v_ashrrev_i32_e32 v5, 31, v4
	v_lshrrev_b32_e32 v5, 26, v5
	v_ashrrev_i32_e32 v3, 31, v136
	v_add_u32_e32 v5, v4, v5
	v_lshrrev_b32_e32 v3, 26, v3
	v_ashrrev_i32_e32 v144, 6, v5
	v_and_b32_e32 v5, 0xc0, v5
	v_add_u32_e32 v3, v136, v3
	v_sub_u32_e32 v4, v4, v5
	v_ashrrev_i32_e32 v139, 6, v3
	v_ashrrev_i16_sdwa v4, v215, sext(v4) dst_sel:DWORD dst_unused:UNUSED_PAD src0_sel:DWORD src1_sel:BYTE_0
	v_bfe_i32 v145, v4, 0, 16
	v_lshlrev_b32_e32 v4, 13, v0
	v_lshlrev_b32_e32 v0, 15, v139
	v_and_b32_e32 v0, 0xffff0000, v0
	v_readlane_b32 s2, v253, 59
	v_lshl_add_u32 v0, v140, 12, v0
	s_lshl_b32 s0, s7, 12
	s_ashr_i32 s2, s54, 3
	v_and_or_b32 v0, v3, 64, v0
	s_and_b32 s4, s0, 0x700000
	s_and_b32 s0, s6, 31
	v_lshl_add_u32 v192, v142, 1, v0
	v_lshlrev_b32_e32 v0, 15, v143
	s_lshl_b32 s1, s2, 8
	s_lshl_b32 s0, s0, 8
	v_and_b32_e32 v0, 0xffff0000, v0
	s_and_b32 s1, s1, 0xffffe000
	v_readlane_b32 s3, v253, 60
	v_add_u32_e32 v5, 0, v2
	v_lshl_add_u32 v0, v144, 12, v0
	v_lshlrev_b32_e32 v2, 6, v143
	s_or_b32 s0, s1, s0
	s_mov_b32 s5, s3
	v_and_or_b32 v0, v2, 64, v0
	s_ashr_i32 s1, s0, 31
	v_lshl_add_u64 v[128:129], s[4:5], 0, v[192:193]
	v_lshl_add_u32 v2, v145, 1, v0
	v_mov_b32_e32 v3, v193
	v_writelane_b32 v253, s4, 59
	s_lshl_b64 s[10:11], s[0:1], 12
	v_mov_b32_e32 v0, 0
	v_writelane_b32 v253, s5, 60
	v_lshl_add_u64 v[130:131], s[4:5], 0, v[2:3]
	v_lshl_add_u64 v[132:133], s[10:11], 0, v[192:193]
	v_lshl_add_u64 v[134:135], s[10:11], 0, v[2:3]
	s_mov_b32 s3, -2
	v_add_u32_e32 v138, 0, v1
	v_add_u32_e32 v137, v5, v4
	s_mov_b64 s[0:1], s[50:51]
	v_mov_b32_e32 v1, v0
	v_mov_b32_e32 v2, v0
	v_mov_b32_e32 v3, v0
	v_mov_b32_e32 v4, v0
	v_mov_b32_e32 v5, v0
	v_mov_b32_e32 v6, v0
	v_mov_b32_e32 v7, v0
	v_mov_b32_e32 v8, v0
	v_mov_b32_e32 v9, v0
	v_mov_b32_e32 v10, v0
	v_mov_b32_e32 v11, v0
	v_mov_b32_e32 v12, v0
	v_mov_b32_e32 v13, v0
	v_mov_b32_e32 v14, v0
	v_mov_b32_e32 v15, v0
	v_mov_b32_e32 v16, v0
	v_mov_b32_e32 v17, v0
	v_mov_b32_e32 v18, v0
	v_mov_b32_e32 v19, v0
	v_mov_b32_e32 v20, v0
	v_mov_b32_e32 v21, v0
	v_mov_b32_e32 v22, v0
	v_mov_b32_e32 v23, v0
	v_mov_b32_e32 v24, v0
	v_mov_b32_e32 v25, v0
	v_mov_b32_e32 v26, v0
	v_mov_b32_e32 v27, v0
	v_mov_b32_e32 v28, v0
	v_mov_b32_e32 v29, v0
	v_mov_b32_e32 v30, v0
	v_mov_b32_e32 v31, v0
	v_mov_b32_e32 v32, v0
	v_mov_b32_e32 v33, v0
	v_mov_b32_e32 v34, v0
	v_mov_b32_e32 v35, v0
	v_mov_b32_e32 v36, v0
	v_mov_b32_e32 v37, v0
	v_mov_b32_e32 v38, v0
	v_mov_b32_e32 v39, v0
	v_mov_b32_e32 v40, v0
	v_mov_b32_e32 v41, v0
	v_mov_b32_e32 v42, v0
	v_mov_b32_e32 v43, v0
	v_mov_b32_e32 v44, v0
	v_mov_b32_e32 v45, v0
	v_mov_b32_e32 v46, v0
	v_mov_b32_e32 v47, v0
	v_mov_b32_e32 v48, v0
	v_mov_b32_e32 v49, v0
	v_mov_b32_e32 v50, v0
	v_mov_b32_e32 v51, v0
	v_mov_b32_e32 v52, v0
	v_mov_b32_e32 v53, v0
	v_mov_b32_e32 v54, v0
	v_mov_b32_e32 v55, v0
	v_mov_b32_e32 v56, v0
	v_mov_b32_e32 v57, v0
	v_mov_b32_e32 v58, v0
	v_mov_b32_e32 v59, v0
	v_mov_b32_e32 v60, v0
	v_mov_b32_e32 v61, v0
	v_mov_b32_e32 v62, v0
	v_mov_b32_e32 v63, v0
	v_mov_b32_e32 v64, v0
	v_mov_b32_e32 v65, v0
	v_mov_b32_e32 v66, v0
	v_mov_b32_e32 v67, v0
	v_mov_b32_e32 v68, v0
	v_mov_b32_e32 v69, v0
	v_mov_b32_e32 v70, v0
	v_mov_b32_e32 v71, v0
	v_mov_b32_e32 v72, v0
	v_mov_b32_e32 v73, v0
	v_mov_b32_e32 v74, v0
	v_mov_b32_e32 v75, v0
	v_mov_b32_e32 v76, v0
	v_mov_b32_e32 v77, v0
	v_mov_b32_e32 v78, v0
	v_mov_b32_e32 v79, v0
	v_mov_b32_e32 v80, v0
	v_mov_b32_e32 v81, v0
	v_mov_b32_e32 v82, v0
	v_mov_b32_e32 v83, v0
	v_mov_b32_e32 v84, v0
	v_mov_b32_e32 v85, v0
	v_mov_b32_e32 v86, v0
	v_mov_b32_e32 v87, v0
	v_mov_b32_e32 v88, v0
	v_mov_b32_e32 v89, v0
	v_mov_b32_e32 v90, v0
	v_mov_b32_e32 v91, v0
	v_mov_b32_e32 v92, v0
	v_mov_b32_e32 v93, v0
	v_mov_b32_e32 v94, v0
	v_mov_b32_e32 v95, v0
	v_mov_b32_e32 v96, v0
	v_mov_b32_e32 v97, v0
	v_mov_b32_e32 v98, v0
	v_mov_b32_e32 v99, v0
	v_mov_b32_e32 v100, v0
	v_mov_b32_e32 v101, v0
	v_mov_b32_e32 v102, v0
	v_mov_b32_e32 v103, v0
	v_mov_b32_e32 v104, v0
	v_mov_b32_e32 v105, v0
	v_mov_b32_e32 v106, v0
	v_mov_b32_e32 v107, v0
	v_mov_b32_e32 v108, v0
	v_mov_b32_e32 v109, v0
	v_mov_b32_e32 v110, v0
	v_mov_b32_e32 v111, v0
	v_mov_b32_e32 v112, v0
	v_mov_b32_e32 v113, v0
	v_mov_b32_e32 v114, v0
	v_mov_b32_e32 v115, v0
	v_mov_b32_e32 v116, v0
	v_mov_b32_e32 v117, v0
	v_mov_b32_e32 v118, v0
	v_mov_b32_e32 v119, v0
	v_mov_b32_e32 v120, v0
	v_mov_b32_e32 v121, v0
	v_mov_b32_e32 v122, v0
	v_mov_b32_e32 v123, v0
	v_mov_b32_e32 v124, v0
	v_mov_b32_e32 v125, v0
	v_mov_b32_e32 v126, v0
	v_mov_b32_e32 v127, v0
	s_mov_b64 s[8:9], 0x17580080
	s_mov_b64 s[12:13], 0x8100100
	s_mov_b64 s[14:15], 0x17500100
	s_mov_b64 s[16:17], 0x8180100
	s_mov_b64 s[18:19], 0x17580100
	s_mov_b64 s[24:25], 0x8100180
	s_mov_b64 vcc, 0x17500180
	s_mov_b64 s[42:43], 0x8180180
	v_readfirstlane_b32 s4, v141
	s_waitcnt vmcnt(0)
	s_barrier
	s_barrier

; #define STAGE(P, BASE, br, kt) do { const char* _g = (const char*)((BASE) + (size_t)(br) * GK + (kt) * BK); \
;     __builtin_amdgcn_global_load_lds((const unsigned*)(_g + voff0), (unsigned*)((char*)(P) + tx * 16), 16, 0, 0); \
;     __builtin_amdgcn_global_load_lds((const unsigned*)(_g + voff1), (unsigned*)((char*)(P) + tx * 16 + 8192), 16, 0, 0); } while (0)
; __device__ __forceinline__ void gemm_issue(const u16* __restrict__ A, const u16* __restrict__ Bt, int brow, int bcol, u16* shm) {
;   int tx = threadIdx.x; asm volatile("" : "+v"(tx));
;   GEMM_VOFF
;   STAGE(SB(0, 0), Bt, bcol, 0); STAGE(SA(0, 0), A, brow, 0);
;   STAGE(SB(0, 1), Bt, bcol + HALF, 0); STAGE(SA(0, 1), A, brow + HALF, 0);
;   STAGE(SB(1, 0), Bt, bcol, 1); STAGE(SA(1, 0), A, brow, 1); STAGE(SB(1, 1), Bt, bcol + HALF, 1);
; }
.LBB0_567:
	s_or_b64 exec, exec, s[0:1]
	v_mov_b32_e32 v120, v210
	s_lshl_b32 s0, s54, 3
	v_ashrrev_i32_e32 v121, 31, v120
	v_lshrrev_b32_e32 v121, 26, v121
	v_lshlrev_b32_e32 v142, 4, v120
	v_add_u32_e32 v121, v120, v121
	v_bfe_i32 v120, v120, 27, 1
	v_lshrrev_b32_e32 v120, 22, v120
	v_add_u32_e32 v120, v142, v120
	v_and_b32_e32 v120, 0xfffffc00, v120
	v_sub_u32_e32 v120, v142, v120
	v_lshrrev_b32_e32 v122, 4, v120
	v_bitop3_b32 v120, v122, v120, 32 bitop3:0x6c
	v_ashrrev_i32_e32 v123, 31, v120
	v_lshrrev_b32_e32 v123, 26, v123
	v_add_u32_e32 v123, v120, v123
	v_ashrrev_i32_e32 v121, 6, v121
	v_lshrrev_b32_e32 v132, 6, v123
	v_and_b32_e32 v123, 0xc0, v123
	v_lshlrev_b32_e32 v122, 3, v121
	v_lshlrev_b32_e32 v121, 5, v121
	v_sub_u32_e32 v120, v120, v123
	v_and_b32_e32 v122, 0xffff0, v122
	v_and_b32_e32 v121, 32, v121
	v_ashrrev_i16_sdwa v120, v215, sext(v120) dst_sel:DWORD dst_unused:UNUSED_PAD src0_sel:DWORD src1_sel:BYTE_0
	v_add_u32_sdwa v120, v121, sext(v120) dst_sel:DWORD dst_unused:UNUSED_PAD src0_sel:DWORD src1_sel:WORD_0
	v_add_lshl_u32 v121, v132, v122, 12
	v_lshl_add_u32 v192, v120, 1, v121
	v_add_u32_e32 v120, 0x2000, v142
	v_ashrrev_i32_e32 v121, 31, v120
	v_lshrrev_b32_e32 v121, 22, v121
	v_add_u32_e32 v121, v120, v121
	v_ashrrev_i32_e32 v121, 10, v121
	v_mul_i32_i24_e32 v122, 0x400, v121
	v_sub_u32_e32 v120, v120, v122
	v_lshrrev_b32_e32 v122, 4, v120
	v_bitop3_b32 v120, v122, v120, 32 bitop3:0x6c
	v_ashrrev_i32_e32 v123, 31, v120
	v_lshrrev_b32_e32 v123, 26, v123
	s_and_b32 s55, s0, 0x700
	v_add_u32_e32 v123, v120, v123
	s_lshl_b32 s2, s55, 12
	s_ashr_i32 s9, s8, 31
	v_lshrrev_b32_e32 v132, 6, v123
	v_and_b32_e32 v123, 0xc0, v123
	s_lshl_b64 s[0:1], s[8:9], 12
	s_or_b32 s9, s2, 0x80000
	v_lshlrev_b32_e32 v122, 3, v121
	v_lshlrev_b32_e32 v121, 5, v121
	v_sub_u32_e32 v120, v120, v123
	v_readlane_b32 s14, v251, 48
	v_add_u32_e32 v134, s28, v142
	v_and_b32_e32 v122, 0xffff0, v122
	v_and_b32_e32 v121, 32, v121
	v_ashrrev_i16_sdwa v120, v215, sext(v120) dst_sel:DWORD dst_unused:UNUSED_PAD src0_sel:DWORD src1_sel:BYTE_0
	s_add_u32 s4, s14, s2
	v_readlane_b32 s15, v251, 49
	v_readfirstlane_b32 s3, v134
	v_add_u32_e32 v134, 0x2000, v134
	v_add_u32_sdwa v120, v121, sext(v120) dst_sel:DWORD dst_unused:UNUSED_PAD src0_sel:DWORD src1_sel:WORD_0
	v_add_lshl_u32 v121, v132, v122, 12
	s_addc_u32 s5, s15, 0
	s_mov_b32 m0, s3
	v_readfirstlane_b32 s3, v134
	v_lshl_add_u32 v120, v120, 1, v121
	global_load_lds_dwordx4 v192, s[4:5]
	v_mov_b32_e32 v121, v193
	s_mov_b32 m0, s3
	v_add_u32_e32 v143, 0, v142
	v_lshl_add_u64 v[122:123], s[4:5], 0, v[192:193]
	v_lshl_add_u64 v[132:133], s[4:5], 0, v[120:121]
	global_load_lds_dwordx4 v120, s[4:5]
	s_add_u32 s4, s90, s0
	v_readfirstlane_b32 s3, v143
	v_add_u32_e32 v138, 0x2000, v143
	s_addc_u32 s5, s91, s1
	s_mov_b32 m0, s3
	v_readfirstlane_b32 s3, v138
	global_load_lds_dwordx4 v192, s[4:5]
	s_mov_b32 m0, s3
	v_lshl_add_u64 v[134:135], s[4:5], 0, v[192:193]
	v_lshl_add_u64 v[136:137], s[4:5], 0, v[120:121]
	global_load_lds_dwordx4 v120, s[4:5]
	s_add_u32 s4, s14, s9
	s_addc_u32 s5, s15, 0
	v_add_u32_e32 v144, s29, v142
	v_lshl_add_u64 v[140:141], s[4:5], 0, v[120:121]
	v_readfirstlane_b32 s3, v144
	v_add_u32_e32 v121, 0x2000, v144
	s_mov_b32 m0, s3
	v_readfirstlane_b32 s3, v121
	global_load_lds_dwordx4 v192, s[4:5]
	s_mov_b32 m0, s3
	v_add_u32_e32 v121, 0x4000, v143
	v_lshl_add_u64 v[138:139], s[4:5], 0, v[192:193]
	global_load_lds_dwordx4 v120, s[4:5]
	s_add_u32 s4, s90, s12
	v_readfirstlane_b32 s3, v121
	v_add_u32_e32 v121, 0x6000, v143
	s_addc_u32 s5, s91, s13
	s_mov_b32 m0, s3
	v_readfirstlane_b32 s3, v121
	global_load_lds_dwordx4 v192, s[4:5]
	s_mov_b32 m0, s3
	s_mov_b64 s[14:15], 0x80
	global_load_lds_dwordx4 v120, s[4:5]
	v_lshl_add_u64 v[120:121], v[122:123], 0, s[14:15]
	v_add_u32_e32 v122, s30, v142
	s_nop 0
	v_readfirstlane_b32 s3, v122
	v_add_u32_e32 v122, 0x2000, v122
	s_mov_b32 m0, s3
	v_readfirstlane_b32 s3, v122
	v_add_u32_e32 v122, 0x8000, v143
	global_load_lds_dwordx4 v[120:121], off
	v_lshl_add_u64 v[120:121], v[132:133], 0, s[14:15]
	s_mov_b32 m0, s3
	v_readfirstlane_b32 s3, v122
	v_add_u32_e32 v122, 0xa000, v143
	global_load_lds_dwordx4 v[120:121], off
	v_lshl_add_u64 v[120:121], v[134:135], 0, s[14:15]
	s_mov_b32 m0, s3
	v_readfirstlane_b32 s3, v122
	v_add_u32_e32 v122, s31, v142
	global_load_lds_dwordx4 v[120:121], off
	v_lshl_add_u64 v[120:121], v[136:137], 0, s[14:15]
	s_mov_b32 m0, s3
	v_readfirstlane_b32 s3, v122
	v_add_u32_e32 v122, 0x2000, v122
	global_load_lds_dwordx4 v[120:121], off
	v_lshl_add_u64 v[120:121], v[138:139], 0, s[14:15]
	s_mov_b32 m0, s3
	v_readfirstlane_b32 s3, v122
	global_load_lds_dwordx4 v[120:121], off
	v_lshl_add_u64 v[120:121], v[140:141], 0, s[14:15]
	s_mov_b32 m0, s3
	v_readlane_b32 s14, v251, 15
	global_load_lds_dwordx4 v[120:121], off
	v_mov_b32_e32 v120, v223
	v_mov_b32_e32 v121, v224
	v_readlane_b32 s15, v251, 16
	v_add_u32_e32 v176, s55, v121
	v_add_lshl_u32 v177, v120, s8, 11
	v_add_u32_e32 v192, v177, v176
	v_lshlrev_b64 v[168:169], 1, v[192:193]
	v_lshl_add_u64 v[120:121], s[14:15], 0, v[168:169]
	global_load_dwordx4 v[148:151], v[120:121], off
	v_add_u32_e32 v122, 0x8000, v177
	v_add_u32_e32 v192, v122, v176
	v_lshlrev_b64 v[170:171], 1, v[192:193]
	v_lshl_add_u64 v[120:121], s[14:15], 0, v[170:171]
	global_load_dwordx4 v[152:155], v[120:121], off
	v_add_u32_e32 v132, 0x10000, v177
	v_add_u32_e32 v192, v132, v176
	v_lshlrev_b64 v[172:173], 1, v[192:193]
	v_lshl_add_u64 v[120:121], s[14:15], 0, v[172:173]
	global_load_dwordx4 v[156:159], v[120:121], off
	v_add_u32_e32 v133, 0x18000, v177
	v_add_u32_e32 v192, v133, v176
	v_lshlrev_b64 v[174:175], 1, v[192:193]
	v_lshl_add_u64 v[120:121], s[14:15], 0, v[174:175]
	global_load_dwordx4 v[160:163], v[120:121], off
	v_add_u32_e32 v178, 0x80, v176
	v_add_u32_e32 v192, v178, v177
	v_lshlrev_b64 v[146:147], 1, v[192:193]
	v_add_u32_e32 v192, v122, v178
	v_lshlrev_b64 v[144:145], 1, v[192:193]
	v_add_u32_e32 v192, v132, v178
	v_lshlrev_b64 v[142:143], 1, v[192:193]
	v_add_u32_e32 v192, v133, v178
	v_lshl_add_u64 v[120:121], s[14:15], 0, v[146:147]
	v_lshl_add_u64 v[122:123], s[14:15], 0, v[144:145]
	v_lshlrev_b64 v[140:141], 1, v[192:193]
	global_load_dwordx4 v[164:167], v[120:121], off
	global_load_dwordx4 v[136:139], v[122:123], off
	v_lshl_add_u64 v[120:121], s[14:15], 0, v[142:143]
	v_lshl_add_u64 v[122:123], s[14:15], 0, v[140:141]
	global_load_dwordx4 v[132:135], v[120:121], off
	s_nop 0
	global_load_dwordx4 v[120:123], v[122:123], off
	s_waitcnt vmcnt(0)
	v_mov_b32_e32 v179, v150
	v_mov_b32_e32 v180, v151
	s_nop 0
	v_permlane16_swap_b32_e32 v148, v179
	v_permlane16_swap_b32_e32 v149, v180
	v_lshlrev_b32_e32 v150, 16, v148
	v_and_b32_e32 v151, 0xffff0000, v148
	v_lshlrev_b32_e32 v148, 16, v149
	v_and_b32_e32 v149, 0xffff0000, v149
	v_pk_mul_f32 v[128:129], v[128:129], v[150:151]
	v_pk_mul_f32 v[130:131], v[130:131], v[148:149]
	v_cvt_pk_bf16_f32 v128, v128, v129
	v_cvt_pk_bf16_f32 v129, v130, v131
	v_lshlrev_b32_e32 v130, 16, v179
	v_and_b32_e32 v131, 0xffff0000, v179
	v_pk_mul_f32 v[124:125], v[124:125], v[130:131]
	v_lshlrev_b32_e32 v130, 16, v180
	v_and_b32_e32 v131, 0xffff0000, v180
	v_pk_mul_f32 v[126:127], v[126:127], v[130:131]
	v_cvt_pk_bf16_f32 v130, v124, v125
	v_cvt_pk_bf16_f32 v131, v126, v127
	v_mov_b32_e32 v126, v154
	v_permlane16_swap_b32_e32 v128, v130
	v_permlane16_swap_b32_e32 v129, v131
	v_lshl_add_u64 v[124:125], s[84:85], 0, v[168:169]
	v_permlane16_swap_b32_e32 v152, v126
	v_mov_b32_e32 v127, v155
	global_store_dwordx4 v[124:125], v[128:131], off
	s_nop 0
	v_permlane16_swap_b32_e32 v153, v127
	v_lshlrev_b32_e32 v124, 16, v152
	v_and_b32_e32 v125, 0xffff0000, v152
	v_pk_mul_f32 v[116:117], v[116:117], v[124:125]
	v_lshlrev_b32_e32 v124, 16, v153
	v_and_b32_e32 v125, 0xffff0000, v153
	v_pk_mul_f32 v[118:119], v[118:119], v[124:125]
	v_cvt_pk_bf16_f32 v116, v116, v117
	v_cvt_pk_bf16_f32 v117, v118, v119
	v_lshlrev_b32_e32 v118, 16, v126
	v_and_b32_e32 v119, 0xffff0000, v126
	v_pk_mul_f32 v[112:113], v[112:113], v[118:119]
	v_lshlrev_b32_e32 v118, 16, v127
	v_and_b32_e32 v119, 0xffff0000, v127
	v_pk_mul_f32 v[114:115], v[114:115], v[118:119]
	v_cvt_pk_bf16_f32 v118, v112, v113
	v_cvt_pk_bf16_f32 v119, v114, v115
	v_mov_b32_e32 v114, v158
	v_permlane16_swap_b32_e32 v116, v118
	v_permlane16_swap_b32_e32 v117, v119
	v_lshl_add_u64 v[112:113], s[84:85], 0, v[170:171]
	v_permlane16_swap_b32_e32 v156, v114
	v_mov_b32_e32 v115, v159
	global_store_dwordx4 v[112:113], v[116:119], off
	s_nop 0
	v_permlane16_swap_b32_e32 v157, v115
	v_lshlrev_b32_e32 v112, 16, v156
	v_and_b32_e32 v113, 0xffff0000, v156
	v_pk_mul_f32 v[108:109], v[108:109], v[112:113]
	v_lshlrev_b32_e32 v112, 16, v157
	v_and_b32_e32 v113, 0xffff0000, v157
	v_pk_mul_f32 v[110:111], v[110:111], v[112:113]
	v_cvt_pk_bf16_f32 v108, v108, v109
	v_cvt_pk_bf16_f32 v109, v110, v111
	v_lshlrev_b32_e32 v110, 16, v114
	v_and_b32_e32 v111, 0xffff0000, v114
	v_pk_mul_f32 v[104:105], v[104:105], v[110:111]
	v_lshlrev_b32_e32 v110, 16, v115
	v_and_b32_e32 v111, 0xffff0000, v115
	v_pk_mul_f32 v[106:107], v[106:107], v[110:111]
	v_cvt_pk_bf16_f32 v110, v104, v105
	v_cvt_pk_bf16_f32 v111, v106, v107
	v_mov_b32_e32 v106, v162
	v_permlane16_swap_b32_e32 v108, v110
	v_permlane16_swap_b32_e32 v109, v111
	v_lshl_add_u64 v[104:105], s[84:85], 0, v[172:173]
	v_permlane16_swap_b32_e32 v160, v106
	v_mov_b32_e32 v107, v163
	global_store_dwordx4 v[104:105], v[108:111], off
	s_nop 0
	v_permlane16_swap_b32_e32 v161, v107
	v_lshlrev_b32_e32 v104, 16, v160
	v_and_b32_e32 v105, 0xffff0000, v160
	v_pk_mul_f32 v[100:101], v[100:101], v[104:105]
	v_lshlrev_b32_e32 v104, 16, v161
	v_and_b32_e32 v105, 0xffff0000, v161
	v_pk_mul_f32 v[102:103], v[102:103], v[104:105]
	v_cvt_pk_bf16_f32 v100, v100, v101
	v_cvt_pk_bf16_f32 v101, v102, v103
	v_lshlrev_b32_e32 v102, 16, v106
	v_and_b32_e32 v103, 0xffff0000, v106
	v_pk_mul_f32 v[96:97], v[96:97], v[102:103]
	v_lshlrev_b32_e32 v102, 16, v107
	v_and_b32_e32 v103, 0xffff0000, v107
	v_pk_mul_f32 v[98:99], v[98:99], v[102:103]
	v_cvt_pk_bf16_f32 v102, v96, v97
	v_cvt_pk_bf16_f32 v103, v98, v99
	s_nop 0
	v_permlane16_swap_b32_e32 v100, v102
	v_permlane16_swap_b32_e32 v101, v103
	v_lshl_add_u64 v[96:97], s[84:85], 0, v[174:175]
	global_store_dwordx4 v[96:97], v[100:103], off
	v_add_u32_e32 v126, 0x40000, v177
	v_add_u32_e32 v192, v126, v176
	v_add_u32_e32 v127, 0x48000, v177
	v_lshlrev_b64 v[114:115], 1, v[192:193]
	v_add_u32_e32 v192, v127, v176
	v_add_u32_e32 v128, 0x50000, v177
	v_lshlrev_b64 v[112:113], 1, v[192:193]
	v_add_u32_e32 v192, v128, v176
	v_add_u32_e32 v129, 0x58000, v177
	v_lshlrev_b64 v[110:111], 1, v[192:193]
	v_add_u32_e32 v192, v129, v176
	v_lshl_add_u64 v[96:97], s[14:15], 0, v[114:115]
	v_lshl_add_u64 v[98:99], s[14:15], 0, v[112:113]
	v_lshlrev_b64 v[108:109], 1, v[192:193]
	global_load_dwordx4 v[116:119], v[96:97], off
	global_load_dwordx4 v[104:107], v[98:99], off
	v_lshl_add_u64 v[96:97], s[14:15], 0, v[110:111]
	v_lshl_add_u64 v[98:99], s[14:15], 0, v[108:109]
	global_load_dwordx4 v[100:103], v[96:97], off
	s_nop 0
	global_load_dwordx4 v[96:99], v[98:99], off
	v_mov_b32_e32 v130, v166
	s_nop 1
	v_permlane16_swap_b32_e32 v164, v130
	v_mov_b32_e32 v131, v167
	s_nop 1
	v_permlane16_swap_b32_e32 v165, v131
	v_lshlrev_b32_e32 v124, 16, v164
	v_and_b32_e32 v125, 0xffff0000, v164
	v_pk_mul_f32 v[92:93], v[92:93], v[124:125]
	v_lshlrev_b32_e32 v124, 16, v165
	v_and_b32_e32 v125, 0xffff0000, v165
	v_pk_mul_f32 v[94:95], v[94:95], v[124:125]
	v_cvt_pk_bf16_f32 v92, v92, v93
	v_cvt_pk_bf16_f32 v93, v94, v95
	v_lshlrev_b32_e32 v94, 16, v130
	v_and_b32_e32 v95, 0xffff0000, v130
	v_pk_mul_f32 v[88:89], v[88:89], v[94:95]
	v_lshlrev_b32_e32 v94, 16, v131
	v_and_b32_e32 v95, 0xffff0000, v131
	v_pk_mul_f32 v[90:91], v[90:91], v[94:95]
	v_cvt_pk_bf16_f32 v94, v88, v89
	v_cvt_pk_bf16_f32 v95, v90, v91
	v_mov_b32_e32 v90, v138
	v_permlane16_swap_b32_e32 v92, v94
	v_permlane16_swap_b32_e32 v93, v95
	v_lshl_add_u64 v[88:89], s[84:85], 0, v[146:147]
	v_permlane16_swap_b32_e32 v136, v90
	v_mov_b32_e32 v91, v139
	global_store_dwordx4 v[88:89], v[92:95], off
	s_nop 0
	v_permlane16_swap_b32_e32 v137, v91
	v_lshlrev_b32_e32 v88, 16, v136
	v_and_b32_e32 v89, 0xffff0000, v136
	v_pk_mul_f32 v[84:85], v[84:85], v[88:89]
	v_lshlrev_b32_e32 v88, 16, v137
	v_and_b32_e32 v89, 0xffff0000, v137
	v_pk_mul_f32 v[86:87], v[86:87], v[88:89]
	v_cvt_pk_bf16_f32 v84, v84, v85
	v_cvt_pk_bf16_f32 v85, v86, v87
	v_lshlrev_b32_e32 v86, 16, v90
	v_and_b32_e32 v87, 0xffff0000, v90
	v_pk_mul_f32 v[80:81], v[80:81], v[86:87]
	v_lshlrev_b32_e32 v86, 16, v91
	v_and_b32_e32 v87, 0xffff0000, v91
	v_pk_mul_f32 v[82:83], v[82:83], v[86:87]
	v_cvt_pk_bf16_f32 v86, v80, v81
	v_cvt_pk_bf16_f32 v87, v82, v83
	v_mov_b32_e32 v82, v134
	v_permlane16_swap_b32_e32 v84, v86
	v_permlane16_swap_b32_e32 v85, v87
	v_lshl_add_u64 v[80:81], s[84:85], 0, v[144:145]
	v_permlane16_swap_b32_e32 v132, v82
	v_mov_b32_e32 v83, v135
	global_store_dwordx4 v[80:81], v[84:87], off
	s_nop 0
	v_permlane16_swap_b32_e32 v133, v83
	v_lshlrev_b32_e32 v80, 16, v132
	v_and_b32_e32 v81, 0xffff0000, v132
	v_pk_mul_f32 v[76:77], v[76:77], v[80:81]
	v_lshlrev_b32_e32 v80, 16, v133
	v_and_b32_e32 v81, 0xffff0000, v133
	v_pk_mul_f32 v[78:79], v[78:79], v[80:81]
	v_cvt_pk_bf16_f32 v76, v76, v77
	v_cvt_pk_bf16_f32 v77, v78, v79
	v_lshlrev_b32_e32 v78, 16, v82
	v_and_b32_e32 v79, 0xffff0000, v82
	v_pk_mul_f32 v[72:73], v[72:73], v[78:79]
	v_lshlrev_b32_e32 v78, 16, v83
	v_and_b32_e32 v79, 0xffff0000, v83
	v_pk_mul_f32 v[74:75], v[74:75], v[78:79]
	v_cvt_pk_bf16_f32 v78, v72, v73
	v_cvt_pk_bf16_f32 v79, v74, v75
	v_mov_b32_e32 v74, v122
	v_permlane16_swap_b32_e32 v76, v78
	v_permlane16_swap_b32_e32 v77, v79
	v_lshl_add_u64 v[72:73], s[84:85], 0, v[142:143]
	v_permlane16_swap_b32_e32 v120, v74
	v_mov_b32_e32 v75, v123
	global_store_dwordx4 v[72:73], v[76:79], off
	s_nop 0
	v_permlane16_swap_b32_e32 v121, v75
	v_lshlrev_b32_e32 v72, 16, v120
	v_and_b32_e32 v73, 0xffff0000, v120
	v_pk_mul_f32 v[68:69], v[68:69], v[72:73]
	v_lshlrev_b32_e32 v72, 16, v121
	v_and_b32_e32 v73, 0xffff0000, v121
	v_pk_mul_f32 v[70:71], v[70:71], v[72:73]
	v_cvt_pk_bf16_f32 v68, v68, v69
	v_cvt_pk_bf16_f32 v69, v70, v71
	v_lshlrev_b32_e32 v70, 16, v74
	v_and_b32_e32 v71, 0xffff0000, v74
	v_pk_mul_f32 v[64:65], v[64:65], v[70:71]
	v_lshlrev_b32_e32 v70, 16, v75
	v_and_b32_e32 v71, 0xffff0000, v75
	v_pk_mul_f32 v[66:67], v[66:67], v[70:71]
	v_cvt_pk_bf16_f32 v70, v64, v65
	v_cvt_pk_bf16_f32 v71, v66, v67
	s_nop 0
	v_permlane16_swap_b32_e32 v68, v70
	v_permlane16_swap_b32_e32 v69, v71
	v_lshl_add_u64 v[64:65], s[84:85], 0, v[140:141]
	global_store_dwordx4 v[64:65], v[68:71], off
	v_add_u32_e32 v192, v126, v178
	v_lshlrev_b64 v[86:87], 1, v[192:193]
	v_add_u32_e32 v192, v127, v178
	v_lshlrev_b64 v[80:81], 1, v[192:193]
	v_add_u32_e32 v192, v128, v178
	v_lshlrev_b64 v[78:79], 1, v[192:193]
	v_add_u32_e32 v192, v129, v178
	v_lshl_add_u64 v[64:65], s[14:15], 0, v[86:87]
	v_lshl_add_u64 v[66:67], s[14:15], 0, v[80:81]
	v_lshlrev_b64 v[76:77], 1, v[192:193]
	global_load_dwordx4 v[82:85], v[64:65], off
	global_load_dwordx4 v[72:75], v[66:67], off
	v_lshl_add_u64 v[64:65], s[14:15], 0, v[78:79]
	v_lshl_add_u64 v[66:67], s[14:15], 0, v[76:77]
	global_load_dwordx4 v[68:71], v[64:65], off
	s_nop 0
	global_load_dwordx4 v[64:67], v[66:67], off
	s_waitcnt vmcnt(0)
	v_mov_b32_e32 v90, v118
	s_nop 1
	v_permlane16_swap_b32_e32 v116, v90
	v_mov_b32_e32 v91, v119
	s_nop 1
	v_permlane16_swap_b32_e32 v117, v91
	v_lshlrev_b32_e32 v88, 16, v116
	v_and_b32_e32 v89, 0xffff0000, v116
	v_pk_mul_f32 v[60:61], v[60:61], v[88:89]
	v_lshlrev_b32_e32 v88, 16, v117
	v_and_b32_e32 v89, 0xffff0000, v117
	v_pk_mul_f32 v[62:63], v[62:63], v[88:89]
	v_cvt_pk_bf16_f32 v60, v60, v61
	v_cvt_pk_bf16_f32 v61, v62, v63
	v_lshlrev_b32_e32 v62, 16, v90
	v_and_b32_e32 v63, 0xffff0000, v90
	v_pk_mul_f32 v[56:57], v[56:57], v[62:63]
	v_lshlrev_b32_e32 v62, 16, v91
	v_and_b32_e32 v63, 0xffff0000, v91
	v_pk_mul_f32 v[58:59], v[58:59], v[62:63]
	v_cvt_pk_bf16_f32 v62, v56, v57
	v_cvt_pk_bf16_f32 v63, v58, v59
	v_mov_b32_e32 v58, v106
	v_permlane16_swap_b32_e32 v60, v62
	v_permlane16_swap_b32_e32 v61, v63
	v_lshl_add_u64 v[56:57], s[84:85], 0, v[114:115]
	v_permlane16_swap_b32_e32 v104, v58
	v_mov_b32_e32 v59, v107
	global_store_dwordx4 v[56:57], v[60:63], off
	s_nop 0
	v_permlane16_swap_b32_e32 v105, v59
	v_lshlrev_b32_e32 v56, 16, v104
	v_and_b32_e32 v57, 0xffff0000, v104
	v_pk_mul_f32 v[52:53], v[52:53], v[56:57]
	v_lshlrev_b32_e32 v56, 16, v105
	v_and_b32_e32 v57, 0xffff0000, v105
	v_pk_mul_f32 v[54:55], v[54:55], v[56:57]
	v_cvt_pk_bf16_f32 v52, v52, v53
	v_cvt_pk_bf16_f32 v53, v54, v55
	v_lshlrev_b32_e32 v54, 16, v58
	v_and_b32_e32 v55, 0xffff0000, v58
	v_pk_mul_f32 v[48:49], v[48:49], v[54:55]
	v_lshlrev_b32_e32 v54, 16, v59
	v_and_b32_e32 v55, 0xffff0000, v59
	v_pk_mul_f32 v[50:51], v[50:51], v[54:55]
	v_cvt_pk_bf16_f32 v54, v48, v49
	v_cvt_pk_bf16_f32 v55, v50, v51
	v_mov_b32_e32 v50, v102
	v_permlane16_swap_b32_e32 v52, v54
	v_permlane16_swap_b32_e32 v53, v55
	v_lshl_add_u64 v[48:49], s[84:85], 0, v[112:113]
	v_permlane16_swap_b32_e32 v100, v50
	v_mov_b32_e32 v51, v103
	global_store_dwordx4 v[48:49], v[52:55], off
	s_nop 0
	v_permlane16_swap_b32_e32 v101, v51
	v_lshlrev_b32_e32 v48, 16, v100
	v_and_b32_e32 v49, 0xffff0000, v100
	v_pk_mul_f32 v[44:45], v[44:45], v[48:49]
	v_lshlrev_b32_e32 v48, 16, v101
	v_and_b32_e32 v49, 0xffff0000, v101
	v_pk_mul_f32 v[46:47], v[46:47], v[48:49]
	v_cvt_pk_bf16_f32 v44, v44, v45
	v_cvt_pk_bf16_f32 v45, v46, v47
	v_lshlrev_b32_e32 v46, 16, v50
	v_and_b32_e32 v47, 0xffff0000, v50
	v_pk_mul_f32 v[40:41], v[40:41], v[46:47]
	v_lshlrev_b32_e32 v46, 16, v51
	v_and_b32_e32 v47, 0xffff0000, v51
	v_pk_mul_f32 v[42:43], v[42:43], v[46:47]
	v_cvt_pk_bf16_f32 v46, v40, v41
; #define BAR __builtin_amdgcn_s_barrier()
; template <bool SWAP>
; __device__ __forceinline__ void gemm_main(const u16* __restrict__ A, const u16* __restrict__ Bt, int brow, int bcol,
;                                           u16* shm, f32x4 (&acc)[2][2][4][2]) {
;     ...
;   const int lpart = (fr * 64 + fq * 16) ^ ((fr >> 3) << 5);
;   const int abase = wr * 8192 + lpart; int bbase = 65536 + wc * 4096 + lpart;
;   asm volatile("" : "+v"(bbase));
;   if (wr == 1) BAR;
	v_cvt_pk_bf16_f32 v47, v42, v43
	v_mov_b32_e32 v42, v98
	v_permlane16_swap_b32_e32 v44, v46
	v_permlane16_swap_b32_e32 v45, v47
	v_lshl_add_u64 v[40:41], s[84:85], 0, v[110:111]
	v_permlane16_swap_b32_e32 v96, v42
	v_mov_b32_e32 v43, v99
	global_store_dwordx4 v[40:41], v[44:47], off
	s_nop 0
	v_permlane16_swap_b32_e32 v97, v43
	v_lshlrev_b32_e32 v40, 16, v96
	v_and_b32_e32 v41, 0xffff0000, v96
	v_pk_mul_f32 v[36:37], v[36:37], v[40:41]
	v_lshlrev_b32_e32 v40, 16, v97
	v_and_b32_e32 v41, 0xffff0000, v97
	v_pk_mul_f32 v[38:39], v[38:39], v[40:41]
	v_cvt_pk_bf16_f32 v36, v36, v37
	v_cvt_pk_bf16_f32 v37, v38, v39
	v_lshlrev_b32_e32 v38, 16, v42
	v_and_b32_e32 v39, 0xffff0000, v42
	v_pk_mul_f32 v[32:33], v[32:33], v[38:39]
	v_lshlrev_b32_e32 v38, 16, v43
	v_and_b32_e32 v39, 0xffff0000, v43
	v_pk_mul_f32 v[34:35], v[34:35], v[38:39]
	v_cvt_pk_bf16_f32 v38, v32, v33
	v_cvt_pk_bf16_f32 v39, v34, v35
	s_nop 0
	v_permlane16_swap_b32_e32 v36, v38
	v_permlane16_swap_b32_e32 v37, v39
	v_lshl_add_u64 v[32:33], s[84:85], 0, v[108:109]
	global_store_dwordx4 v[32:33], v[36:39], off
	v_mov_b32_e32 v34, v84
	s_nop 1
	v_permlane16_swap_b32_e32 v82, v34
	v_mov_b32_e32 v35, v85
	s_nop 1
	v_permlane16_swap_b32_e32 v83, v35
	v_lshlrev_b32_e32 v32, 16, v82
	v_and_b32_e32 v33, 0xffff0000, v82
	v_pk_mul_f32 v[28:29], v[28:29], v[32:33]
	v_lshlrev_b32_e32 v32, 16, v83
	v_and_b32_e32 v33, 0xffff0000, v83
	v_pk_mul_f32 v[30:31], v[30:31], v[32:33]
	v_cvt_pk_bf16_f32 v28, v28, v29
	v_cvt_pk_bf16_f32 v29, v30, v31
	v_lshlrev_b32_e32 v30, 16, v34
	v_and_b32_e32 v31, 0xffff0000, v34
	v_pk_mul_f32 v[24:25], v[24:25], v[30:31]
	v_lshlrev_b32_e32 v30, 16, v35
	v_and_b32_e32 v31, 0xffff0000, v35
	v_pk_mul_f32 v[26:27], v[26:27], v[30:31]
	v_cvt_pk_bf16_f32 v30, v24, v25
	v_cvt_pk_bf16_f32 v31, v26, v27
	v_mov_b32_e32 v26, v74
	v_permlane16_swap_b32_e32 v28, v30
	v_permlane16_swap_b32_e32 v29, v31
	v_lshl_add_u64 v[24:25], s[84:85], 0, v[86:87]
	v_permlane16_swap_b32_e32 v72, v26
	v_mov_b32_e32 v27, v75
	global_store_dwordx4 v[24:25], v[28:31], off
	s_nop 0
	v_permlane16_swap_b32_e32 v73, v27
	v_lshlrev_b32_e32 v24, 16, v72
	v_and_b32_e32 v25, 0xffff0000, v72
	v_pk_mul_f32 v[20:21], v[20:21], v[24:25]
	v_lshlrev_b32_e32 v24, 16, v73
	v_and_b32_e32 v25, 0xffff0000, v73
	v_pk_mul_f32 v[22:23], v[22:23], v[24:25]
	v_cvt_pk_bf16_f32 v20, v20, v21
	v_cvt_pk_bf16_f32 v21, v22, v23
	v_lshlrev_b32_e32 v22, 16, v26
	v_and_b32_e32 v23, 0xffff0000, v26
	v_pk_mul_f32 v[16:17], v[16:17], v[22:23]
	v_lshlrev_b32_e32 v22, 16, v27
	v_and_b32_e32 v23, 0xffff0000, v27
	v_pk_mul_f32 v[18:19], v[18:19], v[22:23]
	v_cvt_pk_bf16_f32 v22, v16, v17
	v_cvt_pk_bf16_f32 v23, v18, v19
	v_mov_b32_e32 v18, v70
	v_permlane16_swap_b32_e32 v20, v22
	v_permlane16_swap_b32_e32 v21, v23
	v_lshl_add_u64 v[16:17], s[84:85], 0, v[80:81]
	v_permlane16_swap_b32_e32 v68, v18
	v_mov_b32_e32 v19, v71
	global_store_dwordx4 v[16:17], v[20:23], off
	s_nop 0
	v_permlane16_swap_b32_e32 v69, v19
	v_lshlrev_b32_e32 v16, 16, v68
	v_and_b32_e32 v17, 0xffff0000, v68
	v_pk_mul_f32 v[12:13], v[12:13], v[16:17]
	v_lshlrev_b32_e32 v16, 16, v69
	v_and_b32_e32 v17, 0xffff0000, v69
	v_pk_mul_f32 v[14:15], v[14:15], v[16:17]
	v_cvt_pk_bf16_f32 v12, v12, v13
	v_cvt_pk_bf16_f32 v13, v14, v15
	v_lshlrev_b32_e32 v14, 16, v18
	v_and_b32_e32 v15, 0xffff0000, v18
	v_pk_mul_f32 v[8:9], v[8:9], v[14:15]
	v_lshlrev_b32_e32 v14, 16, v19
	v_and_b32_e32 v15, 0xffff0000, v19
	v_pk_mul_f32 v[10:11], v[10:11], v[14:15]
	v_cvt_pk_bf16_f32 v14, v8, v9
	v_cvt_pk_bf16_f32 v15, v10, v11
	v_mov_b32_e32 v10, v66
	v_permlane16_swap_b32_e32 v12, v14
	v_permlane16_swap_b32_e32 v13, v15
	v_lshl_add_u64 v[8:9], s[84:85], 0, v[78:79]
	v_permlane16_swap_b32_e32 v64, v10
	v_mov_b32_e32 v11, v67
	global_store_dwordx4 v[8:9], v[12:15], off
	s_nop 0
	v_permlane16_swap_b32_e32 v65, v11
	v_lshlrev_b32_e32 v8, 16, v64
	v_and_b32_e32 v9, 0xffff0000, v64
	v_pk_mul_f32 v[4:5], v[4:5], v[8:9]
	v_lshlrev_b32_e32 v8, 16, v65
	v_and_b32_e32 v9, 0xffff0000, v65
	v_pk_mul_f32 v[6:7], v[6:7], v[8:9]
	v_cvt_pk_bf16_f32 v4, v4, v5
	v_cvt_pk_bf16_f32 v5, v6, v7
	v_lshlrev_b32_e32 v6, 16, v10
	v_and_b32_e32 v7, 0xffff0000, v10
	v_pk_mul_f32 v[0:1], v[0:1], v[6:7]
	v_lshlrev_b32_e32 v6, 16, v11
	v_and_b32_e32 v7, 0xffff0000, v11
	v_pk_mul_f32 v[2:3], v[2:3], v[6:7]
	v_cvt_pk_bf16_f32 v6, v0, v1
	v_cvt_pk_bf16_f32 v7, v2, v3
	s_nop 0
	v_permlane16_swap_b32_e32 v4, v6
	v_permlane16_swap_b32_e32 v5, v7
	v_lshl_add_u64 v[0:1], s[84:85], 0, v[76:77]
	global_store_dwordx4 v[0:1], v[4:7], off
	v_mov_b32_e32 v136, v210
	s_nop 1
	s_mov_b32 s3, 0x10000
	v_and_b32_e32 v1, 15, v136
	v_lshlrev_b32_e32 v3, 2, v136
	v_and_b32_e32 v2, 48, v136
	v_lshlrev_b32_e32 v1, 6, v1
	v_and_b32_e32 v3, 32, v3
	v_bitop3_b32 v2, v1, v3, v2 bitop3:0x36
	v_lshlrev_b32_e32 v1, 6, v136
	v_ashrrev_i32_e32 v0, 8, v136
	v_and_b32_e32 v1, 0x3000, v1
	v_or3_b32 v1, v1, v2, s3
	v_cmp_eq_u32_e32 vcc, 1, v0
	s_and_saveexec_b64 s[24:25], vcc
	s_cbranch_execz .LBB0_569
	s_barrier
; #define WAIT_V(n) asm volatile("s_waitcnt vmcnt(" #n ")" ::: "memory")
; #define BAR __builtin_amdgcn_s_barrier()
; template <bool SWAP>
; __device__ __forceinline__ void gemm_main(const u16* __restrict__ A, const u16* __restrict__ Bt, int brow, int bcol,
;                                           u16* shm, f32x4 (&acc)[2][2][4][2]) {
;     ...
;   int tx = threadIdx.x; asm volatile("" : "+v"(tx));
;   const int wid = tx >> 6, lane = tx & 63, wr = wid >> 2, wc = wid & 3, fr = lane & 15, fq = lane >> 4;
; #pragma unroll
;   for (int a = 0; a < 2; ++a)
; #pragma unroll
;     for (int b = 0; b < 2; ++b)
; #pragma unroll
;       for (int m = 0; m < 4; ++m)
; #pragma unroll
;         for (int n = 0; n < 2; ++n) acc[a][b][m][n] = f32x4{0.f, 0.f, 0.f, 0.f};
;   bf16x8 At[4][2], B0[2][2], B1[2][2];
;   constexpr int nt = GK / BK;
;   GEMM_VOFF
;   const int lpart = (fr * 64 + fq * 16) ^ ((fr >> 3) << 5);
;   const int abase = wr * 8192 + lpart; int bbase = 65536 + wc * 4096 + lpart;
;   asm volatile("" : "+v"(bbase));
;   if (wr == 1) BAR;
;   WAIT_V(0); BAR;
;   BAR;
.LBB0_569:
	s_or_b64 exec, exec, s[24:25]
	v_bfe_i32 v4, v136, 27, 1
	v_lshlrev_b32_e32 v140, 4, v136
	v_lshrrev_b32_e32 v4, 22, v4
	v_add_u32_e32 v4, v140, v4
	v_and_b32_e32 v4, 0xfffffc00, v4
	v_sub_u32_e32 v4, v140, v4
	v_lshrrev_b32_e32 v5, 4, v4
	v_bitop3_b32 v4, v5, v4, 32 bitop3:0x6c
	v_ashrrev_i32_e32 v5, 31, v4
	v_lshrrev_b32_e32 v5, 26, v5
	v_add_u32_e32 v5, v4, v5
	v_ashrrev_i32_e32 v141, 6, v5
	v_and_b32_e32 v5, 0xc0, v5
	v_sub_u32_e32 v4, v4, v5
	v_ashrrev_i16_sdwa v4, v215, sext(v4) dst_sel:DWORD dst_unused:UNUSED_PAD src0_sel:DWORD src1_sel:BYTE_0
	v_bfe_i32 v142, v4, 0, 16
	v_add_u32_e32 v4, 0x2000, v140
	v_ashrrev_i32_e32 v5, 31, v4
	v_lshrrev_b32_e32 v5, 22, v5
	v_add_u32_e32 v5, v4, v5
	v_ashrrev_i32_e32 v143, 10, v5
	v_mul_i32_i24_e32 v5, 0x400, v143
	v_sub_u32_e32 v4, v4, v5
	v_lshrrev_b32_e32 v5, 4, v4
	v_bitop3_b32 v4, v5, v4, 32 bitop3:0x6c
	v_ashrrev_i32_e32 v5, 31, v4
	v_lshrrev_b32_e32 v5, 26, v5
	v_ashrrev_i32_e32 v3, 31, v136
	v_add_u32_e32 v5, v4, v5
	v_lshrrev_b32_e32 v3, 26, v3
	v_ashrrev_i32_e32 v144, 6, v5
	v_and_b32_e32 v5, 0xc0, v5
	v_add_u32_e32 v3, v136, v3
	v_sub_u32_e32 v4, v4, v5
	v_ashrrev_i32_e32 v139, 6, v3
	v_ashrrev_i16_sdwa v4, v215, sext(v4) dst_sel:DWORD dst_unused:UNUSED_PAD src0_sel:DWORD src1_sel:BYTE_0
	v_bfe_i32 v145, v4, 0, 16
	v_lshlrev_b32_e32 v4, 13, v0
	v_lshlrev_b32_e32 v0, 15, v139
	v_and_b32_e32 v0, 0xffff0000, v0
	v_lshl_add_u32 v0, v141, 12, v0
	v_and_or_b32 v0, v3, 64, v0
	v_lshl_add_u32 v192, v142, 1, v0
	v_lshlrev_b32_e32 v0, 15, v143
	v_and_b32_e32 v0, 0xffff0000, v0
	v_add_u32_e32 v5, 0, v2
	v_lshl_add_u32 v0, v144, 12, v0
	v_lshlrev_b32_e32 v2, 6, v143
	v_readlane_b32 s14, v253, 59
	v_and_or_b32 v0, v2, 64, v0
	v_readlane_b32 s15, v253, 60
	v_lshl_add_u32 v2, v145, 1, v0
	v_mov_b32_e32 v3, v193
	v_mov_b32_e32 v0, 0
	v_lshl_add_u64 v[128:129], s[14:15], 0, v[192:193]
	v_lshl_add_u64 v[130:131], s[14:15], 0, v[2:3]
	v_lshl_add_u64 v[132:133], s[10:11], 0, v[192:193]
	v_lshl_add_u64 v[134:135], s[10:11], 0, v[2:3]
	s_mov_b32 s3, -2
	v_add_u32_e32 v138, 0, v1
	v_add_u32_e32 v137, v5, v4
	s_mov_b64 vcc, s[50:51]
	v_mov_b32_e32 v1, v0
	v_mov_b32_e32 v2, v0
	v_mov_b32_e32 v3, v0
	v_mov_b32_e32 v4, v0
	v_mov_b32_e32 v5, v0
	v_mov_b32_e32 v6, v0
	v_mov_b32_e32 v7, v0
	v_mov_b32_e32 v8, v0
	v_mov_b32_e32 v9, v0
	v_mov_b32_e32 v10, v0
	v_mov_b32_e32 v11, v0
	v_mov_b32_e32 v12, v0
	v_mov_b32_e32 v13, v0
	v_mov_b32_e32 v14, v0
	v_mov_b32_e32 v15, v0
	v_mov_b32_e32 v16, v0
	v_mov_b32_e32 v17, v0
	v_mov_b32_e32 v18, v0
	v_mov_b32_e32 v19, v0
	v_mov_b32_e32 v20, v0
	v_mov_b32_e32 v21, v0
	v_mov_b32_e32 v22, v0
	v_mov_b32_e32 v23, v0
	v_mov_b32_e32 v24, v0
	v_mov_b32_e32 v25, v0
	v_mov_b32_e32 v26, v0
	v_mov_b32_e32 v27, v0
	v_mov_b32_e32 v28, v0
	v_mov_b32_e32 v29, v0
	v_mov_b32_e32 v30, v0
	v_mov_b32_e32 v31, v0
	v_mov_b32_e32 v32, v0
	v_mov_b32_e32 v33, v0
	v_mov_b32_e32 v34, v0
	v_mov_b32_e32 v35, v0
	v_mov_b32_e32 v36, v0
	v_mov_b32_e32 v37, v0
	v_mov_b32_e32 v38, v0
	v_mov_b32_e32 v39, v0
	v_mov_b32_e32 v40, v0
	v_mov_b32_e32 v41, v0
	v_mov_b32_e32 v42, v0
	v_mov_b32_e32 v43, v0
	v_mov_b32_e32 v44, v0
	v_mov_b32_e32 v45, v0
	v_mov_b32_e32 v46, v0
	v_mov_b32_e32 v47, v0
	v_mov_b32_e32 v48, v0
	v_mov_b32_e32 v49, v0
	v_mov_b32_e32 v50, v0
	v_mov_b32_e32 v51, v0
	v_mov_b32_e32 v52, v0
	v_mov_b32_e32 v53, v0
	v_mov_b32_e32 v54, v0
	v_mov_b32_e32 v55, v0
	v_mov_b32_e32 v56, v0
	v_mov_b32_e32 v57, v0
	v_mov_b32_e32 v58, v0
	v_mov_b32_e32 v59, v0
	v_mov_b32_e32 v60, v0
	v_mov_b32_e32 v61, v0
	v_mov_b32_e32 v62, v0
	v_mov_b32_e32 v63, v0
	v_mov_b32_e32 v64, v0
	v_mov_b32_e32 v65, v0
	v_mov_b32_e32 v66, v0
	v_mov_b32_e32 v67, v0
	v_mov_b32_e32 v68, v0
	v_mov_b32_e32 v69, v0
	v_mov_b32_e32 v70, v0
	v_mov_b32_e32 v71, v0
	v_mov_b32_e32 v72, v0
	v_mov_b32_e32 v73, v0
	v_mov_b32_e32 v74, v0
	v_mov_b32_e32 v75, v0
	v_mov_b32_e32 v76, v0
	v_mov_b32_e32 v77, v0
	v_mov_b32_e32 v78, v0
	v_mov_b32_e32 v79, v0
	v_mov_b32_e32 v80, v0
	v_mov_b32_e32 v81, v0
	v_mov_b32_e32 v82, v0
	v_mov_b32_e32 v83, v0
	v_mov_b32_e32 v84, v0
	v_mov_b32_e32 v85, v0
	v_mov_b32_e32 v86, v0
	v_mov_b32_e32 v87, v0
	v_mov_b32_e32 v88, v0
	v_mov_b32_e32 v89, v0
	v_mov_b32_e32 v90, v0
	v_mov_b32_e32 v91, v0
	v_mov_b32_e32 v92, v0
	v_mov_b32_e32 v93, v0
	v_mov_b32_e32 v94, v0
	v_mov_b32_e32 v95, v0
	v_mov_b32_e32 v96, v0
	v_mov_b32_e32 v97, v0
	v_mov_b32_e32 v98, v0
	v_mov_b32_e32 v99, v0
	v_mov_b32_e32 v100, v0
	v_mov_b32_e32 v101, v0
	v_mov_b32_e32 v102, v0
	v_mov_b32_e32 v103, v0
	v_mov_b32_e32 v104, v0
	v_mov_b32_e32 v105, v0
	v_mov_b32_e32 v106, v0
	v_mov_b32_e32 v107, v0
	v_mov_b32_e32 v108, v0
	v_mov_b32_e32 v109, v0
	v_mov_b32_e32 v110, v0
	v_mov_b32_e32 v111, v0
	v_mov_b32_e32 v112, v0
	v_mov_b32_e32 v113, v0
	v_mov_b32_e32 v114, v0
	v_mov_b32_e32 v115, v0
	v_mov_b32_e32 v116, v0
	v_mov_b32_e32 v117, v0
	v_mov_b32_e32 v118, v0
	v_mov_b32_e32 v119, v0
	v_mov_b32_e32 v120, v0
	v_mov_b32_e32 v121, v0
	v_mov_b32_e32 v122, v0
	v_mov_b32_e32 v123, v0
	v_mov_b32_e32 v124, v0
	v_mov_b32_e32 v125, v0
	v_mov_b32_e32 v126, v0
	v_mov_b32_e32 v127, v0
	s_mov_b64 s[14:15], 0x1b580080
	s_mov_b64 s[16:17], 0x8900100
	s_mov_b64 s[18:19], 0x1b500100
	s_mov_b64 s[42:43], 0x8980100
	s_mov_b64 s[22:23], 0x1b580100
	s_mov_b64 s[20:21], 0x8900180
	s_mov_b64 s[92:93], 0x1b500180
	s_mov_b64 s[72:73], 0x8980180
	v_readfirstlane_b32 s24, v140
	s_waitcnt vmcnt(0)
	s_barrier
	s_barrier

; #define STAGE(P, BASE, br, kt) do { const char* _g = (const char*)((BASE) + (size_t)(br) * GK + (kt) * BK); \
;     __builtin_amdgcn_global_load_lds((const unsigned*)(_g + voff0), (unsigned*)((char*)(P) + tx * 16), 16, 0, 0); \
;     __builtin_amdgcn_global_load_lds((const unsigned*)(_g + voff1), (unsigned*)((char*)(P) + tx * 16 + 8192), 16, 0, 0); } while (0)
; __device__ __forceinline__ void gemm_issue(const u16* __restrict__ A, const u16* __restrict__ Bt, int brow, int bcol, u16* shm) {
;   int tx = threadIdx.x; asm volatile("" : "+v"(tx));
;   GEMM_VOFF
;   STAGE(SB(0, 0), Bt, bcol, 0); STAGE(SA(0, 0), A, brow, 0);
;   STAGE(SB(0, 1), Bt, bcol + HALF, 0); STAGE(SA(0, 1), A, brow + HALF, 0);
;   STAGE(SB(1, 0), Bt, bcol, 1); STAGE(SA(1, 0), A, brow, 1); STAGE(SB(1, 1), Bt, bcol + HALF, 1);
; }
.LBB0_573:
	s_or_b64 exec, exec, s[4:5]
	v_mov_b32_e32 v104, v210
	v_readlane_b32 s5, v251, 50
	v_ashrrev_i32_e32 v105, 31, v104
	v_lshrrev_b32_e32 v105, 26, v105
	v_lshlrev_b32_e32 v126, 4, v104
	v_add_u32_e32 v105, v104, v105
	v_bfe_i32 v104, v104, 27, 1
	v_lshrrev_b32_e32 v104, 22, v104
	v_add_u32_e32 v104, v126, v104
	v_and_b32_e32 v104, 0xfffffc00, v104
	v_sub_u32_e32 v104, v126, v104
	v_lshrrev_b32_e32 v106, 4, v104
	v_bitop3_b32 v104, v106, v104, 32 bitop3:0x6c
	v_ashrrev_i32_e32 v107, 31, v104
	v_lshrrev_b32_e32 v107, 26, v107
	v_add_u32_e32 v107, v104, v107
	v_ashrrev_i32_e32 v105, 6, v105
	v_lshrrev_b32_e32 v108, 6, v107
	v_and_b32_e32 v107, 0xc0, v107
	v_lshlrev_b32_e32 v106, 3, v105
	v_lshlrev_b32_e32 v105, 5, v105
	v_sub_u32_e32 v104, v104, v107
	v_and_b32_e32 v106, 0xffff0, v106
	v_and_b32_e32 v105, 32, v105
	v_ashrrev_i16_sdwa v104, v215, sext(v104) dst_sel:DWORD dst_unused:UNUSED_PAD src0_sel:DWORD src1_sel:BYTE_0
	v_add_u32_sdwa v104, v105, sext(v104) dst_sel:DWORD dst_unused:UNUSED_PAD src0_sel:DWORD src1_sel:WORD_0
	v_add_lshl_u32 v105, v108, v106, 12
	v_lshl_add_u32 v192, v104, 1, v105
	v_add_u32_e32 v104, 0x2000, v126
	v_ashrrev_i32_e32 v105, 31, v104
	v_lshrrev_b32_e32 v105, 22, v105
	v_add_u32_e32 v105, v104, v105
	v_ashrrev_i32_e32 v105, 10, v105
	v_mul_i32_i24_e32 v106, 0x400, v105
	v_sub_u32_e32 v104, v104, v106
	v_lshrrev_b32_e32 v106, 4, v104
	v_bitop3_b32 v104, v106, v104, 32 bitop3:0x6c
	v_ashrrev_i32_e32 v107, 31, v104
	v_lshrrev_b32_e32 v107, 26, v107
	v_add_u32_e32 v107, v104, v107
	v_lshrrev_b32_e32 v108, 6, v107
	v_and_b32_e32 v107, 0xc0, v107
	v_lshlrev_b32_e32 v106, 3, v105
	v_lshlrev_b32_e32 v105, 5, v105
	v_sub_u32_e32 v104, v104, v107
	v_add_u32_e32 v110, s28, v126
	v_and_b32_e32 v106, 0xffff0, v106
	v_and_b32_e32 v105, 32, v105
	v_ashrrev_i16_sdwa v104, v215, sext(v104) dst_sel:DWORD dst_unused:UNUSED_PAD src0_sel:DWORD src1_sel:BYTE_0
	s_add_u32 s2, s5, s2
	v_readlane_b32 s14, v251, 51
	v_readfirstlane_b32 s4, v110
	v_add_u32_e32 v110, 0x2000, v110
	v_add_u32_sdwa v104, v105, sext(v104) dst_sel:DWORD dst_unused:UNUSED_PAD src0_sel:DWORD src1_sel:WORD_0
	v_add_lshl_u32 v105, v108, v106, 12
	s_addc_u32 s3, s14, 0
	s_mov_b32 m0, s4
	v_readfirstlane_b32 s4, v110
	v_lshl_add_u32 v104, v104, 1, v105
	global_load_lds_dwordx4 v192, s[2:3]
	v_mov_b32_e32 v105, v193
	s_mov_b32 m0, s4
	v_add_u32_e32 v127, 0, v126
	v_lshl_add_u64 v[106:107], s[2:3], 0, v[192:193]
	v_lshl_add_u64 v[108:109], s[2:3], 0, v[104:105]
	global_load_lds_dwordx4 v104, s[2:3]
	s_add_u32 s0, s60, s0
	v_readfirstlane_b32 s2, v127
	v_add_u32_e32 v122, 0x2000, v127
	s_addc_u32 s1, s61, s1
	s_mov_b32 m0, s2
	v_readfirstlane_b32 s2, v122
	global_load_lds_dwordx4 v192, s[0:1]
	s_mov_b32 m0, s2
	v_lshl_add_u64 v[110:111], s[0:1], 0, v[192:193]
	v_lshl_add_u64 v[120:121], s[0:1], 0, v[104:105]
	global_load_lds_dwordx4 v104, s[0:1]
	s_add_u32 s0, s5, s9
	s_addc_u32 s1, s14, 0
	v_add_u32_e32 v136, s29, v126
	v_lshl_add_u64 v[124:125], s[0:1], 0, v[104:105]
	v_readfirstlane_b32 s2, v136
	v_add_u32_e32 v105, 0x2000, v136
	s_mov_b32 m0, s2
	v_readfirstlane_b32 s2, v105
	global_load_lds_dwordx4 v192, s[0:1]
	s_mov_b32 m0, s2
	v_add_u32_e32 v105, 0x4000, v127
	v_lshl_add_u64 v[122:123], s[0:1], 0, v[192:193]
	global_load_lds_dwordx4 v104, s[0:1]
	s_add_u32 s0, s60, s12
	v_readfirstlane_b32 s2, v105
	v_add_u32_e32 v105, 0x6000, v127
	s_addc_u32 s1, s61, s13
	s_mov_b32 m0, s2
	v_readfirstlane_b32 s2, v105
	global_load_lds_dwordx4 v192, s[0:1]
	s_mov_b32 m0, s2
	s_mov_b64 s[4:5], 0x80
	global_load_lds_dwordx4 v104, s[0:1]
	v_lshl_add_u64 v[104:105], v[106:107], 0, s[4:5]
	v_add_u32_e32 v106, s30, v126
	s_nop 0
	v_readfirstlane_b32 s2, v106
	v_add_u32_e32 v106, 0x2000, v106
	s_mov_b32 m0, s2
	v_readfirstlane_b32 s2, v106
	v_add_u32_e32 v106, 0x8000, v127
	global_load_lds_dwordx4 v[104:105], off
	v_lshl_add_u64 v[104:105], v[108:109], 0, s[4:5]
	s_mov_b32 m0, s2
	v_readfirstlane_b32 s2, v106
	v_add_u32_e32 v106, 0xa000, v127
	global_load_lds_dwordx4 v[104:105], off
	v_lshl_add_u64 v[104:105], v[110:111], 0, s[4:5]
	s_mov_b32 m0, s2
	v_readfirstlane_b32 s2, v106
	v_add_u32_e32 v106, s31, v126
	global_load_lds_dwordx4 v[104:105], off
	v_lshl_add_u64 v[104:105], v[120:121], 0, s[4:5]
	s_mov_b32 m0, s2
	v_readfirstlane_b32 s2, v106
	v_add_u32_e32 v106, 0x2000, v106
	global_load_lds_dwordx4 v[104:105], off
	v_lshl_add_u64 v[104:105], v[122:123], 0, s[4:5]
	s_mov_b32 m0, s2
	v_readfirstlane_b32 s2, v106
	global_load_lds_dwordx4 v[104:105], off
	v_lshl_add_u64 v[104:105], v[124:125], 0, s[4:5]
	s_mov_b32 m0, s2
	v_readlane_b32 s2, v253, 29
	global_load_lds_dwordx4 v[104:105], off
	v_mov_b32_e32 v104, v223
	v_mov_b32_e32 v105, v224
	v_readlane_b32 s3, v253, 30
	v_add_u32_e32 v179, s55, v105
	v_add_lshl_u32 v225, v104, s8, 11
	v_add_u32_e32 v192, v225, v179
	v_lshlrev_b64 v[104:105], 1, v[192:193]
	v_lshl_add_u64 v[106:107], s[2:3], 0, v[104:105]
	v_lshl_add_u64 v[206:207], s[84:85], 0, v[104:105]
	global_load_dwordx4 v[180:183], v[106:107], off
	global_load_dwordx4 v[184:187], v[206:207], off
	v_add_u32_e32 v108, 0x8000, v225
	v_add_u32_e32 v192, v108, v179
	v_lshlrev_b64 v[104:105], 1, v[192:193]
	v_lshl_add_u64 v[106:107], s[2:3], 0, v[104:105]
	v_lshl_add_u64 v[208:209], s[84:85], 0, v[104:105]
	global_load_dwordx4 v[188:191], v[106:107], off
	global_load_dwordx4 v[194:197], v[208:209], off
	v_add_u32_e32 v109, 0x10000, v225
	v_add_u32_e32 v192, v109, v179
	v_lshlrev_b64 v[104:105], 1, v[192:193]
	v_lshl_add_u64 v[106:107], s[2:3], 0, v[104:105]
	v_lshl_add_u64 v[226:227], s[84:85], 0, v[104:105]
	global_load_dwordx4 v[198:201], v[106:107], off
	global_load_dwordx4 v[202:205], v[226:227], off
	v_add_u32_e32 v110, 0x18000, v225
	v_add_u32_e32 v192, v110, v179
	v_lshlrev_b64 v[104:105], 1, v[192:193]
	v_lshl_add_u64 v[106:107], s[2:3], 0, v[104:105]
	v_lshl_add_u64 v[176:177], s[84:85], 0, v[104:105]
	global_load_dwordx4 v[164:167], v[106:107], off
	global_load_dwordx4 v[160:163], v[176:177], off
	v_add_u32_e32 v178, 0x80, v179
	v_add_u32_e32 v192, v178, v225
	v_lshlrev_b64 v[104:105], 1, v[192:193]
	v_add_u32_e32 v192, v108, v178
	v_lshl_add_u64 v[106:107], s[2:3], 0, v[104:105]
	v_lshl_add_u64 v[174:175], s[84:85], 0, v[104:105]
	v_lshlrev_b64 v[104:105], 1, v[192:193]
	v_add_u32_e32 v192, v109, v178
	global_load_dwordx4 v[156:159], v[106:107], off
	global_load_dwordx4 v[152:155], v[174:175], off
	v_lshl_add_u64 v[106:107], s[2:3], 0, v[104:105]
	v_lshl_add_u64 v[172:173], s[84:85], 0, v[104:105]
	v_lshlrev_b64 v[104:105], 1, v[192:193]
	v_add_u32_e32 v192, v110, v178
	global_load_dwordx4 v[140:143], v[106:107], off
	global_load_dwordx4 v[136:139], v[172:173], off
	v_lshl_add_u64 v[106:107], s[2:3], 0, v[104:105]
	v_lshl_add_u64 v[170:171], s[84:85], 0, v[104:105]
	v_lshlrev_b64 v[104:105], 1, v[192:193]
	global_load_dwordx4 v[124:127], v[106:107], off
	global_load_dwordx4 v[120:123], v[170:171], off
	v_lshl_add_u64 v[106:107], s[2:3], 0, v[104:105]
	v_lshl_add_u64 v[168:169], s[84:85], 0, v[104:105]
	global_load_dwordx4 v[108:111], v[106:107], off
	s_nop 0
	global_load_dwordx4 v[104:107], v[168:169], off
	s_waitcnt vmcnt(0)
	v_mov_b32_e32 v192, v182
	v_mov_b32_e32 v229, v186
	s_nop 0
	v_permlane16_swap_b32_e32 v180, v192
	v_mov_b32_e32 v228, v183
	v_permlane16_swap_b32_e32 v184, v229
	v_mov_b32_e32 v230, v187
	v_permlane16_swap_b32_e32 v181, v228
	s_nop 0
	v_permlane16_swap_b32_e32 v185, v230
	v_lshlrev_b32_e32 v182, 16, v180
	v_and_b32_e32 v183, 0xffff0000, v180
	v_lshlrev_b32_e32 v186, 16, v184
	v_and_b32_e32 v187, 0xffff0000, v184
	v_lshlrev_b32_e32 v180, 16, v181
	v_and_b32_e32 v181, 0xffff0000, v181
	v_pk_fma_f32 v[148:149], v[148:149], v[182:183], v[186:187]
	v_lshlrev_b32_e32 v182, 16, v185
	v_and_b32_e32 v183, 0xffff0000, v185
	v_pk_fma_f32 v[150:151], v[150:151], v[180:181], v[182:183]
	v_cvt_pk_bf16_f32 v148, v148, v149
	v_cvt_pk_bf16_f32 v149, v150, v151
	v_lshlrev_b32_e32 v150, 16, v192
	v_and_b32_e32 v151, 0xffff0000, v192
	v_lshlrev_b32_e32 v182, 16, v229
	v_and_b32_e32 v183, 0xffff0000, v229
	v_lshlrev_b32_e32 v180, 16, v228
	v_and_b32_e32 v181, 0xffff0000, v228
	v_pk_fma_f32 v[144:145], v[144:145], v[150:151], v[182:183]
	v_lshlrev_b32_e32 v150, 16, v230
	v_and_b32_e32 v151, 0xffff0000, v230
	v_pk_fma_f32 v[146:147], v[146:147], v[180:181], v[150:151]
	v_cvt_pk_bf16_f32 v150, v144, v145
	v_cvt_pk_bf16_f32 v151, v146, v147
	s_nop 0
	v_permlane16_swap_b32_e32 v148, v150
	v_permlane16_swap_b32_e32 v149, v151
	global_store_dwordx4 v[206:207], v[148:151], off
	v_mov_b32_e32 v180, v196
	s_nop 1
	v_permlane16_swap_b32_e32 v194, v180
	v_mov_b32_e32 v150, v190
	s_nop 1
	v_permlane16_swap_b32_e32 v188, v150
	v_mov_b32_e32 v151, v191
	v_mov_b32_e32 v181, v197
	s_nop 0
	v_permlane16_swap_b32_e32 v189, v151
	v_permlane16_swap_b32_e32 v195, v181
	v_lshlrev_b32_e32 v144, 16, v188
	v_and_b32_e32 v145, 0xffff0000, v188
	v_lshlrev_b32_e32 v148, 16, v194
	v_and_b32_e32 v149, 0xffff0000, v194
	v_lshlrev_b32_e32 v146, 16, v189
	v_and_b32_e32 v147, 0xffff0000, v189
	v_pk_fma_f32 v[132:133], v[132:133], v[144:145], v[148:149]
	v_lshlrev_b32_e32 v144, 16, v195
	v_and_b32_e32 v145, 0xffff0000, v195
	v_pk_fma_f32 v[134:135], v[134:135], v[146:147], v[144:145]
	v_cvt_pk_bf16_f32 v132, v132, v133
	v_cvt_pk_bf16_f32 v133, v134, v135
	v_lshlrev_b32_e32 v134, 16, v150
	v_and_b32_e32 v135, 0xffff0000, v150
	v_lshlrev_b32_e32 v146, 16, v180
	v_and_b32_e32 v147, 0xffff0000, v180
	v_lshlrev_b32_e32 v144, 16, v151
	v_and_b32_e32 v145, 0xffff0000, v151
	v_pk_fma_f32 v[128:129], v[128:129], v[134:135], v[146:147]
	v_lshlrev_b32_e32 v134, 16, v181
	v_and_b32_e32 v135, 0xffff0000, v181
	v_pk_fma_f32 v[130:131], v[130:131], v[144:145], v[134:135]
	v_cvt_pk_bf16_f32 v134, v128, v129
	v_cvt_pk_bf16_f32 v135, v130, v131
	s_nop 0
	v_permlane16_swap_b32_e32 v132, v134
	v_permlane16_swap_b32_e32 v133, v135
	global_store_dwordx4 v[208:209], v[132:135], off
	v_mov_b32_e32 v144, v204
	s_nop 1
	v_permlane16_swap_b32_e32 v202, v144
	v_mov_b32_e32 v134, v200
	s_nop 1
	v_permlane16_swap_b32_e32 v198, v134
	v_mov_b32_e32 v135, v201
	v_mov_b32_e32 v145, v205
	s_nop 0
	v_permlane16_swap_b32_e32 v199, v135
	v_permlane16_swap_b32_e32 v203, v145
	v_lshlrev_b32_e32 v128, 16, v198
	v_and_b32_e32 v129, 0xffff0000, v198
	v_lshlrev_b32_e32 v132, 16, v202
	v_and_b32_e32 v133, 0xffff0000, v202
	v_lshlrev_b32_e32 v130, 16, v199
	v_and_b32_e32 v131, 0xffff0000, v199
	v_pk_fma_f32 v[116:117], v[116:117], v[128:129], v[132:133]
	v_lshlrev_b32_e32 v128, 16, v203
	v_and_b32_e32 v129, 0xffff0000, v203
	v_pk_fma_f32 v[118:119], v[118:119], v[130:131], v[128:129]
	v_cvt_pk_bf16_f32 v116, v116, v117
	v_cvt_pk_bf16_f32 v117, v118, v119
	v_lshlrev_b32_e32 v118, 16, v134
	v_and_b32_e32 v119, 0xffff0000, v134
	v_lshlrev_b32_e32 v130, 16, v144
	v_and_b32_e32 v131, 0xffff0000, v144
	v_lshlrev_b32_e32 v128, 16, v135
	v_and_b32_e32 v129, 0xffff0000, v135
	v_pk_fma_f32 v[112:113], v[112:113], v[118:119], v[130:131]
	v_lshlrev_b32_e32 v118, 16, v145
	v_and_b32_e32 v119, 0xffff0000, v145
	v_pk_fma_f32 v[114:115], v[114:115], v[128:129], v[118:119]
	v_cvt_pk_bf16_f32 v118, v112, v113
	v_cvt_pk_bf16_f32 v119, v114, v115
	s_nop 0
	v_permlane16_swap_b32_e32 v116, v118
	v_permlane16_swap_b32_e32 v117, v119
	global_store_dwordx4 v[226:227], v[116:119], off
	v_mov_b32_e32 v128, v162
	s_nop 1
	v_permlane16_swap_b32_e32 v160, v128
	v_mov_b32_e32 v118, v166
	s_nop 1
	v_permlane16_swap_b32_e32 v164, v118
	v_mov_b32_e32 v119, v167
	v_mov_b32_e32 v129, v163
	s_nop 0
	v_permlane16_swap_b32_e32 v165, v119
	v_permlane16_swap_b32_e32 v161, v129
	v_lshlrev_b32_e32 v112, 16, v164
	v_and_b32_e32 v113, 0xffff0000, v164
	v_lshlrev_b32_e32 v116, 16, v160
	v_and_b32_e32 v117, 0xffff0000, v160
	v_lshlrev_b32_e32 v114, 16, v165
	v_and_b32_e32 v115, 0xffff0000, v165
	v_pk_fma_f32 v[100:101], v[100:101], v[112:113], v[116:117]
	v_lshlrev_b32_e32 v112, 16, v161
	v_and_b32_e32 v113, 0xffff0000, v161
	v_pk_fma_f32 v[102:103], v[102:103], v[114:115], v[112:113]
	v_cvt_pk_bf16_f32 v100, v100, v101
	v_cvt_pk_bf16_f32 v101, v102, v103
	v_lshlrev_b32_e32 v102, 16, v118
	v_and_b32_e32 v103, 0xffff0000, v118
	v_lshlrev_b32_e32 v114, 16, v128
	v_and_b32_e32 v115, 0xffff0000, v128
	v_lshlrev_b32_e32 v112, 16, v119
	v_and_b32_e32 v113, 0xffff0000, v119
	v_pk_fma_f32 v[96:97], v[96:97], v[102:103], v[114:115]
	v_lshlrev_b32_e32 v102, 16, v129
	v_and_b32_e32 v103, 0xffff0000, v129
	v_pk_fma_f32 v[98:99], v[98:99], v[112:113], v[102:103]
	v_cvt_pk_bf16_f32 v102, v96, v97
	v_cvt_pk_bf16_f32 v103, v98, v99
	s_nop 0
	v_permlane16_swap_b32_e32 v100, v102
	v_permlane16_swap_b32_e32 v101, v103
	global_store_dwordx4 v[176:177], v[100:103], off
	v_add_u32_e32 v176, 0x40000, v225
	v_add_u32_e32 v192, v176, v179
	v_add_u32_e32 v177, 0x48000, v225
	v_lshlrev_b64 v[96:97], 1, v[192:193]
	v_add_u32_e32 v192, v177, v179
	v_add_u32_e32 v180, 0x50000, v225
	v_lshl_add_u64 v[98:99], s[2:3], 0, v[96:97]
	v_lshl_add_u64 v[166:167], s[84:85], 0, v[96:97]
	v_lshlrev_b64 v[96:97], 1, v[192:193]
	v_add_u32_e32 v192, v180, v179
	v_add_u32_e32 v181, 0x58000, v225
	global_load_dwordx4 v[148:151], v[98:99], off
	global_load_dwordx4 v[144:147], v[166:167], off
	v_lshl_add_u64 v[98:99], s[2:3], 0, v[96:97]
	v_lshl_add_u64 v[164:165], s[84:85], 0, v[96:97]
	v_lshlrev_b64 v[96:97], 1, v[192:193]
	v_add_u32_e32 v192, v181, v179
	global_load_dwordx4 v[132:135], v[98:99], off
	global_load_dwordx4 v[128:131], v[164:165], off
	v_lshl_add_u64 v[98:99], s[2:3], 0, v[96:97]
	v_lshl_add_u64 v[162:163], s[84:85], 0, v[96:97]
	v_lshlrev_b64 v[96:97], 1, v[192:193]
	global_load_dwordx4 v[116:119], v[98:99], off
	global_load_dwordx4 v[112:115], v[162:163], off
	v_lshl_add_u64 v[98:99], s[2:3], 0, v[96:97]
	v_lshl_add_u64 v[160:161], s[84:85], 0, v[96:97]
	global_load_dwordx4 v[100:103], v[98:99], off
	s_nop 0
	global_load_dwordx4 v[96:99], v[160:161], off
	v_mov_b32_e32 v179, v158
	v_mov_b32_e32 v182, v159
	v_mov_b32_e32 v183, v154
	v_mov_b32_e32 v184, v155
	v_permlane16_swap_b32_e32 v156, v179
	v_permlane16_swap_b32_e32 v157, v182
	v_permlane16_swap_b32_e32 v152, v183
	v_permlane16_swap_b32_e32 v153, v184
	v_lshlrev_b32_e32 v154, 16, v156
	v_and_b32_e32 v155, 0xffff0000, v156
	v_lshlrev_b32_e32 v156, 16, v157
	v_and_b32_e32 v157, 0xffff0000, v157
	v_lshlrev_b32_e32 v158, 16, v152
	v_and_b32_e32 v159, 0xffff0000, v152
	v_lshlrev_b32_e32 v152, 16, v153
	v_and_b32_e32 v153, 0xffff0000, v153
	v_pk_fma_f32 v[92:93], v[92:93], v[154:155], v[158:159]
	v_pk_fma_f32 v[94:95], v[94:95], v[156:157], v[152:153]
	v_cvt_pk_bf16_f32 v92, v92, v93
	v_cvt_pk_bf16_f32 v93, v94, v95
	v_lshlrev_b32_e32 v94, 16, v179
	v_and_b32_e32 v95, 0xffff0000, v179
	v_lshlrev_b32_e32 v154, 16, v183
	v_and_b32_e32 v155, 0xffff0000, v183
	v_lshlrev_b32_e32 v152, 16, v182
	v_and_b32_e32 v153, 0xffff0000, v182
	v_pk_fma_f32 v[88:89], v[88:89], v[94:95], v[154:155]
	v_lshlrev_b32_e32 v94, 16, v184
	v_and_b32_e32 v95, 0xffff0000, v184
	v_pk_fma_f32 v[90:91], v[90:91], v[152:153], v[94:95]
	v_cvt_pk_bf16_f32 v94, v88, v89
	v_cvt_pk_bf16_f32 v95, v90, v91
	s_nop 0
	v_permlane16_swap_b32_e32 v92, v94
	v_permlane16_swap_b32_e32 v93, v95
	global_store_dwordx4 v[174:175], v[92:95], off
	v_permlane16_swap_b32_e32 v136, v138
	s_nop 0
	v_mov_b32_e32 v94, v142
	s_nop 1
	v_permlane16_swap_b32_e32 v140, v94
	v_mov_b32_e32 v95, v143
	s_nop 1
	v_permlane16_swap_b32_e32 v141, v95
	v_permlane16_swap_b32_e32 v137, v139
	v_lshlrev_b32_e32 v88, 16, v140
	v_and_b32_e32 v89, 0xffff0000, v140
	v_lshlrev_b32_e32 v92, 16, v136
	v_and_b32_e32 v93, 0xffff0000, v136
	v_lshlrev_b32_e32 v90, 16, v141
	v_and_b32_e32 v91, 0xffff0000, v141
	v_pk_fma_f32 v[84:85], v[84:85], v[88:89], v[92:93]
	v_lshlrev_b32_e32 v88, 16, v137
	v_and_b32_e32 v89, 0xffff0000, v137
	v_pk_fma_f32 v[86:87], v[86:87], v[90:91], v[88:89]
	v_cvt_pk_bf16_f32 v84, v84, v85
	v_cvt_pk_bf16_f32 v85, v86, v87
	v_lshlrev_b32_e32 v86, 16, v94
	v_and_b32_e32 v87, 0xffff0000, v94
	v_lshlrev_b32_e32 v90, 16, v138
	v_and_b32_e32 v91, 0xffff0000, v138
	v_lshlrev_b32_e32 v88, 16, v95
	v_and_b32_e32 v89, 0xffff0000, v95
	v_pk_fma_f32 v[80:81], v[80:81], v[86:87], v[90:91]
	v_lshlrev_b32_e32 v86, 16, v139
	v_and_b32_e32 v87, 0xffff0000, v139
	v_pk_fma_f32 v[82:83], v[82:83], v[88:89], v[86:87]
	v_cvt_pk_bf16_f32 v86, v80, v81
	v_cvt_pk_bf16_f32 v87, v82, v83
	s_nop 0
	v_permlane16_swap_b32_e32 v84, v86
	v_permlane16_swap_b32_e32 v85, v87
	global_store_dwordx4 v[172:173], v[84:87], off
	v_mov_b32_e32 v88, v122
	s_nop 1
	v_permlane16_swap_b32_e32 v120, v88
	v_mov_b32_e32 v86, v126
	s_nop 1
	v_permlane16_swap_b32_e32 v124, v86
	v_mov_b32_e32 v87, v127
	v_mov_b32_e32 v89, v123
	s_nop 0
	v_permlane16_swap_b32_e32 v125, v87
	v_permlane16_swap_b32_e32 v121, v89
	v_lshlrev_b32_e32 v80, 16, v124
	v_and_b32_e32 v81, 0xffff0000, v124
	v_lshlrev_b32_e32 v84, 16, v120
	v_and_b32_e32 v85, 0xffff0000, v120
	v_lshlrev_b32_e32 v82, 16, v125
	v_and_b32_e32 v83, 0xffff0000, v125
	v_pk_fma_f32 v[76:77], v[76:77], v[80:81], v[84:85]
	v_lshlrev_b32_e32 v80, 16, v121
	v_and_b32_e32 v81, 0xffff0000, v121
	v_pk_fma_f32 v[78:79], v[78:79], v[82:83], v[80:81]
	v_cvt_pk_bf16_f32 v76, v76, v77
	v_cvt_pk_bf16_f32 v77, v78, v79
	v_lshlrev_b32_e32 v78, 16, v86
	v_and_b32_e32 v79, 0xffff0000, v86
	v_lshlrev_b32_e32 v82, 16, v88
	v_and_b32_e32 v83, 0xffff0000, v88
	v_lshlrev_b32_e32 v80, 16, v87
	v_and_b32_e32 v81, 0xffff0000, v87
	v_pk_fma_f32 v[72:73], v[72:73], v[78:79], v[82:83]
	v_lshlrev_b32_e32 v78, 16, v89
	v_and_b32_e32 v79, 0xffff0000, v89
	v_pk_fma_f32 v[74:75], v[74:75], v[80:81], v[78:79]
	v_cvt_pk_bf16_f32 v78, v72, v73
	v_cvt_pk_bf16_f32 v79, v74, v75
	s_nop 0
	v_permlane16_swap_b32_e32 v76, v78
	v_permlane16_swap_b32_e32 v77, v79
	global_store_dwordx4 v[170:171], v[76:79], off
	v_mov_b32_e32 v80, v106
	s_nop 1
	v_permlane16_swap_b32_e32 v104, v80
	v_mov_b32_e32 v78, v110
	s_nop 1
	v_permlane16_swap_b32_e32 v108, v78
	v_mov_b32_e32 v79, v111
	v_mov_b32_e32 v81, v107
	s_nop 0
	v_permlane16_swap_b32_e32 v109, v79
	v_permlane16_swap_b32_e32 v105, v81
	v_lshlrev_b32_e32 v72, 16, v108
	v_and_b32_e32 v73, 0xffff0000, v108
	v_lshlrev_b32_e32 v76, 16, v104
	v_and_b32_e32 v77, 0xffff0000, v104
	v_lshlrev_b32_e32 v74, 16, v109
	v_and_b32_e32 v75, 0xffff0000, v109
	v_pk_fma_f32 v[68:69], v[68:69], v[72:73], v[76:77]
	v_lshlrev_b32_e32 v72, 16, v105
	v_and_b32_e32 v73, 0xffff0000, v105
	v_pk_fma_f32 v[70:71], v[70:71], v[74:75], v[72:73]
	v_cvt_pk_bf16_f32 v68, v68, v69
	v_cvt_pk_bf16_f32 v69, v70, v71
	v_lshlrev_b32_e32 v70, 16, v78
	v_and_b32_e32 v71, 0xffff0000, v78
	v_lshlrev_b32_e32 v74, 16, v80
	v_and_b32_e32 v75, 0xffff0000, v80
	v_lshlrev_b32_e32 v72, 16, v79
	v_and_b32_e32 v73, 0xffff0000, v79
	v_pk_fma_f32 v[64:65], v[64:65], v[70:71], v[74:75]
	v_lshlrev_b32_e32 v70, 16, v81
	v_and_b32_e32 v71, 0xffff0000, v81
	v_pk_fma_f32 v[66:67], v[66:67], v[72:73], v[70:71]
	v_cvt_pk_bf16_f32 v70, v64, v65
	v_cvt_pk_bf16_f32 v71, v66, v67
	s_nop 0
	v_permlane16_swap_b32_e32 v68, v70
	v_permlane16_swap_b32_e32 v69, v71
	global_store_dwordx4 v[168:169], v[68:71], off
	v_add_u32_e32 v192, v176, v178
	v_lshlrev_b64 v[64:65], 1, v[192:193]
	v_add_u32_e32 v192, v177, v178
	v_lshl_add_u64 v[66:67], s[2:3], 0, v[64:65]
	v_lshl_add_u64 v[110:111], s[84:85], 0, v[64:65]
	v_lshlrev_b64 v[64:65], 1, v[192:193]
	v_add_u32_e32 v192, v180, v178
	global_load_dwordx4 v[92:95], v[66:67], off
	global_load_dwordx4 v[88:91], v[110:111], off
	v_lshl_add_u64 v[66:67], s[2:3], 0, v[64:65]
	v_lshl_add_u64 v[108:109], s[84:85], 0, v[64:65]
	v_lshlrev_b64 v[64:65], 1, v[192:193]
	v_add_u32_e32 v192, v181, v178
	global_load_dwordx4 v[84:87], v[66:67], off
	global_load_dwordx4 v[80:83], v[108:109], off
	v_lshl_add_u64 v[66:67], s[2:3], 0, v[64:65]
	v_lshl_add_u64 v[106:107], s[84:85], 0, v[64:65]
	v_lshlrev_b64 v[64:65], 1, v[192:193]
	global_load_dwordx4 v[76:79], v[66:67], off
	global_load_dwordx4 v[72:75], v[106:107], off
	v_lshl_add_u64 v[66:67], s[2:3], 0, v[64:65]
	v_lshl_add_u64 v[104:105], s[84:85], 0, v[64:65]
	global_load_dwordx4 v[68:71], v[66:67], off
	s_nop 0
	global_load_dwordx4 v[64:67], v[104:105], off
	s_waitcnt vmcnt(0)
	v_mov_b32_e32 v126, v150
	v_mov_b32_e32 v136, v146
	s_nop 0
	v_permlane16_swap_b32_e32 v148, v126
	v_mov_b32_e32 v127, v151
	v_permlane16_swap_b32_e32 v144, v136
	v_mov_b32_e32 v137, v147
	v_permlane16_swap_b32_e32 v149, v127
	s_nop 0
	v_permlane16_swap_b32_e32 v145, v137
	v_lshlrev_b32_e32 v120, 16, v148
	v_and_b32_e32 v121, 0xffff0000, v148
	v_lshlrev_b32_e32 v124, 16, v144
	v_and_b32_e32 v125, 0xffff0000, v144
	v_lshlrev_b32_e32 v122, 16, v149
	v_and_b32_e32 v123, 0xffff0000, v149
	v_pk_fma_f32 v[60:61], v[60:61], v[120:121], v[124:125]
	v_lshlrev_b32_e32 v120, 16, v145
	v_and_b32_e32 v121, 0xffff0000, v145
	v_pk_fma_f32 v[62:63], v[62:63], v[122:123], v[120:121]
	v_cvt_pk_bf16_f32 v60, v60, v61
	v_cvt_pk_bf16_f32 v61, v62, v63
	v_lshlrev_b32_e32 v62, 16, v126
	v_and_b32_e32 v63, 0xffff0000, v126
	v_lshlrev_b32_e32 v122, 16, v136
	v_and_b32_e32 v123, 0xffff0000, v136
	v_lshlrev_b32_e32 v120, 16, v127
	v_and_b32_e32 v121, 0xffff0000, v127
	v_pk_fma_f32 v[56:57], v[56:57], v[62:63], v[122:123]
	v_lshlrev_b32_e32 v62, 16, v137
	v_and_b32_e32 v63, 0xffff0000, v137
	v_pk_fma_f32 v[58:59], v[58:59], v[120:121], v[62:63]
	v_cvt_pk_bf16_f32 v62, v56, v57
	v_cvt_pk_bf16_f32 v63, v58, v59
	s_nop 0
	v_permlane16_swap_b32_e32 v60, v62
	v_permlane16_swap_b32_e32 v61, v63
	global_store_dwordx4 v[166:167], v[60:63], off
	v_mov_b32_e32 v120, v130
	s_nop 1
	v_permlane16_swap_b32_e32 v128, v120
	v_mov_b32_e32 v62, v134
	s_nop 1
	v_permlane16_swap_b32_e32 v132, v62
	v_mov_b32_e32 v63, v135
	v_mov_b32_e32 v121, v131
	s_nop 0
	v_permlane16_swap_b32_e32 v133, v63
	v_permlane16_swap_b32_e32 v129, v121
	v_lshlrev_b32_e32 v56, 16, v132
	v_and_b32_e32 v57, 0xffff0000, v132
	v_lshlrev_b32_e32 v60, 16, v128
	v_and_b32_e32 v61, 0xffff0000, v128
	v_lshlrev_b32_e32 v58, 16, v133
	v_and_b32_e32 v59, 0xffff0000, v133
	v_pk_fma_f32 v[52:53], v[52:53], v[56:57], v[60:61]
	v_lshlrev_b32_e32 v56, 16, v129
	v_and_b32_e32 v57, 0xffff0000, v129
	v_pk_fma_f32 v[54:55], v[54:55], v[58:59], v[56:57]
	v_cvt_pk_bf16_f32 v52, v52, v53
	v_cvt_pk_bf16_f32 v53, v54, v55
	v_lshlrev_b32_e32 v54, 16, v62
	v_and_b32_e32 v55, 0xffff0000, v62
	v_lshlrev_b32_e32 v58, 16, v120
	v_and_b32_e32 v59, 0xffff0000, v120
	v_lshlrev_b32_e32 v56, 16, v63
	v_and_b32_e32 v57, 0xffff0000, v63
	v_pk_fma_f32 v[48:49], v[48:49], v[54:55], v[58:59]
	v_lshlrev_b32_e32 v54, 16, v121
	v_and_b32_e32 v55, 0xffff0000, v121
	v_pk_fma_f32 v[50:51], v[50:51], v[56:57], v[54:55]
	v_cvt_pk_bf16_f32 v54, v48, v49
	v_cvt_pk_bf16_f32 v55, v50, v51
	s_nop 0
	v_permlane16_swap_b32_e32 v52, v54
	v_permlane16_swap_b32_e32 v53, v55
	global_store_dwordx4 v[164:165], v[52:55], off
	v_mov_b32_e32 v56, v114
	s_nop 1
	v_permlane16_swap_b32_e32 v112, v56
	v_mov_b32_e32 v54, v118
	s_nop 1
	v_permlane16_swap_b32_e32 v116, v54
	v_mov_b32_e32 v55, v119
	v_mov_b32_e32 v57, v115
	s_nop 0
	v_permlane16_swap_b32_e32 v117, v55
	v_permlane16_swap_b32_e32 v113, v57
	v_lshlrev_b32_e32 v48, 16, v116
	v_and_b32_e32 v49, 0xffff0000, v116
	v_lshlrev_b32_e32 v52, 16, v112
	v_and_b32_e32 v53, 0xffff0000, v112
	v_lshlrev_b32_e32 v50, 16, v117
	v_and_b32_e32 v51, 0xffff0000, v117
	v_pk_fma_f32 v[44:45], v[44:45], v[48:49], v[52:53]
	v_lshlrev_b32_e32 v48, 16, v113
	v_and_b32_e32 v49, 0xffff0000, v113
	v_pk_fma_f32 v[46:47], v[46:47], v[50:51], v[48:49]
	v_cvt_pk_bf16_f32 v44, v44, v45
	v_cvt_pk_bf16_f32 v45, v46, v47
	v_lshlrev_b32_e32 v46, 16, v54
	v_and_b32_e32 v47, 0xffff0000, v54
	v_lshlrev_b32_e32 v50, 16, v56
	v_and_b32_e32 v51, 0xffff0000, v56
	v_lshlrev_b32_e32 v48, 16, v55
	v_and_b32_e32 v49, 0xffff0000, v55
	v_pk_fma_f32 v[40:41], v[40:41], v[46:47], v[50:51]
	v_lshlrev_b32_e32 v46, 16, v57
	v_and_b32_e32 v47, 0xffff0000, v57
	v_pk_fma_f32 v[42:43], v[42:43], v[48:49], v[46:47]
	v_cvt_pk_bf16_f32 v46, v40, v41
	v_cvt_pk_bf16_f32 v47, v42, v43
	s_nop 0
	v_permlane16_swap_b32_e32 v44, v46
	v_permlane16_swap_b32_e32 v45, v47
	global_store_dwordx4 v[162:163], v[44:47], off
	v_mov_b32_e32 v48, v98
	s_nop 1
	v_permlane16_swap_b32_e32 v96, v48
	v_mov_b32_e32 v46, v102
	s_nop 1
	v_permlane16_swap_b32_e32 v100, v46
	v_mov_b32_e32 v47, v103
	v_mov_b32_e32 v49, v99
	s_nop 0
	v_permlane16_swap_b32_e32 v101, v47
	v_permlane16_swap_b32_e32 v97, v49
	v_lshlrev_b32_e32 v40, 16, v100
	v_and_b32_e32 v41, 0xffff0000, v100
	v_lshlrev_b32_e32 v44, 16, v96
	v_and_b32_e32 v45, 0xffff0000, v96
	v_lshlrev_b32_e32 v42, 16, v101
	v_and_b32_e32 v43, 0xffff0000, v101
	v_pk_fma_f32 v[36:37], v[36:37], v[40:41], v[44:45]
	v_lshlrev_b32_e32 v40, 16, v97
	v_and_b32_e32 v41, 0xffff0000, v97
	v_pk_fma_f32 v[38:39], v[38:39], v[42:43], v[40:41]
	v_cvt_pk_bf16_f32 v36, v36, v37
	v_cvt_pk_bf16_f32 v37, v38, v39
	v_lshlrev_b32_e32 v38, 16, v46
	v_and_b32_e32 v39, 0xffff0000, v46
	v_lshlrev_b32_e32 v42, 16, v48
	v_and_b32_e32 v43, 0xffff0000, v48
	v_lshlrev_b32_e32 v40, 16, v47
	v_and_b32_e32 v41, 0xffff0000, v47
	v_pk_fma_f32 v[32:33], v[32:33], v[38:39], v[42:43]
	v_lshlrev_b32_e32 v38, 16, v49
	v_and_b32_e32 v39, 0xffff0000, v49
	v_pk_fma_f32 v[34:35], v[34:35], v[40:41], v[38:39]
	v_cvt_pk_bf16_f32 v38, v32, v33
	v_cvt_pk_bf16_f32 v39, v34, v35
	s_nop 0
	v_permlane16_swap_b32_e32 v36, v38
	v_permlane16_swap_b32_e32 v37, v39
	global_store_dwordx4 v[160:161], v[36:39], off
	s_nop 1
	v_mov_b32_e32 v38, v94
	v_mov_b32_e32 v40, v90
	s_nop 0
	v_permlane16_swap_b32_e32 v92, v38
	v_mov_b32_e32 v39, v95
	v_permlane16_swap_b32_e32 v88, v40
	v_mov_b32_e32 v41, v91
	v_permlane16_swap_b32_e32 v93, v39
	s_nop 0
	v_permlane16_swap_b32_e32 v89, v41
	v_lshlrev_b32_e32 v32, 16, v92
	v_and_b32_e32 v33, 0xffff0000, v92
	v_lshlrev_b32_e32 v36, 16, v88
	v_and_b32_e32 v37, 0xffff0000, v88
	v_lshlrev_b32_e32 v34, 16, v93
	v_and_b32_e32 v35, 0xffff0000, v93
	v_pk_fma_f32 v[28:29], v[28:29], v[32:33], v[36:37]
	v_lshlrev_b32_e32 v32, 16, v89
	v_and_b32_e32 v33, 0xffff0000, v89
	v_pk_fma_f32 v[30:31], v[30:31], v[34:35], v[32:33]
	v_cvt_pk_bf16_f32 v28, v28, v29
	v_cvt_pk_bf16_f32 v29, v30, v31
	v_lshlrev_b32_e32 v30, 16, v38
	v_and_b32_e32 v31, 0xffff0000, v38
	v_lshlrev_b32_e32 v34, 16, v40
	v_and_b32_e32 v35, 0xffff0000, v40
	v_lshlrev_b32_e32 v32, 16, v39
	v_and_b32_e32 v33, 0xffff0000, v39
	v_pk_fma_f32 v[24:25], v[24:25], v[30:31], v[34:35]
	v_lshlrev_b32_e32 v30, 16, v41
	v_and_b32_e32 v31, 0xffff0000, v41
	v_pk_fma_f32 v[26:27], v[26:27], v[32:33], v[30:31]
	v_cvt_pk_bf16_f32 v30, v24, v25
	v_cvt_pk_bf16_f32 v31, v26, v27
	s_nop 0
	v_permlane16_swap_b32_e32 v28, v30
	v_permlane16_swap_b32_e32 v29, v31
	global_store_dwordx4 v[110:111], v[28:31], off
	v_mov_b32_e32 v32, v82
	s_nop 1
	v_permlane16_swap_b32_e32 v80, v32
	v_mov_b32_e32 v30, v86
	s_nop 1
	v_permlane16_swap_b32_e32 v84, v30
	v_mov_b32_e32 v31, v87
	v_mov_b32_e32 v33, v83
	s_nop 0
	v_permlane16_swap_b32_e32 v85, v31
	v_permlane16_swap_b32_e32 v81, v33
	v_lshlrev_b32_e32 v24, 16, v84
	v_and_b32_e32 v25, 0xffff0000, v84
	v_lshlrev_b32_e32 v28, 16, v80
	v_and_b32_e32 v29, 0xffff0000, v80
	v_lshlrev_b32_e32 v26, 16, v85
	v_and_b32_e32 v27, 0xffff0000, v85
	v_pk_fma_f32 v[20:21], v[20:21], v[24:25], v[28:29]
	v_lshlrev_b32_e32 v24, 16, v81
	v_and_b32_e32 v25, 0xffff0000, v81
	v_pk_fma_f32 v[22:23], v[22:23], v[26:27], v[24:25]
	v_cvt_pk_bf16_f32 v20, v20, v21
	v_cvt_pk_bf16_f32 v21, v22, v23
	v_lshlrev_b32_e32 v22, 16, v30
	v_and_b32_e32 v23, 0xffff0000, v30
	v_lshlrev_b32_e32 v26, 16, v32
	v_and_b32_e32 v27, 0xffff0000, v32
	v_lshlrev_b32_e32 v24, 16, v31
	v_and_b32_e32 v25, 0xffff0000, v31
	v_pk_fma_f32 v[16:17], v[16:17], v[22:23], v[26:27]
	v_lshlrev_b32_e32 v22, 16, v33
	v_and_b32_e32 v23, 0xffff0000, v33
	v_pk_fma_f32 v[18:19], v[18:19], v[24:25], v[22:23]
	v_cvt_pk_bf16_f32 v22, v16, v17
	v_cvt_pk_bf16_f32 v23, v18, v19
	s_nop 0
	v_permlane16_swap_b32_e32 v20, v22
	v_permlane16_swap_b32_e32 v21, v23
	global_store_dwordx4 v[108:109], v[20:23], off
	v_mov_b32_e32 v24, v74
	s_nop 1
	v_permlane16_swap_b32_e32 v72, v24
	v_mov_b32_e32 v22, v78
	s_nop 1
	v_permlane16_swap_b32_e32 v76, v22
	v_mov_b32_e32 v23, v79
	v_mov_b32_e32 v25, v75
	s_nop 0
	v_permlane16_swap_b32_e32 v77, v23
	v_permlane16_swap_b32_e32 v73, v25
	v_lshlrev_b32_e32 v16, 16, v76
; #define BAR __builtin_amdgcn_s_barrier()
; template <bool SWAP>
; __device__ __forceinline__ void gemm_main(const u16* __restrict__ A, const u16* __restrict__ Bt, int brow, int bcol,
;                                           u16* shm, f32x4 (&acc)[2][2][4][2]) {
;     ...
;   const int lpart = (fr * 64 + fq * 16) ^ ((fr >> 3) << 5);
;   const int abase = wr * 8192 + lpart; int bbase = 65536 + wc * 4096 + lpart;
;   asm volatile("" : "+v"(bbase));
;   if (wr == 1) BAR;
	v_and_b32_e32 v17, 0xffff0000, v76
	v_lshlrev_b32_e32 v20, 16, v72
	v_and_b32_e32 v21, 0xffff0000, v72
	v_lshlrev_b32_e32 v18, 16, v77
	v_and_b32_e32 v19, 0xffff0000, v77
	v_pk_fma_f32 v[12:13], v[12:13], v[16:17], v[20:21]
	v_lshlrev_b32_e32 v16, 16, v73
	v_and_b32_e32 v17, 0xffff0000, v73
	v_pk_fma_f32 v[14:15], v[14:15], v[18:19], v[16:17]
	v_cvt_pk_bf16_f32 v12, v12, v13
	v_cvt_pk_bf16_f32 v13, v14, v15
	v_lshlrev_b32_e32 v14, 16, v22
	v_and_b32_e32 v15, 0xffff0000, v22
	v_lshlrev_b32_e32 v18, 16, v24
	v_and_b32_e32 v19, 0xffff0000, v24
	v_lshlrev_b32_e32 v16, 16, v23
	v_and_b32_e32 v17, 0xffff0000, v23
	v_pk_fma_f32 v[8:9], v[8:9], v[14:15], v[18:19]
	v_lshlrev_b32_e32 v14, 16, v25
	v_and_b32_e32 v15, 0xffff0000, v25
	v_pk_fma_f32 v[10:11], v[10:11], v[16:17], v[14:15]
	v_cvt_pk_bf16_f32 v14, v8, v9
	v_cvt_pk_bf16_f32 v15, v10, v11
	s_nop 0
	v_permlane16_swap_b32_e32 v12, v14
	v_permlane16_swap_b32_e32 v13, v15
	global_store_dwordx4 v[106:107], v[12:15], off
	v_mov_b32_e32 v16, v66
	s_nop 1
	v_permlane16_swap_b32_e32 v64, v16
	v_mov_b32_e32 v14, v70
	s_nop 1
	v_permlane16_swap_b32_e32 v68, v14
	v_mov_b32_e32 v15, v71
	v_mov_b32_e32 v17, v67
	s_nop 0
	v_permlane16_swap_b32_e32 v69, v15
	v_permlane16_swap_b32_e32 v65, v17
	v_lshlrev_b32_e32 v8, 16, v68
	v_and_b32_e32 v9, 0xffff0000, v68
	v_lshlrev_b32_e32 v12, 16, v64
	v_and_b32_e32 v13, 0xffff0000, v64
	v_lshlrev_b32_e32 v10, 16, v69
	v_and_b32_e32 v11, 0xffff0000, v69
	v_pk_fma_f32 v[4:5], v[4:5], v[8:9], v[12:13]
	v_lshlrev_b32_e32 v8, 16, v65
	v_and_b32_e32 v9, 0xffff0000, v65
	v_pk_fma_f32 v[6:7], v[6:7], v[10:11], v[8:9]
	v_cvt_pk_bf16_f32 v4, v4, v5
	v_cvt_pk_bf16_f32 v5, v6, v7
	v_lshlrev_b32_e32 v6, 16, v14
	v_and_b32_e32 v7, 0xffff0000, v14
	v_lshlrev_b32_e32 v10, 16, v16
	v_and_b32_e32 v11, 0xffff0000, v16
	v_lshlrev_b32_e32 v8, 16, v15
	v_and_b32_e32 v9, 0xffff0000, v15
	v_pk_fma_f32 v[0:1], v[0:1], v[6:7], v[10:11]
	v_lshlrev_b32_e32 v6, 16, v17
	v_and_b32_e32 v7, 0xffff0000, v17
	v_pk_fma_f32 v[2:3], v[2:3], v[8:9], v[6:7]
	v_cvt_pk_bf16_f32 v6, v0, v1
	v_cvt_pk_bf16_f32 v7, v2, v3
	s_nop 0
	v_permlane16_swap_b32_e32 v4, v6
	v_permlane16_swap_b32_e32 v5, v7
	global_store_dwordx4 v[104:105], v[4:7], off
	v_mov_b32_e32 v136, v210
	s_nop 1
	s_mov_b32 s2, 0x10000
	v_and_b32_e32 v1, 15, v136
	v_lshlrev_b32_e32 v3, 2, v136
	v_and_b32_e32 v2, 48, v136
	v_lshlrev_b32_e32 v1, 6, v1
	v_and_b32_e32 v3, 32, v3
	v_bitop3_b32 v2, v1, v3, v2 bitop3:0x36
	v_lshlrev_b32_e32 v1, 6, v136
	v_ashrrev_i32_e32 v0, 8, v136
	v_and_b32_e32 v1, 0x3000, v1
	v_or3_b32 v1, v1, v2, s2
	v_cmp_eq_u32_e32 vcc, 1, v0
	s_and_saveexec_b64 s[4:5], vcc
	s_cbranch_execz .LBB0_575
	s_barrier
; #define WAIT_V(n) asm volatile("s_waitcnt vmcnt(" #n ")" ::: "memory")
; #define BAR __builtin_amdgcn_s_barrier()
; template <bool SWAP>
; __device__ __forceinline__ void gemm_main(const u16* __restrict__ A, const u16* __restrict__ Bt, int brow, int bcol,
;                                           u16* shm, f32x4 (&acc)[2][2][4][2]) {
;     ...
;   int tx = threadIdx.x; asm volatile("" : "+v"(tx));
;   const int wid = tx >> 6, lane = tx & 63, wr = wid >> 2, wc = wid & 3, fr = lane & 15, fq = lane >> 4;
; #pragma unroll
;   for (int a = 0; a < 2; ++a)
; #pragma unroll
;     for (int b = 0; b < 2; ++b)
; #pragma unroll
;       for (int m = 0; m < 4; ++m)
; #pragma unroll
;         for (int n = 0; n < 2; ++n) acc[a][b][m][n] = f32x4{0.f, 0.f, 0.f, 0.f};
;   bf16x8 At[4][2], B0[2][2], B1[2][2];
;   constexpr int nt = GK / BK;
;   GEMM_VOFF
;   const int lpart = (fr * 64 + fq * 16) ^ ((fr >> 3) << 5);
;   const int abase = wr * 8192 + lpart; int bbase = 65536 + wc * 4096 + lpart;
;   asm volatile("" : "+v"(bbase));
;   if (wr == 1) BAR;
;   WAIT_V(0); BAR;
;   BAR;
.LBB0_575:
	s_or_b64 exec, exec, s[4:5]
	v_bfe_i32 v4, v136, 27, 1
	v_lshlrev_b32_e32 v140, 4, v136
	v_lshrrev_b32_e32 v4, 22, v4
	v_add_u32_e32 v4, v140, v4
	v_and_b32_e32 v4, 0xfffffc00, v4
	v_sub_u32_e32 v4, v140, v4
	v_lshrrev_b32_e32 v5, 4, v4
	v_bitop3_b32 v4, v5, v4, 32 bitop3:0x6c
	v_ashrrev_i32_e32 v5, 31, v4
	v_lshrrev_b32_e32 v5, 26, v5
	v_add_u32_e32 v5, v4, v5
	v_ashrrev_i32_e32 v141, 6, v5
	v_and_b32_e32 v5, 0xc0, v5
	v_sub_u32_e32 v4, v4, v5
	v_ashrrev_i16_sdwa v4, v215, sext(v4) dst_sel:DWORD dst_unused:UNUSED_PAD src0_sel:DWORD src1_sel:BYTE_0
	v_bfe_i32 v142, v4, 0, 16
	v_add_u32_e32 v4, 0x2000, v140
	v_ashrrev_i32_e32 v5, 31, v4
	v_lshrrev_b32_e32 v5, 22, v5
	v_add_u32_e32 v5, v4, v5
	v_ashrrev_i32_e32 v143, 10, v5
	v_mul_i32_i24_e32 v5, 0x400, v143
	v_sub_u32_e32 v4, v4, v5
	v_lshrrev_b32_e32 v5, 4, v4
	v_bitop3_b32 v4, v5, v4, 32 bitop3:0x6c
	v_ashrrev_i32_e32 v5, 31, v4
	v_lshrrev_b32_e32 v5, 26, v5
	v_ashrrev_i32_e32 v3, 31, v136
	v_add_u32_e32 v5, v4, v5
	v_lshrrev_b32_e32 v3, 26, v3
	v_ashrrev_i32_e32 v144, 6, v5
	v_and_b32_e32 v5, 0xc0, v5
	v_add_u32_e32 v3, v136, v3
	v_sub_u32_e32 v4, v4, v5
	v_ashrrev_i32_e32 v139, 6, v3
	v_ashrrev_i16_sdwa v4, v215, sext(v4) dst_sel:DWORD dst_unused:UNUSED_PAD src0_sel:DWORD src1_sel:BYTE_0
	v_bfe_i32 v145, v4, 0, 16
	v_lshlrev_b32_e32 v4, 13, v0
	v_lshlrev_b32_e32 v0, 15, v139
	v_and_b32_e32 v0, 0xffff0000, v0
	v_lshl_add_u32 v0, v141, 12, v0
	v_and_or_b32 v0, v3, 64, v0
	v_lshl_add_u32 v192, v142, 1, v0
	v_lshlrev_b32_e32 v0, 15, v143
	v_and_b32_e32 v0, 0xffff0000, v0
	v_add_u32_e32 v5, 0, v2
	v_lshl_add_u32 v0, v144, 12, v0
	v_lshlrev_b32_e32 v2, 6, v143
	v_readlane_b32 s2, v253, 59
	v_and_or_b32 v0, v2, 64, v0
	v_readlane_b32 s3, v253, 60
	v_lshl_add_u32 v2, v145, 1, v0
	v_mov_b32_e32 v3, v193
	v_mov_b32_e32 v0, 0
	v_lshl_add_u64 v[128:129], s[2:3], 0, v[192:193]
	v_lshl_add_u64 v[130:131], s[2:3], 0, v[2:3]
	v_lshl_add_u64 v[132:133], s[10:11], 0, v[192:193]
	v_lshl_add_u64 v[134:135], s[10:11], 0, v[2:3]
	s_mov_b32 s2, -2
	v_add_u32_e32 v138, 0, v1
	v_add_u32_e32 v137, v5, v4
	s_mov_b64 s[4:5], s[50:51]
	v_mov_b32_e32 v1, v0
	v_mov_b32_e32 v2, v0
	v_mov_b32_e32 v3, v0
	v_mov_b32_e32 v4, v0
	v_mov_b32_e32 v5, v0
	v_mov_b32_e32 v6, v0
	v_mov_b32_e32 v7, v0
	v_mov_b32_e32 v8, v0
	v_mov_b32_e32 v9, v0
	v_mov_b32_e32 v10, v0
	v_mov_b32_e32 v11, v0
	v_mov_b32_e32 v12, v0
	v_mov_b32_e32 v13, v0
	v_mov_b32_e32 v14, v0
	v_mov_b32_e32 v15, v0
	v_mov_b32_e32 v16, v0
	v_mov_b32_e32 v17, v0
	v_mov_b32_e32 v18, v0
	v_mov_b32_e32 v19, v0
	v_mov_b32_e32 v20, v0
	v_mov_b32_e32 v21, v0
	v_mov_b32_e32 v22, v0
	v_mov_b32_e32 v23, v0
	v_mov_b32_e32 v24, v0
	v_mov_b32_e32 v25, v0
	v_mov_b32_e32 v26, v0
	v_mov_b32_e32 v27, v0
	v_mov_b32_e32 v28, v0
	v_mov_b32_e32 v29, v0
	v_mov_b32_e32 v30, v0
	v_mov_b32_e32 v31, v0
	v_mov_b32_e32 v32, v0
	v_mov_b32_e32 v33, v0
	v_mov_b32_e32 v34, v0
	v_mov_b32_e32 v35, v0
	v_mov_b32_e32 v36, v0
	v_mov_b32_e32 v37, v0
	v_mov_b32_e32 v38, v0
	v_mov_b32_e32 v39, v0
	v_mov_b32_e32 v40, v0
	v_mov_b32_e32 v41, v0
	v_mov_b32_e32 v42, v0
	v_mov_b32_e32 v43, v0
	v_mov_b32_e32 v44, v0
	v_mov_b32_e32 v45, v0
	v_mov_b32_e32 v46, v0
	v_mov_b32_e32 v47, v0
	v_mov_b32_e32 v48, v0
	v_mov_b32_e32 v49, v0
	v_mov_b32_e32 v50, v0
	v_mov_b32_e32 v51, v0
	v_mov_b32_e32 v52, v0
	v_mov_b32_e32 v53, v0
	v_mov_b32_e32 v54, v0
	v_mov_b32_e32 v55, v0
	v_mov_b32_e32 v56, v0
	v_mov_b32_e32 v57, v0
	v_mov_b32_e32 v58, v0
	v_mov_b32_e32 v59, v0
	v_mov_b32_e32 v60, v0
	v_mov_b32_e32 v61, v0
	v_mov_b32_e32 v62, v0
	v_mov_b32_e32 v63, v0
	v_mov_b32_e32 v64, v0
	v_mov_b32_e32 v65, v0
	v_mov_b32_e32 v66, v0
	v_mov_b32_e32 v67, v0
	v_mov_b32_e32 v68, v0
	v_mov_b32_e32 v69, v0
	v_mov_b32_e32 v70, v0
	v_mov_b32_e32 v71, v0
	v_mov_b32_e32 v72, v0
	v_mov_b32_e32 v73, v0
	v_mov_b32_e32 v74, v0
	v_mov_b32_e32 v75, v0
	v_mov_b32_e32 v76, v0
	v_mov_b32_e32 v77, v0
	v_mov_b32_e32 v78, v0
	v_mov_b32_e32 v79, v0
	v_mov_b32_e32 v80, v0
	v_mov_b32_e32 v81, v0
	v_mov_b32_e32 v82, v0
	v_mov_b32_e32 v83, v0
	v_mov_b32_e32 v84, v0
	v_mov_b32_e32 v85, v0
	v_mov_b32_e32 v86, v0
	v_mov_b32_e32 v87, v0
	v_mov_b32_e32 v88, v0
	v_mov_b32_e32 v89, v0
	v_mov_b32_e32 v90, v0
	v_mov_b32_e32 v91, v0
	v_mov_b32_e32 v92, v0
	v_mov_b32_e32 v93, v0
	v_mov_b32_e32 v94, v0
	v_mov_b32_e32 v95, v0
	v_mov_b32_e32 v96, v0
	v_mov_b32_e32 v97, v0
	v_mov_b32_e32 v98, v0
	v_mov_b32_e32 v99, v0
	v_mov_b32_e32 v100, v0
	v_mov_b32_e32 v101, v0
	v_mov_b32_e32 v102, v0
	v_mov_b32_e32 v103, v0
	v_mov_b32_e32 v104, v0
	v_mov_b32_e32 v105, v0
	v_mov_b32_e32 v106, v0
	v_mov_b32_e32 v107, v0
	v_mov_b32_e32 v108, v0
	v_mov_b32_e32 v109, v0
	v_mov_b32_e32 v110, v0
	v_mov_b32_e32 v111, v0
	v_mov_b32_e32 v112, v0
	v_mov_b32_e32 v113, v0
	v_mov_b32_e32 v114, v0
	v_mov_b32_e32 v115, v0
	v_mov_b32_e32 v116, v0
	v_mov_b32_e32 v117, v0
	v_mov_b32_e32 v118, v0
	v_mov_b32_e32 v119, v0
	v_mov_b32_e32 v120, v0
	v_mov_b32_e32 v121, v0
	v_mov_b32_e32 v122, v0
	v_mov_b32_e32 v123, v0
	v_mov_b32_e32 v124, v0
	v_mov_b32_e32 v125, v0
	v_mov_b32_e32 v126, v0
	v_mov_b32_e32 v127, v0
	s_mov_b64 s[10:11], 0x27580080
	s_mov_b64 s[12:13], 0x9100100
	s_mov_b64 s[14:15], 0x27500100
	v_readfirstlane_b32 s3, v140
	s_waitcnt vmcnt(0)
	s_barrier
	s_barrier

; #define WAIT_V(n) asm volatile("s_waitcnt vmcnt(" #n ")" ::: "memory")
; #define EPIW_ALL(F, BODY) _Pragma("unroll") for (int ai = 0; ai < 2; ++ai) _Pragma("unroll") for (int bj = 0; bj < 2; ++bj) { \
;   _Pragma("unroll") for (int m = 0; m < 4; ++m) { \
;     const int row = brow + ai * 128 + m * 16 + e_rr; const int tcw = bj * 128 + e_cw; \
;     const uint4 w = widen16(pack4(F(acc[ai][bj][m][0])), pack4(F(acc[ai][bj][m][1]))); BODY } SCHED; }
; __device__ __forceinline__ uint4 widen16(uint2 a, uint2 b) {
;   auto r0 = __builtin_amdgcn_permlane16_swap(a.x, b.x, false, false);
;   auto r1 = __builtin_amdgcn_permlane16_swap(a.y, b.y, false, false);
;   return uint4{r0[0], r1[0], r0[1], r1[1]};
; }
; __device__ __forceinline__ void unwiden16(uint4 w, uint2& a, uint2& b) {
;   auto r0 = __builtin_amdgcn_permlane16_swap(w.x, w.z, false, false);
;   auto r1 = __builtin_amdgcn_permlane16_swap(w.y, w.w, false, false);
;   a = uint2{r0[0], r1[0]}; b = uint2{r0[1], r1[1]};
; }
; __device__ __forceinline__ uint2 pack4(f32x4 v) { uint2 o; o.x = pack2(v[0], v[1]); o.y = pack2(v[2], v[3]); return o; }
; __device__ __forceinline__ void phase_outproj(const Params& p, int half, int sg, char* smem) {
;     ...
;     EPIW_BEGIN
;     EPIW_ALL(f_id, { *(uint4*)(rout + ((unsigned)row * 4096u + nt * 256 + tcw)) = w; })
;     WAIT_V(0);
.LBB0_623:
	s_lshl_b32 s6, s6, 3
	v_mov_b32_e32 v128, v136
	v_mov_b32_e32 v129, v137
	s_and_b32 s6, s6, 0x700
	v_cvt_pk_bf16_f32 v120, v120, v121
	v_add_u32_e32 v129, s6, v129
	v_cvt_pk_bf16_f32 v121, v122, v123
	v_cvt_pk_bf16_f32 v123, v126, v127
	v_add_lshl_u32 v126, v128, s10, 12
	v_add_u32_e32 v192, v126, v129
	v_cvt_pk_bf16_f32 v112, v112, v113
	v_cvt_pk_bf16_f32 v113, v114, v115
	v_cvt_pk_bf16_f32 v115, v118, v119
	v_add_u32_e32 v118, 0x10000, v126
	v_cvt_pk_bf16_f32 v122, v124, v125
	v_lshl_add_u64 v[124:125], v[192:193], 1, s[0:1]
	v_add_u32_e32 v192, v118, v129
	v_cvt_pk_bf16_f32 v104, v104, v105
	v_cvt_pk_bf16_f32 v105, v106, v107
	v_cvt_pk_bf16_f32 v107, v110, v111
	v_add_u32_e32 v110, 0x20000, v126
	v_cvt_pk_bf16_f32 v114, v116, v117
	v_lshl_add_u64 v[116:117], v[192:193], 1, s[0:1]
	v_add_u32_e32 v192, v110, v129
	v_cvt_pk_bf16_f32 v96, v96, v97
	v_cvt_pk_bf16_f32 v97, v98, v99
	v_cvt_pk_bf16_f32 v99, v102, v103
	v_add_u32_e32 v102, 0x30000, v126
	v_cvt_pk_bf16_f32 v106, v108, v109
	v_lshl_add_u64 v[108:109], v[192:193], 1, s[0:1]
	v_cvt_pk_bf16_f32 v98, v100, v101
	v_add_u32_e32 v192, v102, v129
	v_permlane16_swap_b32_e32 v120, v122
	v_permlane16_swap_b32_e32 v121, v123
	v_permlane16_swap_b32_e32 v112, v114
	v_permlane16_swap_b32_e32 v113, v115
	v_permlane16_swap_b32_e32 v104, v106
	v_permlane16_swap_b32_e32 v105, v107
	v_permlane16_swap_b32_e32 v96, v98
	v_permlane16_swap_b32_e32 v97, v99
	v_lshl_add_u64 v[100:101], v[192:193], 1, s[0:1]
	global_store_dwordx4 v[124:125], v[120:123], off
	global_store_dwordx4 v[116:117], v[112:115], off
	global_store_dwordx4 v[108:109], v[104:107], off
	global_store_dwordx4 v[100:101], v[96:99], off
	s_nop 1
	v_add_u32_e32 v96, 0x80, v129
	v_add_u32_e32 v192, v96, v126
	v_cvt_pk_bf16_f32 v88, v88, v89
	v_cvt_pk_bf16_f32 v89, v90, v91
	v_cvt_pk_bf16_f32 v90, v92, v93
	v_lshl_add_u64 v[92:93], v[192:193], 1, s[0:1]
	v_add_u32_e32 v192, v118, v96
	v_cvt_pk_bf16_f32 v80, v80, v81
	v_cvt_pk_bf16_f32 v81, v82, v83
	v_cvt_pk_bf16_f32 v82, v84, v85
	v_lshl_add_u64 v[84:85], v[192:193], 1, s[0:1]
	v_add_u32_e32 v192, v110, v96
	v_cvt_pk_bf16_f32 v91, v94, v95
	v_cvt_pk_bf16_f32 v83, v86, v87
	v_cvt_pk_bf16_f32 v72, v72, v73
	v_cvt_pk_bf16_f32 v73, v74, v75
	v_cvt_pk_bf16_f32 v74, v76, v77
	v_cvt_pk_bf16_f32 v75, v78, v79
	v_lshl_add_u64 v[76:77], v[192:193], 1, s[0:1]
	v_cvt_pk_bf16_f32 v64, v64, v65
	v_cvt_pk_bf16_f32 v65, v66, v67
	v_cvt_pk_bf16_f32 v66, v68, v69
	v_cvt_pk_bf16_f32 v67, v70, v71
	v_add_u32_e32 v192, v102, v96
	v_permlane16_swap_b32_e32 v88, v90
	v_permlane16_swap_b32_e32 v89, v91
	v_permlane16_swap_b32_e32 v80, v82
	v_permlane16_swap_b32_e32 v81, v83
	v_permlane16_swap_b32_e32 v72, v74
	v_permlane16_swap_b32_e32 v73, v75
	v_permlane16_swap_b32_e32 v64, v66
	v_permlane16_swap_b32_e32 v65, v67
	v_lshl_add_u64 v[68:69], v[192:193], 1, s[0:1]
	global_store_dwordx4 v[92:93], v[88:91], off
	global_store_dwordx4 v[84:85], v[80:83], off
	global_store_dwordx4 v[76:77], v[72:75], off
	global_store_dwordx4 v[68:69], v[64:67], off
	v_cvt_pk_bf16_f32 v56, v56, v57
	v_cvt_pk_bf16_f32 v57, v58, v59
	v_cvt_pk_bf16_f32 v59, v62, v63
	v_add_u32_e32 v62, 0x80000, v126
	v_add_u32_e32 v192, v62, v129
	v_cvt_pk_bf16_f32 v48, v48, v49
	v_cvt_pk_bf16_f32 v49, v50, v51
	v_cvt_pk_bf16_f32 v51, v54, v55
	v_add_u32_e32 v54, 0x90000, v126
	v_cvt_pk_bf16_f32 v58, v60, v61
	v_lshl_add_u64 v[60:61], v[192:193], 1, s[0:1]
	v_add_u32_e32 v192, v54, v129
	v_cvt_pk_bf16_f32 v40, v40, v41
	v_cvt_pk_bf16_f32 v41, v42, v43
	v_cvt_pk_bf16_f32 v43, v46, v47
	v_add_u32_e32 v46, 0xa0000, v126
	v_cvt_pk_bf16_f32 v50, v52, v53
	v_lshl_add_u64 v[52:53], v[192:193], 1, s[0:1]
	v_add_u32_e32 v192, v46, v129
	v_cvt_pk_bf16_f32 v32, v32, v33
	v_cvt_pk_bf16_f32 v33, v34, v35
	v_cvt_pk_bf16_f32 v35, v38, v39
	v_add_u32_e32 v38, 0xb0000, v126
	v_cvt_pk_bf16_f32 v42, v44, v45
	v_lshl_add_u64 v[44:45], v[192:193], 1, s[0:1]
	v_cvt_pk_bf16_f32 v34, v36, v37
	v_add_u32_e32 v192, v38, v129
	v_permlane16_swap_b32_e32 v56, v58
	v_permlane16_swap_b32_e32 v57, v59
	v_permlane16_swap_b32_e32 v48, v50
	v_permlane16_swap_b32_e32 v49, v51
	v_permlane16_swap_b32_e32 v40, v42
	v_permlane16_swap_b32_e32 v41, v43
	v_permlane16_swap_b32_e32 v32, v34
	v_permlane16_swap_b32_e32 v33, v35
	v_lshl_add_u64 v[36:37], v[192:193], 1, s[0:1]
	global_store_dwordx4 v[60:61], v[56:59], off
	global_store_dwordx4 v[52:53], v[48:51], off
	global_store_dwordx4 v[44:45], v[40:43], off
	global_store_dwordx4 v[36:37], v[32:35], off
	v_add_u32_e32 v192, v62, v96
	v_cvt_pk_bf16_f32 v24, v24, v25
	v_cvt_pk_bf16_f32 v25, v26, v27
	v_cvt_pk_bf16_f32 v26, v28, v29
	v_lshl_add_u64 v[28:29], v[192:193], 1, s[0:1]
	v_add_u32_e32 v192, v54, v96
	v_cvt_pk_bf16_f32 v16, v16, v17
	v_cvt_pk_bf16_f32 v17, v18, v19
	v_cvt_pk_bf16_f32 v18, v20, v21
	v_lshl_add_u64 v[20:21], v[192:193], 1, s[0:1]
	v_add_u32_e32 v192, v46, v96
	v_cvt_pk_bf16_f32 v27, v30, v31
	v_cvt_pk_bf16_f32 v19, v22, v23
	v_cvt_pk_bf16_f32 v8, v8, v9
	v_cvt_pk_bf16_f32 v9, v10, v11
	v_cvt_pk_bf16_f32 v10, v12, v13
	v_cvt_pk_bf16_f32 v11, v14, v15
	v_lshl_add_u64 v[12:13], v[192:193], 1, s[0:1]
	v_cvt_pk_bf16_f32 v0, v0, v1
	v_cvt_pk_bf16_f32 v1, v2, v3
	v_cvt_pk_bf16_f32 v2, v4, v5
	v_cvt_pk_bf16_f32 v3, v6, v7
	v_add_u32_e32 v192, v38, v96
	v_permlane16_swap_b32_e32 v24, v26
	v_permlane16_swap_b32_e32 v25, v27
	v_permlane16_swap_b32_e32 v16, v18
	v_permlane16_swap_b32_e32 v17, v19
	v_permlane16_swap_b32_e32 v8, v10
	v_permlane16_swap_b32_e32 v9, v11
	v_permlane16_swap_b32_e32 v0, v2
	v_permlane16_swap_b32_e32 v1, v3
	v_lshl_add_u64 v[4:5], v[192:193], 1, s[0:1]
	global_store_dwordx4 v[28:29], v[24:27], off
	global_store_dwordx4 v[20:21], v[16:19], off
	global_store_dwordx4 v[12:13], v[8:11], off
	global_store_dwordx4 v[4:5], v[0:3], off
	s_nop 1
	v_readlane_b32 s6, v252, 4
	s_add_i32 s3, s3, s6
	v_readlane_b32 s6, v252, 16
	s_add_i32 s2, s2, s6
	s_andn2_b64 vcc, exec, s[4:5]
	s_mov_b32 s6, s7
	s_cbranch_vccz .LBB0_427

; #define WAIT_V(n) asm volatile("s_waitcnt vmcnt(" #n ")" ::: "memory")
; #define BAR __builtin_amdgcn_s_barrier()
; template <bool SWAP>
; __device__ __forceinline__ void gemm_main(const u16* __restrict__ A, const u16* __restrict__ Bt, int brow, int bcol,
;                                           u16* shm, f32x4 (&acc)[2][2][4][2]) {
;     ...
;   int tx = threadIdx.x; asm volatile("" : "+v"(tx));
;   const int wid = tx >> 6, lane = tx & 63, wr = wid >> 2, wc = wid & 3, fr = lane & 15, fq = lane >> 4;
; #pragma unroll
;   for (int a = 0; a < 2; ++a)
; #pragma unroll
;     for (int b = 0; b < 2; ++b)
; #pragma unroll
;       for (int m = 0; m < 4; ++m)
; #pragma unroll
;         for (int n = 0; n < 2; ++n) acc[a][b][m][n] = f32x4{0.f, 0.f, 0.f, 0.f};
;   bf16x8 At[4][2], B0[2][2], B1[2][2];
;   constexpr int nt = GK / BK;
;   GEMM_VOFF
;   const int lpart = (fr * 64 + fq * 16) ^ ((fr >> 3) << 5);
;   const int abase = wr * 8192 + lpart; int bbase = 65536 + wc * 4096 + lpart;
;   asm volatile("" : "+v"(bbase));
;   if (wr == 1) BAR;
;   WAIT_V(0); BAR;
;   BAR;
.LBB0_626:
	s_or_b64 exec, exec, s[4:5]
	v_bfe_i32 v4, v138, 27, 1
	v_lshlrev_b32_e32 v142, 4, v138
	v_lshrrev_b32_e32 v4, 22, v4
	v_add_u32_e32 v4, v142, v4
	v_and_b32_e32 v4, 0xfffffc00, v4
	v_sub_u32_e32 v4, v142, v4
	v_lshrrev_b32_e32 v5, 4, v4
	v_bitop3_b32 v4, v5, v4, 32 bitop3:0x6c
	v_ashrrev_i32_e32 v5, 31, v4
	v_lshrrev_b32_e32 v5, 26, v5
	v_add_u32_e32 v5, v4, v5
	v_ashrrev_i32_e32 v143, 6, v5
	v_and_b32_e32 v5, 0xc0, v5
	v_sub_u32_e32 v4, v4, v5
	v_ashrrev_i16_sdwa v4, v215, sext(v4) dst_sel:DWORD dst_unused:UNUSED_PAD src0_sel:DWORD src1_sel:BYTE_0
	v_bfe_i32 v144, v4, 0, 16
	v_add_u32_e32 v4, 0x2000, v142
	v_ashrrev_i32_e32 v5, 31, v4
	v_lshrrev_b32_e32 v5, 22, v5
	v_add_u32_e32 v5, v4, v5
	v_ashrrev_i32_e32 v145, 10, v5
	v_mul_i32_i24_e32 v5, 0x400, v145
	v_sub_u32_e32 v4, v4, v5
	v_lshrrev_b32_e32 v5, 4, v4
	v_bitop3_b32 v4, v5, v4, 32 bitop3:0x6c
	v_ashrrev_i32_e32 v5, 31, v4
	v_lshrrev_b32_e32 v5, 26, v5
	v_ashrrev_i32_e32 v3, 31, v138
	v_add_u32_e32 v5, v4, v5
	v_lshrrev_b32_e32 v3, 26, v3
	v_ashrrev_i32_e32 v146, 6, v5
	v_and_b32_e32 v5, 0xc0, v5
	v_add_u32_e32 v3, v138, v3
	v_sub_u32_e32 v4, v4, v5
	v_ashrrev_i32_e32 v141, 6, v3
	v_ashrrev_i16_sdwa v4, v215, sext(v4) dst_sel:DWORD dst_unused:UNUSED_PAD src0_sel:DWORD src1_sel:BYTE_0
	s_lshl_b32 s4, s3, 12
	v_readlane_b32 s8, v253, 59
	v_bfe_i32 v147, v4, 0, 16
	v_lshlrev_b32_e32 v4, 13, v0
	v_lshlrev_b32_e32 v0, 15, v141
	v_readlane_b32 s9, v253, 60
	s_and_b32 s8, s4, 0x700000
	s_and_b32 s4, s2, 31
	v_and_b32_e32 v0, 0xffff0000, v0
	s_lshl_b32 s4, s4, 8
	v_lshl_add_u32 v0, v143, 12, v0
	s_mov_b32 s5, s9
	s_ashr_i32 s7, s6, 3
	v_and_or_b32 v0, v3, 64, v0
	v_writelane_b32 v253, s4, 59
	v_lshl_add_u32 v192, v144, 1, v0
	v_lshlrev_b32_e32 v0, 15, v145
	v_writelane_b32 v253, s5, 60
	s_lshl_b32 s5, s7, 8
	v_and_b32_e32 v0, 0xffff0000, v0
	s_and_b32 s5, s5, 0xffffe000
	v_add_u32_e32 v5, 0, v2
	v_lshl_add_u32 v0, v146, 12, v0
	v_lshlrev_b32_e32 v2, 6, v145
	s_or_b32 s4, s5, s4
	v_and_or_b32 v0, v2, 64, v0
	s_ashr_i32 s5, s4, 31
	v_lshl_add_u32 v2, v147, 1, v0
	v_mov_b32_e32 v3, v193
	s_lshl_b64 s[4:5], s[4:5], 12
	v_mov_b32_e32 v0, 0
	v_lshl_add_u64 v[128:129], s[8:9], 0, v[192:193]
	v_lshl_add_u64 v[130:131], s[8:9], 0, v[2:3]
	v_lshl_add_u64 v[132:133], s[4:5], 0, v[192:193]
	v_lshl_add_u64 v[134:135], s[4:5], 0, v[2:3]
	s_mov_b32 s8, -2
	v_add_u32_e32 v140, 0, v1
	v_add_u32_e32 v139, v5, v4
	s_mov_b64 s[4:5], s[50:51]
	v_mov_b32_e32 v1, v0
	v_mov_b32_e32 v2, v0
	v_mov_b32_e32 v3, v0
	v_mov_b32_e32 v4, v0
	v_mov_b32_e32 v5, v0
	v_mov_b32_e32 v6, v0
	v_mov_b32_e32 v7, v0
	v_mov_b32_e32 v8, v0
	v_mov_b32_e32 v9, v0
	v_mov_b32_e32 v10, v0
	v_mov_b32_e32 v11, v0
	v_mov_b32_e32 v12, v0
	v_mov_b32_e32 v13, v0
	v_mov_b32_e32 v14, v0
	v_mov_b32_e32 v15, v0
	v_mov_b32_e32 v16, v0
	v_mov_b32_e32 v17, v0
	v_mov_b32_e32 v18, v0
	v_mov_b32_e32 v19, v0
	v_mov_b32_e32 v20, v0
	v_mov_b32_e32 v21, v0
	v_mov_b32_e32 v22, v0
	v_mov_b32_e32 v23, v0
	v_mov_b32_e32 v24, v0
	v_mov_b32_e32 v25, v0
	v_mov_b32_e32 v26, v0
	v_mov_b32_e32 v27, v0
	v_mov_b32_e32 v28, v0
	v_mov_b32_e32 v29, v0
	v_mov_b32_e32 v30, v0
	v_mov_b32_e32 v31, v0
	v_mov_b32_e32 v32, v0
	v_mov_b32_e32 v33, v0
	v_mov_b32_e32 v34, v0
	v_mov_b32_e32 v35, v0
	v_mov_b32_e32 v36, v0
	v_mov_b32_e32 v37, v0
	v_mov_b32_e32 v38, v0
	v_mov_b32_e32 v39, v0
	v_mov_b32_e32 v40, v0
	v_mov_b32_e32 v41, v0
	v_mov_b32_e32 v42, v0
	v_mov_b32_e32 v43, v0
	v_mov_b32_e32 v44, v0
	v_mov_b32_e32 v45, v0
	v_mov_b32_e32 v46, v0
	v_mov_b32_e32 v47, v0
	v_mov_b32_e32 v48, v0
	v_mov_b32_e32 v49, v0
	v_mov_b32_e32 v50, v0
	v_mov_b32_e32 v51, v0
	v_mov_b32_e32 v52, v0
	v_mov_b32_e32 v53, v0
	v_mov_b32_e32 v54, v0
	v_mov_b32_e32 v55, v0
	v_mov_b32_e32 v56, v0
	v_mov_b32_e32 v57, v0
	v_mov_b32_e32 v58, v0
	v_mov_b32_e32 v59, v0
	v_mov_b32_e32 v60, v0
	v_mov_b32_e32 v61, v0
	v_mov_b32_e32 v62, v0
	v_mov_b32_e32 v63, v0
	v_mov_b32_e32 v64, v0
	v_mov_b32_e32 v65, v0
	v_mov_b32_e32 v66, v0
	v_mov_b32_e32 v67, v0
	v_mov_b32_e32 v68, v0
	v_mov_b32_e32 v69, v0
	v_mov_b32_e32 v70, v0
	v_mov_b32_e32 v71, v0
	v_mov_b32_e32 v72, v0
	v_mov_b32_e32 v73, v0
	v_mov_b32_e32 v74, v0
	v_mov_b32_e32 v75, v0
	v_mov_b32_e32 v76, v0
	v_mov_b32_e32 v77, v0
	v_mov_b32_e32 v78, v0
	v_mov_b32_e32 v79, v0
	v_mov_b32_e32 v80, v0
	v_mov_b32_e32 v81, v0
	v_mov_b32_e32 v82, v0
	v_mov_b32_e32 v83, v0
	v_mov_b32_e32 v84, v0
	v_mov_b32_e32 v85, v0
	v_mov_b32_e32 v86, v0
	v_mov_b32_e32 v87, v0
	v_mov_b32_e32 v88, v0
	v_mov_b32_e32 v89, v0
	v_mov_b32_e32 v90, v0
	v_mov_b32_e32 v91, v0
	v_mov_b32_e32 v92, v0
	v_mov_b32_e32 v93, v0
	v_mov_b32_e32 v94, v0
	v_mov_b32_e32 v95, v0
	v_mov_b32_e32 v96, v0
	v_mov_b32_e32 v97, v0
	v_mov_b32_e32 v98, v0
	v_mov_b32_e32 v99, v0
	v_mov_b32_e32 v100, v0
	v_mov_b32_e32 v101, v0
	v_mov_b32_e32 v102, v0
	v_mov_b32_e32 v103, v0
	v_mov_b32_e32 v104, v0
	v_mov_b32_e32 v105, v0
	v_mov_b32_e32 v106, v0
	v_mov_b32_e32 v107, v0
	v_mov_b32_e32 v108, v0
	v_mov_b32_e32 v109, v0
	v_mov_b32_e32 v110, v0
	v_mov_b32_e32 v111, v0
	v_mov_b32_e32 v112, v0
	v_mov_b32_e32 v113, v0
	v_mov_b32_e32 v114, v0
	v_mov_b32_e32 v115, v0
	v_mov_b32_e32 v116, v0
	v_mov_b32_e32 v117, v0
	v_mov_b32_e32 v118, v0
	v_mov_b32_e32 v119, v0
	v_mov_b32_e32 v120, v0
	v_mov_b32_e32 v121, v0
	v_mov_b32_e32 v122, v0
	v_mov_b32_e32 v123, v0
	v_mov_b32_e32 v124, v0
	v_mov_b32_e32 v125, v0
	v_mov_b32_e32 v126, v0
	v_mov_b32_e32 v127, v0
	v_readfirstlane_b32 s9, v142
	s_waitcnt vmcnt(0)
	s_barrier
	s_barrier
